# S5 pass 2 tile loop rewritten by hand: token rows remapped to 16 consecutive tokens per lane half, per-half f32 scan, one cross-half exchange per tile, packed-f32 carry fix-up; on top of the pass 1 re
# speedup vs baseline: 1.0216x; 1.0034x over previous
.LBB0_1058:
	s_and_b32 s2, s62, 31
	v_mov_b32_e32 v148, v228
	s_lshl_b32 s30, s2, 8
	v_ashrrev_i32_e32 v149, 31, v148
	v_lshl_add_u64 v[2:3], v[148:149], 0, s[30:31]
	s_or_b32 s0, s30, 64
	s_mov_b32 s1, s31
	v_lshlrev_b64 v[2:3], 4, v[2:3]
	v_lshl_add_u64 v[4:5], v[148:149], 0, s[0:1]
	v_lshl_add_u64 v[6:7], s[46:47], 0, v[2:3]
	v_lshlrev_b64 v[4:5], 4, v[4:5]
	s_or_b32 s0, s30, 0x80
	v_lshl_add_u64 v[8:9], s[46:47], 0, v[4:5]
	global_load_dwordx4 v[114:117], v[6:7], off
	global_load_dwordx4 v[106:109], v[8:9], off
	v_lshl_add_u64 v[6:7], v[148:149], 0, s[0:1]
	s_or_b32 s30, s30, 0xc0
	v_lshlrev_b64 v[6:7], 4, v[6:7]
	v_lshl_add_u64 v[8:9], v[148:149], 0, s[30:31]
	v_and_b32_e32 v1, 31, v148
	v_lshl_add_u64 v[10:11], s[46:47], 0, v[6:7]
	v_lshlrev_b64 v[8:9], 4, v[8:9]
	s_lshl_b32 s30, s2, 6
	s_ashr_i32 s64, s62, 10
	v_lshl_add_u64 v[12:13], s[46:47], 0, v[8:9]
	global_load_dwordx4 v[110:113], v[10:11], off
	global_load_dwordx4 v[102:105], v[12:13], off
	v_or_b32_e32 v10, s30, v1
	s_bfe_u32 s70, s62, 0x50005
	v_lshlrev_b32_e32 v11, 5, v10
	s_ashr_i32 s65, s64, 31
	global_load_dwordx4 v[70:73], v11, s[52:53] offset:16
	global_load_dwordx4 v[78:81], v11, s[52:53]
	v_or_b32_e32 v11, 32, v10
	s_lshl_b64 s[56:57], s[64:65], 13
	s_lshl_b32 s0, s70, 8
	v_ashrrev_i32_e32 v149, 5, v148
	v_lshlrev_b32_e32 v12, 5, v11
	s_or_b32 s56, s56, s0
	s_lshl_b32 s0, s2, 5
	global_load_dwordx4 v[66:69], v12, s[52:53] offset:16
	global_load_dwordx4 v[74:77], v12, s[52:53]
	s_add_u32 s66, s39, s0
	v_lshlrev_b32_e32 v12, 3, v149
	s_addc_u32 s67, s63, 0
	v_ashrrev_i32_e32 v13, 31, v12
	v_bfe_u32 v146, v1, 3, 2
	v_bfe_u32 v14, v1, 2, 1
	v_lshlrev_b32_e32 v146, 2, v146
	v_and_or_b32 v146, v1, 3, v146
	v_lshl_or_b32 v146, v14, 4, v146
	v_or_b32_e32 v14, s56, v146
	v_mov_b32_e32 v15, s57
	v_lshl_add_u64 v[12:13], v[12:13], 1, s[66:67]
	v_lshlrev_b64 v[16:17], 10, v[14:15]
	v_or_b32_e32 v18, 32, v14
	v_mov_b32_e32 v19, s57
	v_lshl_add_u64 v[16:17], v[12:13], 0, v[16:17]
	v_lshlrev_b64 v[18:19], 10, v[18:19]
	v_lshl_add_u64 v[22:23], v[12:13], 0, v[18:19]
	global_load_dwordx4 v[18:21], v[16:17], off
	global_load_dwordx4 v[142:145], v[22:23], off
	v_or_b32_e32 v16, 64, v14
	v_mov_b32_e32 v17, s57
	v_lshlrev_b64 v[16:17], 10, v[16:17]
	v_or_b32_e32 v22, 0x60, v14
	v_mov_b32_e32 v23, s57
	v_lshl_add_u64 v[16:17], v[12:13], 0, v[16:17]
	v_lshlrev_b64 v[22:23], 10, v[22:23]
	v_lshl_add_u64 v[22:23], v[12:13], 0, v[22:23]
	global_load_dwordx4 v[138:141], v[16:17], off
	global_load_dwordx4 v[134:137], v[22:23], off
	v_or_b32_e32 v16, 0x80, v14
	v_mov_b32_e32 v17, s57
	v_lshlrev_b64 v[16:17], 10, v[16:17]
	v_or_b32_e32 v22, 0xa0, v14
	v_mov_b32_e32 v23, s57
	v_lshl_add_u64 v[16:17], v[12:13], 0, v[16:17]
	v_lshlrev_b64 v[22:23], 10, v[22:23]
	v_lshl_add_u64 v[22:23], v[12:13], 0, v[22:23]
	global_load_dwordx4 v[130:133], v[16:17], off
	global_load_dwordx4 v[126:129], v[22:23], off
	v_or_b32_e32 v16, 0xc0, v14
	v_mov_b32_e32 v17, s57
	v_lshlrev_b64 v[16:17], 10, v[16:17]
	v_or_b32_e32 v14, 0xe0, v14
	v_lshl_add_u64 v[16:17], v[12:13], 0, v[16:17]
	v_lshlrev_b64 v[14:15], 10, v[14:15]
	v_lshl_add_u64 v[12:13], v[12:13], 0, v[14:15]
	global_load_dwordx4 v[122:125], v[16:17], off
	global_load_dwordx4 v[118:121], v[12:13], off
	s_cmp_eq_u32 s70, 0
	v_mov_b32_e32 v167, 0
	v_mov_b32_e32 v166, 0
	v_mov_b32_e32 v151, 0
	v_mov_b32_e32 v150, 0
	s_cbranch_scc1 .LBB0_1063
	v_readlane_b32 s0, v251, 4
	v_lshlrev_b32_e32 v10, 3, v10
	v_readlane_b32 s1, v251, 5
	v_lshlrev_b32_e32 v11, 3, v11
	s_nop 3
	global_load_dwordx2 v[24:25], v10, s[0:1]
	global_load_dwordx2 v[22:23], v11, s[0:1]
	v_readlane_b32 s0, v251, 2
	s_and_b32 s33, s62, 0xfffffc1f
	v_lshlrev_b32_e32 v146, 3, v1
	v_mov_b32_e32 v150, 0
	v_readlane_b32 s1, v251, 3
	s_mov_b32 s65, 0
	s_mov_b32 s4, s33
	v_lshl_add_u64 v[10:11], s[0:1], 0, v[146:147]
	v_mov_b32_e32 v151, v150
	v_mov_b32_e32 v166, v150
	v_mov_b32_e32 v167, v150
	s_waitcnt vmcnt(1)
	v_xor_b32_e32 v12, 0x80000000, v25
	s_waitcnt vmcnt(0)
	v_xor_b32_e32 v14, 0x80000000, v23
	v_mov_b32_e32 v16, v22
	v_mov_b32_e32 v17, v22
	v_mov_b32_e32 v15, v23
	v_mov_b32_e32 v22, v24
	v_mov_b32_e32 v23, v24
	v_mov_b32_e32 v13, v25
	s_branch .LBB0_1061

.LBB0_1063:
	v_lshl_add_u64 v[2:3], s[58:59], 0, v[2:3]
	v_lshl_add_u64 v[4:5], s[58:59], 0, v[4:5]
	global_load_dwordx4 v[94:97], v[2:3], off
	global_load_dwordx4 v[90:93], v[4:5], off
	v_lshl_add_u64 v[2:3], s[58:59], 0, v[6:7]
	v_lshl_add_u64 v[4:5], s[58:59], 0, v[8:9]
	global_load_dwordx4 v[86:89], v[2:3], off
	global_load_dwordx4 v[82:85], v[4:5], off
	s_lshl_b32 s0, s2, 4
	s_lshl_b32 s1, s0, 2
	v_readlane_b32 s4, v252, 48
	v_readlane_b32 s5, v252, 49
	v_lshrrev_b32_e32 v1, 4, v148
	s_add_u32 s4, s4, s1
	s_addc_u32 s5, s5, 0
	v_lshlrev_b32_e32 v178, 4, v1
	v_and_b32_e32 v176, 15, v148
	v_lshlrev_b32_e32 v176, 10, v176
	global_load_dwordx4 v[98:101], v178, s[4:5]
	v_lshl_or_b32 v176, v1, 3, v176
	v_add_u32_e32 v177, 0x4000, v176
	s_lshl_b64 s[8:9], s[56:57], 10
	s_add_u32 s6, s66, s8
	s_addc_u32 s7, s67, s9
	s_lshl_b32 s1, s0, 1
	s_add_u32 s10, s74, s1
	s_addc_u32 s11, s75, 0
	s_add_u32 s10, s10, s8
	s_addc_u32 s11, s11, s9
	v_and_b32_e32 v1, 31, v148
	v_mul_u32_u24_e32 v174, 0x1100, v149
	v_lshlrev_b32_e32 v1, 2, v1
	v_add3_u32 v174, s3, v174, v1
	v_and_b32_e32 v1, 15, v148
	v_mul_u32_u24_e32 v175, 0x110, v1
	v_add3_u32 v175, s3, v175, v178
	v_cmp_lt_u32_e32 vcc, 31, v148
	s_waitcnt vmcnt(12)
	v_mfma_f32_32x32x16_bf16 v[50:65], v[18:21], v[114:117], 0
	v_mfma_f32_32x32x16_bf16 v[2:17], v[18:21], v[110:113], 0
	v_mfma_f32_32x32x16_bf16 v[34:49], v[18:21], v[106:109], 0
	v_mfma_f32_32x32x16_bf16 v[18:33], v[18:21], v[102:105], 0
	global_load_dwordx2 v[160:161], v176, s[6:7]
	global_load_dwordx2 v[162:163], v177, s[6:7]
	v_mov_b32_e32 v1, v79
	v_mov_b32_e32 v79, v80
	v_mov_b32_e32 v80, v1
	v_mov_b32_e32 v1, v71
	v_mov_b32_e32 v71, v72
	v_mov_b32_e32 v72, v1
	v_mov_b32_e32 v1, v75
	v_mov_b32_e32 v75, v76
	v_mov_b32_e32 v76, v1
	v_mov_b32_e32 v1, v67
	v_mov_b32_e32 v67, v68
	v_mov_b32_e32 v68, v1
	v_mul_f32_e32 v156, v71, v71
	v_mul_f32_e32 v157, v71, v73
	v_fma_f32 v156, -v73, v73, v156
	v_add_f32_e32 v157, v157, v157
	v_mul_f32_e32 v152, v156, v156
	v_mul_f32_e32 v153, v156, v157
	v_fma_f32 v152, -v157, v157, v152
	v_add_f32_e32 v153, v153, v153
	v_mul_f32_e32 v156, v67, v67
	v_mul_f32_e32 v157, v67, v69
	v_fma_f32 v156, -v69, v69, v156
	v_add_f32_e32 v157, v157, v157
	v_mul_f32_e32 v154, v156, v156
	v_mul_f32_e32 v155, v156, v157
	v_fma_f32 v154, -v157, v157, v154
	v_add_f32_e32 v155, v155, v155
	v_fmac_f32_e32 v51, v78, v50
	v_fmac_f32_e32 v35, v74, v34
	v_fmac_f32_e32 v3, v80, v50
	v_fmac_f32_e32 v19, v76, v34
	v_fma_f32 v51, -v80, v2, v51
	v_fma_f32 v35, -v76, v18, v35
	v_fmac_f32_e32 v3, v78, v2
	v_fmac_f32_e32 v19, v74, v18
	v_fmac_f32_e32 v52, v78, v51
	v_fmac_f32_e32 v36, v74, v35
	v_fmac_f32_e32 v4, v80, v51
	v_fmac_f32_e32 v20, v76, v35
	v_fma_f32 v52, -v80, v3, v52
	v_fma_f32 v36, -v76, v19, v36
	v_fmac_f32_e32 v4, v78, v3
	v_fmac_f32_e32 v20, v74, v19
	v_fmac_f32_e32 v53, v78, v52
	v_fmac_f32_e32 v37, v74, v36
	v_fmac_f32_e32 v5, v80, v52
	v_fmac_f32_e32 v21, v76, v36
	v_fma_f32 v53, -v80, v4, v53
	v_fma_f32 v37, -v76, v20, v37
	v_fmac_f32_e32 v5, v78, v4
	v_fmac_f32_e32 v21, v74, v20
	v_fmac_f32_e32 v54, v78, v53
	v_fmac_f32_e32 v38, v74, v37
	v_fmac_f32_e32 v6, v80, v53
	v_fmac_f32_e32 v22, v76, v37
	v_fma_f32 v54, -v80, v5, v54
	v_fma_f32 v38, -v76, v21, v38
	v_fmac_f32_e32 v6, v78, v5
	v_fmac_f32_e32 v22, v74, v21
	v_fmac_f32_e32 v55, v78, v54
	v_fmac_f32_e32 v39, v74, v38
	v_fmac_f32_e32 v7, v80, v54
	v_fmac_f32_e32 v23, v76, v38
	v_fma_f32 v55, -v80, v6, v55
	v_fma_f32 v39, -v76, v22, v39
	v_fmac_f32_e32 v7, v78, v6
	v_fmac_f32_e32 v23, v74, v22
	v_fmac_f32_e32 v56, v78, v55
	v_fmac_f32_e32 v40, v74, v39
	v_fmac_f32_e32 v8, v80, v55
	v_fmac_f32_e32 v24, v76, v39
	v_fma_f32 v56, -v80, v7, v56
	v_fma_f32 v40, -v76, v23, v40
	v_fmac_f32_e32 v8, v78, v7
	v_fmac_f32_e32 v24, v74, v23
	v_fmac_f32_e32 v57, v78, v56
	v_fmac_f32_e32 v41, v74, v40
	v_fmac_f32_e32 v9, v80, v56
	v_fmac_f32_e32 v25, v76, v40
	v_fma_f32 v57, -v80, v8, v57
	v_fma_f32 v41, -v76, v24, v41
	v_fmac_f32_e32 v9, v78, v8
	v_fmac_f32_e32 v25, v74, v24
	v_fmac_f32_e32 v58, v78, v57
	v_fmac_f32_e32 v42, v74, v41
	v_fmac_f32_e32 v10, v80, v57
	v_fmac_f32_e32 v26, v76, v41
	v_fma_f32 v58, -v80, v9, v58
	v_fma_f32 v42, -v76, v25, v42
	v_fmac_f32_e32 v10, v78, v9
	v_fmac_f32_e32 v26, v74, v25
	v_fmac_f32_e32 v59, v78, v58
	v_fmac_f32_e32 v43, v74, v42
	v_fmac_f32_e32 v11, v80, v58
	v_fmac_f32_e32 v27, v76, v42
	v_fma_f32 v59, -v80, v10, v59
	v_fma_f32 v43, -v76, v26, v43
	v_fmac_f32_e32 v11, v78, v10
	v_fmac_f32_e32 v27, v74, v26
	v_fmac_f32_e32 v60, v78, v59
	v_fmac_f32_e32 v44, v74, v43
	v_fmac_f32_e32 v12, v80, v59
	v_fmac_f32_e32 v28, v76, v43
	v_fma_f32 v60, -v80, v11, v60
	v_fma_f32 v44, -v76, v27, v44
	v_fmac_f32_e32 v12, v78, v11
	v_fmac_f32_e32 v28, v74, v27
	v_fmac_f32_e32 v61, v78, v60
	v_fmac_f32_e32 v45, v74, v44
	v_fmac_f32_e32 v13, v80, v60
	v_fmac_f32_e32 v29, v76, v44
	v_fma_f32 v61, -v80, v12, v61
	v_fma_f32 v45, -v76, v28, v45
	v_fmac_f32_e32 v13, v78, v12
	v_fmac_f32_e32 v29, v74, v28
	v_fmac_f32_e32 v62, v78, v61
	v_fmac_f32_e32 v46, v74, v45
	v_fmac_f32_e32 v14, v80, v61
	v_fmac_f32_e32 v30, v76, v45
	v_fma_f32 v62, -v80, v13, v62
	v_fma_f32 v46, -v76, v29, v46
	v_fmac_f32_e32 v14, v78, v13
	v_fmac_f32_e32 v30, v74, v29
	v_fmac_f32_e32 v63, v78, v62
	v_fmac_f32_e32 v47, v74, v46
	v_fmac_f32_e32 v15, v80, v62
	v_fmac_f32_e32 v31, v76, v46
	v_fma_f32 v63, -v80, v14, v63
	v_fma_f32 v47, -v76, v30, v47
	v_fmac_f32_e32 v15, v78, v14
	v_fmac_f32_e32 v31, v74, v30
	v_fmac_f32_e32 v64, v78, v63
	v_fmac_f32_e32 v48, v74, v47
	v_fmac_f32_e32 v16, v80, v63
	v_fmac_f32_e32 v32, v76, v47
	v_fma_f32 v64, -v80, v15, v64
	v_fma_f32 v48, -v76, v31, v48
	v_fmac_f32_e32 v16, v78, v15
	v_fmac_f32_e32 v32, v74, v31
	v_fmac_f32_e32 v65, v78, v64
	v_fmac_f32_e32 v49, v74, v48
	v_fmac_f32_e32 v17, v80, v64
	v_fmac_f32_e32 v33, v76, v48
	v_fma_f32 v65, -v80, v16, v65
	v_fma_f32 v49, -v76, v32, v49
	v_fmac_f32_e32 v17, v78, v16
	v_fmac_f32_e32 v33, v74, v32
	v_mov_b32_e32 v156, v65
	v_mov_b32_e32 v157, v17
	v_mov_b32_e32 v158, v65
	v_mov_b32_e32 v159, v17
	s_nop 1
	v_permlane32_swap_b32_e32 v156, v158
	v_permlane32_swap_b32_e32 v157, v159
	v_pk_fma_f32 v[164:165], v[166:167], v[152:153], v[156:157] op_sel_hi:[1,0,1]
	v_pk_fma_f32 v[164:165], v[166:167], v[152:153], v[164:165] op_sel:[1,1,0] op_sel_hi:[0,1,1] neg_lo:[0,1,0]
	v_cndmask_b32_e32 v164, v166, v164, vcc
	v_cndmask_b32_e32 v165, v167, v165, vcc
	v_mov_b32_e32 v156, v49
	v_mov_b32_e32 v157, v33
	v_mov_b32_e32 v158, v49
	v_mov_b32_e32 v159, v33
	s_nop 1
	v_permlane32_swap_b32_e32 v156, v158
	v_permlane32_swap_b32_e32 v157, v159
	v_pk_fma_f32 v[170:171], v[150:151], v[154:155], v[156:157] op_sel_hi:[1,0,1]
	v_pk_fma_f32 v[170:171], v[150:151], v[154:155], v[170:171] op_sel:[1,1,0] op_sel_hi:[0,1,1] neg_lo:[0,1,0]
	v_cndmask_b32_e32 v170, v150, v170, vcc
	v_cndmask_b32_e32 v171, v151, v171, vcc
	v_pk_mul_f32 v[168:169], v[164:165], v[70:71] op_sel:[0,1] op_sel_hi:[1,1]
	v_pk_mul_f32 v[172:173], v[170:171], v[66:67] op_sel:[0,1] op_sel_hi:[1,1]
	v_pk_fma_f32 v[168:169], v[164:165], v[72:73], v[168:169] op_sel:[1,1,0] op_sel_hi:[0,1,1] neg_lo:[0,1,0]
	v_pk_fma_f32 v[172:173], v[170:171], v[68:69], v[172:173] op_sel:[1,1,0] op_sel_hi:[0,1,1] neg_lo:[0,1,0]
	v_pk_fma_f32 v[50:51], v[78:79], v[164:165], v[50:51] op_sel_hi:[1,0,1]
	v_pk_fma_f32 v[34:35], v[74:75], v[170:171], v[34:35] op_sel_hi:[1,0,1]
	v_pk_fma_f32 v[52:53], v[70:71], v[164:165], v[52:53] op_sel_hi:[1,0,1]
	v_pk_fma_f32 v[36:37], v[66:67], v[170:171], v[36:37] op_sel_hi:[1,0,1]
	v_pk_fma_f32 v[2:3], v[80:81], v[164:165], v[2:3] op_sel_hi:[1,0,1]
	v_pk_fma_f32 v[18:19], v[76:77], v[170:171], v[18:19] op_sel_hi:[1,0,1]
	v_pk_fma_f32 v[4:5], v[72:73], v[164:165], v[4:5] op_sel_hi:[1,0,1]
	v_pk_fma_f32 v[20:21], v[68:69], v[170:171], v[20:21] op_sel_hi:[1,0,1]
	v_pk_fma_f32 v[50:51], v[80:81], v[164:165], v[50:51] op_sel:[0,1,0] op_sel_hi:[1,1,1] neg_lo:[0,1,0] neg_hi:[0,1,0]
	v_pk_fma_f32 v[34:35], v[76:77], v[170:171], v[34:35] op_sel:[0,1,0] op_sel_hi:[1,1,1] neg_lo:[0,1,0] neg_hi:[0,1,0]
	v_pk_fma_f32 v[52:53], v[72:73], v[164:165], v[52:53] op_sel:[0,1,0] op_sel_hi:[1,1,1] neg_lo:[0,1,0] neg_hi:[0,1,0]
	v_pk_fma_f32 v[36:37], v[68:69], v[170:171], v[36:37] op_sel:[0,1,0] op_sel_hi:[1,1,1] neg_lo:[0,1,0] neg_hi:[0,1,0]
	v_pk_fma_f32 v[2:3], v[78:79], v[164:165], v[2:3] op_sel:[0,1,0] op_sel_hi:[1,1,1]
	v_pk_fma_f32 v[18:19], v[74:75], v[170:171], v[18:19] op_sel:[0,1,0] op_sel_hi:[1,1,1]
	v_pk_fma_f32 v[4:5], v[70:71], v[164:165], v[4:5] op_sel:[0,1,0] op_sel_hi:[1,1,1]
	v_pk_fma_f32 v[20:21], v[66:67], v[170:171], v[20:21] op_sel:[0,1,0] op_sel_hi:[1,1,1]
	v_pk_mul_f32 v[164:165], v[168:169], v[70:71] op_sel:[0,1] op_sel_hi:[1,1]
	v_pk_mul_f32 v[170:171], v[172:173], v[66:67] op_sel:[0,1] op_sel_hi:[1,1]
	v_pk_fma_f32 v[164:165], v[168:169], v[72:73], v[164:165] op_sel:[1,1,0] op_sel_hi:[0,1,1] neg_lo:[0,1,0]
	v_pk_fma_f32 v[170:171], v[172:173], v[68:69], v[170:171] op_sel:[1,1,0] op_sel_hi:[0,1,1] neg_lo:[0,1,0]
	v_pk_fma_f32 v[54:55], v[78:79], v[168:169], v[54:55] op_sel_hi:[1,0,1]
	v_pk_fma_f32 v[38:39], v[74:75], v[172:173], v[38:39] op_sel_hi:[1,0,1]
	v_pk_fma_f32 v[56:57], v[70:71], v[168:169], v[56:57] op_sel_hi:[1,0,1]
	v_pk_fma_f32 v[40:41], v[66:67], v[172:173], v[40:41] op_sel_hi:[1,0,1]
	v_pk_fma_f32 v[6:7], v[80:81], v[168:169], v[6:7] op_sel_hi:[1,0,1]
	v_pk_fma_f32 v[22:23], v[76:77], v[172:173], v[22:23] op_sel_hi:[1,0,1]
	v_pk_fma_f32 v[8:9], v[72:73], v[168:169], v[8:9] op_sel_hi:[1,0,1]
	v_pk_fma_f32 v[24:25], v[68:69], v[172:173], v[24:25] op_sel_hi:[1,0,1]
	v_pk_fma_f32 v[54:55], v[80:81], v[168:169], v[54:55] op_sel:[0,1,0] op_sel_hi:[1,1,1] neg_lo:[0,1,0] neg_hi:[0,1,0]
	v_pk_fma_f32 v[38:39], v[76:77], v[172:173], v[38:39] op_sel:[0,1,0] op_sel_hi:[1,1,1] neg_lo:[0,1,0] neg_hi:[0,1,0]
	v_pk_fma_f32 v[56:57], v[72:73], v[168:169], v[56:57] op_sel:[0,1,0] op_sel_hi:[1,1,1] neg_lo:[0,1,0] neg_hi:[0,1,0]
	v_pk_fma_f32 v[40:41], v[68:69], v[172:173], v[40:41] op_sel:[0,1,0] op_sel_hi:[1,1,1] neg_lo:[0,1,0] neg_hi:[0,1,0]
	v_pk_fma_f32 v[6:7], v[78:79], v[168:169], v[6:7] op_sel:[0,1,0] op_sel_hi:[1,1,1]
	v_pk_fma_f32 v[22:23], v[74:75], v[172:173], v[22:23] op_sel:[0,1,0] op_sel_hi:[1,1,1]
	v_pk_fma_f32 v[8:9], v[70:71], v[168:169], v[8:9] op_sel:[0,1,0] op_sel_hi:[1,1,1]
	v_pk_fma_f32 v[24:25], v[66:67], v[172:173], v[24:25] op_sel:[0,1,0] op_sel_hi:[1,1,1]
	v_pk_mul_f32 v[168:169], v[164:165], v[70:71] op_sel:[0,1] op_sel_hi:[1,1]
	v_pk_mul_f32 v[172:173], v[170:171], v[66:67] op_sel:[0,1] op_sel_hi:[1,1]
	v_pk_fma_f32 v[168:169], v[164:165], v[72:73], v[168:169] op_sel:[1,1,0] op_sel_hi:[0,1,1] neg_lo:[0,1,0]
	v_pk_fma_f32 v[172:173], v[170:171], v[68:69], v[172:173] op_sel:[1,1,0] op_sel_hi:[0,1,1] neg_lo:[0,1,0]
	v_pk_fma_f32 v[58:59], v[78:79], v[164:165], v[58:59] op_sel_hi:[1,0,1]
	v_pk_fma_f32 v[42:43], v[74:75], v[170:171], v[42:43] op_sel_hi:[1,0,1]
	v_pk_fma_f32 v[60:61], v[70:71], v[164:165], v[60:61] op_sel_hi:[1,0,1]
	v_pk_fma_f32 v[44:45], v[66:67], v[170:171], v[44:45] op_sel_hi:[1,0,1]
	v_pk_fma_f32 v[10:11], v[80:81], v[164:165], v[10:11] op_sel_hi:[1,0,1]
	v_pk_fma_f32 v[26:27], v[76:77], v[170:171], v[26:27] op_sel_hi:[1,0,1]
	v_pk_fma_f32 v[12:13], v[72:73], v[164:165], v[12:13] op_sel_hi:[1,0,1]
	v_pk_fma_f32 v[28:29], v[68:69], v[170:171], v[28:29] op_sel_hi:[1,0,1]
	v_pk_fma_f32 v[58:59], v[80:81], v[164:165], v[58:59] op_sel:[0,1,0] op_sel_hi:[1,1,1] neg_lo:[0,1,0] neg_hi:[0,1,0]
	v_pk_fma_f32 v[42:43], v[76:77], v[170:171], v[42:43] op_sel:[0,1,0] op_sel_hi:[1,1,1] neg_lo:[0,1,0] neg_hi:[0,1,0]
	v_pk_fma_f32 v[60:61], v[72:73], v[164:165], v[60:61] op_sel:[0,1,0] op_sel_hi:[1,1,1] neg_lo:[0,1,0] neg_hi:[0,1,0]
	v_pk_fma_f32 v[44:45], v[68:69], v[170:171], v[44:45] op_sel:[0,1,0] op_sel_hi:[1,1,1] neg_lo:[0,1,0] neg_hi:[0,1,0]
	v_pk_fma_f32 v[10:11], v[78:79], v[164:165], v[10:11] op_sel:[0,1,0] op_sel_hi:[1,1,1]
	v_pk_fma_f32 v[26:27], v[74:75], v[170:171], v[26:27] op_sel:[0,1,0] op_sel_hi:[1,1,1]
	v_pk_fma_f32 v[12:13], v[70:71], v[164:165], v[12:13] op_sel:[0,1,0] op_sel_hi:[1,1,1]
	v_pk_fma_f32 v[28:29], v[66:67], v[170:171], v[28:29] op_sel:[0,1,0] op_sel_hi:[1,1,1]
	v_pk_fma_f32 v[62:63], v[78:79], v[168:169], v[62:63] op_sel_hi:[1,0,1]
	v_pk_fma_f32 v[46:47], v[74:75], v[172:173], v[46:47] op_sel_hi:[1,0,1]
	v_pk_fma_f32 v[64:65], v[70:71], v[168:169], v[64:65] op_sel_hi:[1,0,1]
	v_pk_fma_f32 v[48:49], v[66:67], v[172:173], v[48:49] op_sel_hi:[1,0,1]
	v_pk_fma_f32 v[14:15], v[80:81], v[168:169], v[14:15] op_sel_hi:[1,0,1]
	v_pk_fma_f32 v[30:31], v[76:77], v[172:173], v[30:31] op_sel_hi:[1,0,1]
	v_pk_fma_f32 v[16:17], v[72:73], v[168:169], v[16:17] op_sel_hi:[1,0,1]
	v_pk_fma_f32 v[32:33], v[68:69], v[172:173], v[32:33] op_sel_hi:[1,0,1]
	v_pk_fma_f32 v[62:63], v[80:81], v[168:169], v[62:63] op_sel:[0,1,0] op_sel_hi:[1,1,1] neg_lo:[0,1,0] neg_hi:[0,1,0]
	v_pk_fma_f32 v[46:47], v[76:77], v[172:173], v[46:47] op_sel:[0,1,0] op_sel_hi:[1,1,1] neg_lo:[0,1,0] neg_hi:[0,1,0]
	v_pk_fma_f32 v[64:65], v[72:73], v[168:169], v[64:65] op_sel:[0,1,0] op_sel_hi:[1,1,1] neg_lo:[0,1,0] neg_hi:[0,1,0]
	v_pk_fma_f32 v[48:49], v[68:69], v[172:173], v[48:49] op_sel:[0,1,0] op_sel_hi:[1,1,1] neg_lo:[0,1,0] neg_hi:[0,1,0]
	v_pk_fma_f32 v[14:15], v[78:79], v[168:169], v[14:15] op_sel:[0,1,0] op_sel_hi:[1,1,1]
	v_pk_fma_f32 v[30:31], v[74:75], v[172:173], v[30:31] op_sel:[0,1,0] op_sel_hi:[1,1,1]
	v_pk_fma_f32 v[16:17], v[70:71], v[168:169], v[16:17] op_sel:[0,1,0] op_sel_hi:[1,1,1]
	v_pk_fma_f32 v[32:33], v[66:67], v[172:173], v[32:33] op_sel:[0,1,0] op_sel_hi:[1,1,1]
	v_mov_b32_e32 v156, v65
	v_mov_b32_e32 v157, v17
	v_mov_b32_e32 v166, v65
	v_mov_b32_e32 v167, v17
	s_nop 1
	v_permlane32_swap_b32_e32 v156, v166
	v_permlane32_swap_b32_e32 v157, v167
	v_mov_b32_e32 v156, v49
	v_mov_b32_e32 v157, v33
	v_mov_b32_e32 v150, v49
	v_mov_b32_e32 v151, v33
	s_nop 1
	v_permlane32_swap_b32_e32 v156, v150
	v_permlane32_swap_b32_e32 v157, v151
	v_cvt_pk_bf16_f32 v1, v50, v2
	ds_write_b32 v174, v1
	v_cvt_pk_bf16_f32 v146, v34, v18
	ds_write_b32 v174, v146 offset:128
	v_cvt_pk_bf16_f32 v178, v51, v3
	ds_write_b32 v174, v178 offset:272
	v_cvt_pk_bf16_f32 v1, v35, v19
	ds_write_b32 v174, v1 offset:400
	v_cvt_pk_bf16_f32 v146, v52, v4
	ds_write_b32 v174, v146 offset:544
	v_cvt_pk_bf16_f32 v178, v36, v20
	ds_write_b32 v174, v178 offset:672
	v_cvt_pk_bf16_f32 v1, v53, v5
	ds_write_b32 v174, v1 offset:816
	v_cvt_pk_bf16_f32 v146, v37, v21
	ds_write_b32 v174, v146 offset:944
	v_cvt_pk_bf16_f32 v178, v54, v6
	ds_write_b32 v174, v178 offset:1088
	v_cvt_pk_bf16_f32 v1, v38, v22
	ds_write_b32 v174, v1 offset:1216
	v_cvt_pk_bf16_f32 v146, v55, v7
	ds_write_b32 v174, v146 offset:1360
	v_cvt_pk_bf16_f32 v178, v39, v23
	ds_write_b32 v174, v178 offset:1488
	v_cvt_pk_bf16_f32 v1, v56, v8
	ds_write_b32 v174, v1 offset:1632
	v_cvt_pk_bf16_f32 v146, v40, v24
	ds_write_b32 v174, v146 offset:1760
	v_cvt_pk_bf16_f32 v178, v57, v9
	ds_write_b32 v174, v178 offset:1904
	v_cvt_pk_bf16_f32 v1, v41, v25
	ds_write_b32 v174, v1 offset:2032
	v_cvt_pk_bf16_f32 v146, v58, v10
	ds_write_b32 v174, v146 offset:2176
	v_cvt_pk_bf16_f32 v178, v42, v26
	ds_write_b32 v174, v178 offset:2304
	v_cvt_pk_bf16_f32 v1, v59, v11
	ds_write_b32 v174, v1 offset:2448
	v_cvt_pk_bf16_f32 v146, v43, v27
	ds_write_b32 v174, v146 offset:2576
	v_cvt_pk_bf16_f32 v178, v60, v12
	ds_write_b32 v174, v178 offset:2720
	v_cvt_pk_bf16_f32 v1, v44, v28
	ds_write_b32 v174, v1 offset:2848
	v_cvt_pk_bf16_f32 v146, v61, v13
	ds_write_b32 v174, v146 offset:2992
	v_cvt_pk_bf16_f32 v178, v45, v29
	ds_write_b32 v174, v178 offset:3120
	v_cvt_pk_bf16_f32 v1, v62, v14
	ds_write_b32 v174, v1 offset:3264
	v_cvt_pk_bf16_f32 v146, v46, v30
	ds_write_b32 v174, v146 offset:3392
	v_cvt_pk_bf16_f32 v178, v63, v15
	ds_write_b32 v174, v178 offset:3536
	v_cvt_pk_bf16_f32 v1, v47, v31
	ds_write_b32 v174, v1 offset:3664
	v_cvt_pk_bf16_f32 v146, v64, v16
	ds_write_b32 v174, v146 offset:3808
	v_cvt_pk_bf16_f32 v178, v48, v32
	ds_write_b32 v174, v178 offset:3936
	v_cvt_pk_bf16_f32 v1, v65, v17
	ds_write_b32 v174, v1 offset:4080
	v_cvt_pk_bf16_f32 v146, v49, v33
	ds_write_b32 v174, v146 offset:4208
	s_waitcnt lgkmcnt(0)
	ds_read_b128 v[2:5], v175
	ds_read_b128 v[6:9], v175 offset:64
	ds_read_b128 v[10:13], v175 offset:128
	ds_read_b128 v[14:17], v175 offset:192
	ds_read_b128 v[18:21], v175 offset:4352
	ds_read_b128 v[22:25], v175 offset:4416
	ds_read_b128 v[26:29], v175 offset:4480
	ds_read_b128 v[30:33], v175 offset:4544
	s_waitcnt vmcnt(0)
	s_waitcnt lgkmcnt(7)
	v_mfma_f32_16x16x32_bf16 v[34:37], v[94:97], v[2:5], 0
	s_waitcnt lgkmcnt(6)
	v_mfma_f32_16x16x32_bf16 v[34:37], v[90:93], v[6:9], v[34:37]
	s_waitcnt lgkmcnt(5)
	v_mfma_f32_16x16x32_bf16 v[34:37], v[86:89], v[10:13], v[34:37]
	s_waitcnt lgkmcnt(4)
	v_mfma_f32_16x16x32_bf16 v[34:37], v[82:85], v[14:17], v[34:37]
	s_waitcnt lgkmcnt(3)
	v_mfma_f32_16x16x32_bf16 v[38:41], v[94:97], v[18:21], 0
	s_waitcnt lgkmcnt(2)
	v_mfma_f32_16x16x32_bf16 v[38:41], v[90:93], v[22:25], v[38:41]
	s_waitcnt lgkmcnt(1)
	v_mfma_f32_16x16x32_bf16 v[38:41], v[86:89], v[26:29], v[38:41]
	s_waitcnt lgkmcnt(0)
	v_mfma_f32_16x16x32_bf16 v[38:41], v[82:85], v[30:33], v[38:41]
	s_add_u32 s6, s6, 0x8000
	s_addc_u32 s7, s7, 0
	v_lshlrev_b32_e32 v42, 16, v160
	v_and_b32_e32 v43, 0xffff0000, v160
	v_lshlrev_b32_e32 v44, 16, v161
	v_and_b32_e32 v45, 0xffff0000, v161
	v_lshlrev_b32_e32 v46, 16, v162
	v_and_b32_e32 v47, 0xffff0000, v162
	v_lshlrev_b32_e32 v48, 16, v163
	v_and_b32_e32 v49, 0xffff0000, v163
	s_nop 1
	v_fma_f32 v50, v98, v42, v34
	v_fma_f32 v51, v99, v43, v35
	v_fma_f32 v52, v100, v44, v36
	v_fma_f32 v53, v101, v45, v37
	v_fma_f32 v54, v98, v46, v38
	v_fma_f32 v55, v99, v47, v39
	v_fma_f32 v56, v100, v48, v40
	v_fma_f32 v57, v101, v49, v41
	v_mul_f32_e32 v2, 0x3d372713, v50
	v_mul_f32_e32 v3, 0x3d372713, v51
	v_mul_f32_e32 v4, 0x3d372713, v52
	v_mul_f32_e32 v5, 0x3d372713, v53
	v_mul_f32_e32 v6, 0x3d372713, v54
	v_mul_f32_e32 v7, 0x3d372713, v55
	v_mul_f32_e32 v8, 0x3d372713, v56
	v_mul_f32_e32 v9, 0x3d372713, v57
	v_mul_f32_e32 v2, v50, v2
	v_mul_f32_e32 v3, v51, v3
	v_mul_f32_e32 v4, v52, v4
	v_mul_f32_e32 v5, v53, v5
	v_mul_f32_e32 v6, v54, v6
	v_mul_f32_e32 v7, v55, v7
	v_mul_f32_e32 v8, v56, v8
	v_mul_f32_e32 v9, v57, v9
	v_fma_f32 v2, v50, v2, v50
	v_fma_f32 v3, v51, v3, v51
	v_fma_f32 v4, v52, v4, v52
	v_fma_f32 v5, v53, v5, v53
	v_fma_f32 v6, v54, v6, v54
	v_fma_f32 v7, v55, v7, v55
	v_fma_f32 v8, v56, v8, v56
	v_fma_f32 v9, v57, v9, v57
	v_mul_f32_e32 v2, 0xbfcc422a, v2
	v_mul_f32_e32 v3, 0xbfcc422a, v3
	v_mul_f32_e32 v4, 0xbfcc422a, v4
	v_mul_f32_e32 v5, 0xbfcc422a, v5
	v_mul_f32_e32 v6, 0xbfcc422a, v6
	v_mul_f32_e32 v7, 0xbfcc422a, v7
	v_mul_f32_e32 v8, 0xbfcc422a, v8
	v_mul_f32_e32 v9, 0xbfcc422a, v9
	v_mul_f32_e32 v2, 0x3fb8aa3b, v2
	v_mul_f32_e32 v3, 0x3fb8aa3b, v3
	v_mul_f32_e32 v4, 0x3fb8aa3b, v4
	v_mul_f32_e32 v5, 0x3fb8aa3b, v5
	v_mul_f32_e32 v6, 0x3fb8aa3b, v6
	v_mul_f32_e32 v7, 0x3fb8aa3b, v7
	v_mul_f32_e32 v8, 0x3fb8aa3b, v8
	v_mul_f32_e32 v9, 0x3fb8aa3b, v9
	v_exp_f32_e32 v2, v2
	v_exp_f32_e32 v3, v3
	v_exp_f32_e32 v4, v4
	v_exp_f32_e32 v5, v5
	v_exp_f32_e32 v6, v6
	v_exp_f32_e32 v7, v7
	v_exp_f32_e32 v8, v8
	v_exp_f32_e32 v9, v9
	v_add_f32_e32 v2, 1.0, v2
	v_add_f32_e32 v3, 1.0, v3
	v_add_f32_e32 v4, 1.0, v4
	v_add_f32_e32 v5, 1.0, v5
	v_add_f32_e32 v6, 1.0, v6
	v_add_f32_e32 v7, 1.0, v7
	v_add_f32_e32 v8, 1.0, v8
	v_add_f32_e32 v9, 1.0, v9
	v_rcp_f32_e32 v2, v2
	v_rcp_f32_e32 v3, v3
	v_rcp_f32_e32 v4, v4
	v_rcp_f32_e32 v5, v5
	v_rcp_f32_e32 v6, v6
	v_rcp_f32_e32 v7, v7
	v_rcp_f32_e32 v8, v8
	v_rcp_f32_e32 v9, v9
	v_mul_f32_e32 v50, v50, v2
	v_mul_f32_e32 v51, v51, v3
	v_mul_f32_e32 v52, v52, v4
	v_mul_f32_e32 v53, v53, v5
	v_mul_f32_e32 v54, v54, v6
	v_mul_f32_e32 v55, v55, v7
	v_mul_f32_e32 v56, v56, v8
	v_mul_f32_e32 v57, v57, v9
	v_cvt_pk_bf16_f32 v10, v50, v51
	v_cvt_pk_bf16_f32 v11, v52, v53
	v_cvt_pk_bf16_f32 v12, v54, v55
	v_cvt_pk_bf16_f32 v13, v56, v57
	global_store_dwordx2 v176, v[10:11], s[10:11]
	global_store_dwordx2 v177, v[12:13], s[10:11]
	s_add_u32 s10, s10, 0x8000
	s_addc_u32 s11, s11, 0
	s_nop 0
	v_mfma_f32_32x32x16_bf16 v[50:65], v[142:145], v[114:117], 0
	v_mfma_f32_32x32x16_bf16 v[2:17], v[142:145], v[110:113], 0
	v_mfma_f32_32x32x16_bf16 v[34:49], v[142:145], v[106:109], 0
	v_mfma_f32_32x32x16_bf16 v[18:33], v[142:145], v[102:105], 0
	global_load_dwordx2 v[160:161], v176, s[6:7]
	global_load_dwordx2 v[162:163], v177, s[6:7]
	s_nop 9
	v_fmac_f32_e32 v51, v78, v50
	v_fmac_f32_e32 v35, v74, v34
	v_fmac_f32_e32 v3, v80, v50
	v_fmac_f32_e32 v19, v76, v34
	v_fma_f32 v51, -v80, v2, v51
	v_fma_f32 v35, -v76, v18, v35
	v_fmac_f32_e32 v3, v78, v2
	v_fmac_f32_e32 v19, v74, v18
	v_fmac_f32_e32 v52, v78, v51
	v_fmac_f32_e32 v36, v74, v35
	v_fmac_f32_e32 v4, v80, v51
	v_fmac_f32_e32 v20, v76, v35
	v_fma_f32 v52, -v80, v3, v52
	v_fma_f32 v36, -v76, v19, v36
	v_fmac_f32_e32 v4, v78, v3
	v_fmac_f32_e32 v20, v74, v19
	v_fmac_f32_e32 v53, v78, v52
	v_fmac_f32_e32 v37, v74, v36
	v_fmac_f32_e32 v5, v80, v52
	v_fmac_f32_e32 v21, v76, v36
	v_fma_f32 v53, -v80, v4, v53
	v_fma_f32 v37, -v76, v20, v37
	v_fmac_f32_e32 v5, v78, v4
	v_fmac_f32_e32 v21, v74, v20
	v_fmac_f32_e32 v54, v78, v53
	v_fmac_f32_e32 v38, v74, v37
	v_fmac_f32_e32 v6, v80, v53
	v_fmac_f32_e32 v22, v76, v37
	v_fma_f32 v54, -v80, v5, v54
	v_fma_f32 v38, -v76, v21, v38
	v_fmac_f32_e32 v6, v78, v5
	v_fmac_f32_e32 v22, v74, v21
	v_fmac_f32_e32 v55, v78, v54
	v_fmac_f32_e32 v39, v74, v38
	v_fmac_f32_e32 v7, v80, v54
	v_fmac_f32_e32 v23, v76, v38
	v_fma_f32 v55, -v80, v6, v55
	v_fma_f32 v39, -v76, v22, v39
	v_fmac_f32_e32 v7, v78, v6
	v_fmac_f32_e32 v23, v74, v22
	v_fmac_f32_e32 v56, v78, v55
	v_fmac_f32_e32 v40, v74, v39
	v_fmac_f32_e32 v8, v80, v55
	v_fmac_f32_e32 v24, v76, v39
	v_fma_f32 v56, -v80, v7, v56
	v_fma_f32 v40, -v76, v23, v40
	v_fmac_f32_e32 v8, v78, v7
	v_fmac_f32_e32 v24, v74, v23
	v_fmac_f32_e32 v57, v78, v56
	v_fmac_f32_e32 v41, v74, v40
	v_fmac_f32_e32 v9, v80, v56
	v_fmac_f32_e32 v25, v76, v40
	v_fma_f32 v57, -v80, v8, v57
	v_fma_f32 v41, -v76, v24, v41
	v_fmac_f32_e32 v9, v78, v8
	v_fmac_f32_e32 v25, v74, v24
	v_fmac_f32_e32 v58, v78, v57
	v_fmac_f32_e32 v42, v74, v41
	v_fmac_f32_e32 v10, v80, v57
	v_fmac_f32_e32 v26, v76, v41
	v_fma_f32 v58, -v80, v9, v58
	v_fma_f32 v42, -v76, v25, v42
	v_fmac_f32_e32 v10, v78, v9
	v_fmac_f32_e32 v26, v74, v25
	v_fmac_f32_e32 v59, v78, v58
	v_fmac_f32_e32 v43, v74, v42
	v_fmac_f32_e32 v11, v80, v58
	v_fmac_f32_e32 v27, v76, v42
	v_fma_f32 v59, -v80, v10, v59
	v_fma_f32 v43, -v76, v26, v43
	v_fmac_f32_e32 v11, v78, v10
	v_fmac_f32_e32 v27, v74, v26
	v_fmac_f32_e32 v60, v78, v59
	v_fmac_f32_e32 v44, v74, v43
	v_fmac_f32_e32 v12, v80, v59
	v_fmac_f32_e32 v28, v76, v43
	v_fma_f32 v60, -v80, v11, v60
	v_fma_f32 v44, -v76, v27, v44
	v_fmac_f32_e32 v12, v78, v11
	v_fmac_f32_e32 v28, v74, v27
	v_fmac_f32_e32 v61, v78, v60
	v_fmac_f32_e32 v45, v74, v44
	v_fmac_f32_e32 v13, v80, v60
	v_fmac_f32_e32 v29, v76, v44
	v_fma_f32 v61, -v80, v12, v61
	v_fma_f32 v45, -v76, v28, v45
	v_fmac_f32_e32 v13, v78, v12
	v_fmac_f32_e32 v29, v74, v28
	v_fmac_f32_e32 v62, v78, v61
	v_fmac_f32_e32 v46, v74, v45
	v_fmac_f32_e32 v14, v80, v61
	v_fmac_f32_e32 v30, v76, v45
	v_fma_f32 v62, -v80, v13, v62
	v_fma_f32 v46, -v76, v29, v46
	v_fmac_f32_e32 v14, v78, v13
	v_fmac_f32_e32 v30, v74, v29
	v_fmac_f32_e32 v63, v78, v62
	v_fmac_f32_e32 v47, v74, v46
	v_fmac_f32_e32 v15, v80, v62
	v_fmac_f32_e32 v31, v76, v46
	v_fma_f32 v63, -v80, v14, v63
	v_fma_f32 v47, -v76, v30, v47
	v_fmac_f32_e32 v15, v78, v14
	v_fmac_f32_e32 v31, v74, v30
	v_fmac_f32_e32 v64, v78, v63
	v_fmac_f32_e32 v48, v74, v47
	v_fmac_f32_e32 v16, v80, v63
	v_fmac_f32_e32 v32, v76, v47
	v_fma_f32 v64, -v80, v15, v64
	v_fma_f32 v48, -v76, v31, v48
	v_fmac_f32_e32 v16, v78, v15
	v_fmac_f32_e32 v32, v74, v31
	v_fmac_f32_e32 v65, v78, v64
	v_fmac_f32_e32 v49, v74, v48
	v_fmac_f32_e32 v17, v80, v64
	v_fmac_f32_e32 v33, v76, v48
	v_fma_f32 v65, -v80, v16, v65
	v_fma_f32 v49, -v76, v32, v49
	v_fmac_f32_e32 v17, v78, v16
	v_fmac_f32_e32 v33, v74, v32
	v_mov_b32_e32 v156, v65
	v_mov_b32_e32 v157, v17
	v_mov_b32_e32 v158, v65
	v_mov_b32_e32 v159, v17
	s_nop 1
	v_permlane32_swap_b32_e32 v156, v158
	v_permlane32_swap_b32_e32 v157, v159
	v_pk_fma_f32 v[164:165], v[166:167], v[152:153], v[156:157] op_sel_hi:[1,0,1]
	v_pk_fma_f32 v[164:165], v[166:167], v[152:153], v[164:165] op_sel:[1,1,0] op_sel_hi:[0,1,1] neg_lo:[0,1,0]
	v_cndmask_b32_e32 v164, v166, v164, vcc
	v_cndmask_b32_e32 v165, v167, v165, vcc
	v_mov_b32_e32 v156, v49
	v_mov_b32_e32 v157, v33
	v_mov_b32_e32 v158, v49
	v_mov_b32_e32 v159, v33
	s_nop 1
	v_permlane32_swap_b32_e32 v156, v158
	v_permlane32_swap_b32_e32 v157, v159
	v_pk_fma_f32 v[170:171], v[150:151], v[154:155], v[156:157] op_sel_hi:[1,0,1]
	v_pk_fma_f32 v[170:171], v[150:151], v[154:155], v[170:171] op_sel:[1,1,0] op_sel_hi:[0,1,1] neg_lo:[0,1,0]
	v_cndmask_b32_e32 v170, v150, v170, vcc
	v_cndmask_b32_e32 v171, v151, v171, vcc
	v_pk_mul_f32 v[168:169], v[164:165], v[70:71] op_sel:[0,1] op_sel_hi:[1,1]
	v_pk_mul_f32 v[172:173], v[170:171], v[66:67] op_sel:[0,1] op_sel_hi:[1,1]
	v_pk_fma_f32 v[168:169], v[164:165], v[72:73], v[168:169] op_sel:[1,1,0] op_sel_hi:[0,1,1] neg_lo:[0,1,0]
	v_pk_fma_f32 v[172:173], v[170:171], v[68:69], v[172:173] op_sel:[1,1,0] op_sel_hi:[0,1,1] neg_lo:[0,1,0]
	v_pk_fma_f32 v[50:51], v[78:79], v[164:165], v[50:51] op_sel_hi:[1,0,1]
	v_pk_fma_f32 v[34:35], v[74:75], v[170:171], v[34:35] op_sel_hi:[1,0,1]
	v_pk_fma_f32 v[52:53], v[70:71], v[164:165], v[52:53] op_sel_hi:[1,0,1]
	v_pk_fma_f32 v[36:37], v[66:67], v[170:171], v[36:37] op_sel_hi:[1,0,1]
	v_pk_fma_f32 v[2:3], v[80:81], v[164:165], v[2:3] op_sel_hi:[1,0,1]
	v_pk_fma_f32 v[18:19], v[76:77], v[170:171], v[18:19] op_sel_hi:[1,0,1]
	v_pk_fma_f32 v[4:5], v[72:73], v[164:165], v[4:5] op_sel_hi:[1,0,1]
	v_pk_fma_f32 v[20:21], v[68:69], v[170:171], v[20:21] op_sel_hi:[1,0,1]
	v_pk_fma_f32 v[50:51], v[80:81], v[164:165], v[50:51] op_sel:[0,1,0] op_sel_hi:[1,1,1] neg_lo:[0,1,0] neg_hi:[0,1,0]
	v_pk_fma_f32 v[34:35], v[76:77], v[170:171], v[34:35] op_sel:[0,1,0] op_sel_hi:[1,1,1] neg_lo:[0,1,0] neg_hi:[0,1,0]
	v_pk_fma_f32 v[52:53], v[72:73], v[164:165], v[52:53] op_sel:[0,1,0] op_sel_hi:[1,1,1] neg_lo:[0,1,0] neg_hi:[0,1,0]
	v_pk_fma_f32 v[36:37], v[68:69], v[170:171], v[36:37] op_sel:[0,1,0] op_sel_hi:[1,1,1] neg_lo:[0,1,0] neg_hi:[0,1,0]
	v_pk_fma_f32 v[2:3], v[78:79], v[164:165], v[2:3] op_sel:[0,1,0] op_sel_hi:[1,1,1]
	v_pk_fma_f32 v[18:19], v[74:75], v[170:171], v[18:19] op_sel:[0,1,0] op_sel_hi:[1,1,1]
	v_pk_fma_f32 v[4:5], v[70:71], v[164:165], v[4:5] op_sel:[0,1,0] op_sel_hi:[1,1,1]
	v_pk_fma_f32 v[20:21], v[66:67], v[170:171], v[20:21] op_sel:[0,1,0] op_sel_hi:[1,1,1]
	v_pk_mul_f32 v[164:165], v[168:169], v[70:71] op_sel:[0,1] op_sel_hi:[1,1]
	v_pk_mul_f32 v[170:171], v[172:173], v[66:67] op_sel:[0,1] op_sel_hi:[1,1]
	v_pk_fma_f32 v[164:165], v[168:169], v[72:73], v[164:165] op_sel:[1,1,0] op_sel_hi:[0,1,1] neg_lo:[0,1,0]
	v_pk_fma_f32 v[170:171], v[172:173], v[68:69], v[170:171] op_sel:[1,1,0] op_sel_hi:[0,1,1] neg_lo:[0,1,0]
	v_pk_fma_f32 v[54:55], v[78:79], v[168:169], v[54:55] op_sel_hi:[1,0,1]
	v_pk_fma_f32 v[38:39], v[74:75], v[172:173], v[38:39] op_sel_hi:[1,0,1]
	v_pk_fma_f32 v[56:57], v[70:71], v[168:169], v[56:57] op_sel_hi:[1,0,1]
	v_pk_fma_f32 v[40:41], v[66:67], v[172:173], v[40:41] op_sel_hi:[1,0,1]
	v_pk_fma_f32 v[6:7], v[80:81], v[168:169], v[6:7] op_sel_hi:[1,0,1]
	v_pk_fma_f32 v[22:23], v[76:77], v[172:173], v[22:23] op_sel_hi:[1,0,1]
	v_pk_fma_f32 v[8:9], v[72:73], v[168:169], v[8:9] op_sel_hi:[1,0,1]
	v_pk_fma_f32 v[24:25], v[68:69], v[172:173], v[24:25] op_sel_hi:[1,0,1]
	v_pk_fma_f32 v[54:55], v[80:81], v[168:169], v[54:55] op_sel:[0,1,0] op_sel_hi:[1,1,1] neg_lo:[0,1,0] neg_hi:[0,1,0]
	v_pk_fma_f32 v[38:39], v[76:77], v[172:173], v[38:39] op_sel:[0,1,0] op_sel_hi:[1,1,1] neg_lo:[0,1,0] neg_hi:[0,1,0]
	v_pk_fma_f32 v[56:57], v[72:73], v[168:169], v[56:57] op_sel:[0,1,0] op_sel_hi:[1,1,1] neg_lo:[0,1,0] neg_hi:[0,1,0]
	v_pk_fma_f32 v[40:41], v[68:69], v[172:173], v[40:41] op_sel:[0,1,0] op_sel_hi:[1,1,1] neg_lo:[0,1,0] neg_hi:[0,1,0]
	v_pk_fma_f32 v[6:7], v[78:79], v[168:169], v[6:7] op_sel:[0,1,0] op_sel_hi:[1,1,1]
	v_pk_fma_f32 v[22:23], v[74:75], v[172:173], v[22:23] op_sel:[0,1,0] op_sel_hi:[1,1,1]
	v_pk_fma_f32 v[8:9], v[70:71], v[168:169], v[8:9] op_sel:[0,1,0] op_sel_hi:[1,1,1]
	v_pk_fma_f32 v[24:25], v[66:67], v[172:173], v[24:25] op_sel:[0,1,0] op_sel_hi:[1,1,1]
	v_pk_mul_f32 v[168:169], v[164:165], v[70:71] op_sel:[0,1] op_sel_hi:[1,1]
	v_pk_mul_f32 v[172:173], v[170:171], v[66:67] op_sel:[0,1] op_sel_hi:[1,1]
	v_pk_fma_f32 v[168:169], v[164:165], v[72:73], v[168:169] op_sel:[1,1,0] op_sel_hi:[0,1,1] neg_lo:[0,1,0]
	v_pk_fma_f32 v[172:173], v[170:171], v[68:69], v[172:173] op_sel:[1,1,0] op_sel_hi:[0,1,1] neg_lo:[0,1,0]
	v_pk_fma_f32 v[58:59], v[78:79], v[164:165], v[58:59] op_sel_hi:[1,0,1]
	v_pk_fma_f32 v[42:43], v[74:75], v[170:171], v[42:43] op_sel_hi:[1,0,1]
	v_pk_fma_f32 v[60:61], v[70:71], v[164:165], v[60:61] op_sel_hi:[1,0,1]
	v_pk_fma_f32 v[44:45], v[66:67], v[170:171], v[44:45] op_sel_hi:[1,0,1]
	v_pk_fma_f32 v[10:11], v[80:81], v[164:165], v[10:11] op_sel_hi:[1,0,1]
	v_pk_fma_f32 v[26:27], v[76:77], v[170:171], v[26:27] op_sel_hi:[1,0,1]
	v_pk_fma_f32 v[12:13], v[72:73], v[164:165], v[12:13] op_sel_hi:[1,0,1]
	v_pk_fma_f32 v[28:29], v[68:69], v[170:171], v[28:29] op_sel_hi:[1,0,1]
	v_pk_fma_f32 v[58:59], v[80:81], v[164:165], v[58:59] op_sel:[0,1,0] op_sel_hi:[1,1,1] neg_lo:[0,1,0] neg_hi:[0,1,0]
	v_pk_fma_f32 v[42:43], v[76:77], v[170:171], v[42:43] op_sel:[0,1,0] op_sel_hi:[1,1,1] neg_lo:[0,1,0] neg_hi:[0,1,0]
	v_pk_fma_f32 v[60:61], v[72:73], v[164:165], v[60:61] op_sel:[0,1,0] op_sel_hi:[1,1,1] neg_lo:[0,1,0] neg_hi:[0,1,0]
	v_pk_fma_f32 v[44:45], v[68:69], v[170:171], v[44:45] op_sel:[0,1,0] op_sel_hi:[1,1,1] neg_lo:[0,1,0] neg_hi:[0,1,0]
	v_pk_fma_f32 v[10:11], v[78:79], v[164:165], v[10:11] op_sel:[0,1,0] op_sel_hi:[1,1,1]
	v_pk_fma_f32 v[26:27], v[74:75], v[170:171], v[26:27] op_sel:[0,1,0] op_sel_hi:[1,1,1]
	v_pk_fma_f32 v[12:13], v[70:71], v[164:165], v[12:13] op_sel:[0,1,0] op_sel_hi:[1,1,1]
	v_pk_fma_f32 v[28:29], v[66:67], v[170:171], v[28:29] op_sel:[0,1,0] op_sel_hi:[1,1,1]
	v_pk_fma_f32 v[62:63], v[78:79], v[168:169], v[62:63] op_sel_hi:[1,0,1]
	v_pk_fma_f32 v[46:47], v[74:75], v[172:173], v[46:47] op_sel_hi:[1,0,1]
	v_pk_fma_f32 v[64:65], v[70:71], v[168:169], v[64:65] op_sel_hi:[1,0,1]
	v_pk_fma_f32 v[48:49], v[66:67], v[172:173], v[48:49] op_sel_hi:[1,0,1]
	v_pk_fma_f32 v[14:15], v[80:81], v[168:169], v[14:15] op_sel_hi:[1,0,1]
	v_pk_fma_f32 v[30:31], v[76:77], v[172:173], v[30:31] op_sel_hi:[1,0,1]
	v_pk_fma_f32 v[16:17], v[72:73], v[168:169], v[16:17] op_sel_hi:[1,0,1]
	v_pk_fma_f32 v[32:33], v[68:69], v[172:173], v[32:33] op_sel_hi:[1,0,1]
	v_pk_fma_f32 v[62:63], v[80:81], v[168:169], v[62:63] op_sel:[0,1,0] op_sel_hi:[1,1,1] neg_lo:[0,1,0] neg_hi:[0,1,0]
	v_pk_fma_f32 v[46:47], v[76:77], v[172:173], v[46:47] op_sel:[0,1,0] op_sel_hi:[1,1,1] neg_lo:[0,1,0] neg_hi:[0,1,0]
	v_pk_fma_f32 v[64:65], v[72:73], v[168:169], v[64:65] op_sel:[0,1,0] op_sel_hi:[1,1,1] neg_lo:[0,1,0] neg_hi:[0,1,0]
	v_pk_fma_f32 v[48:49], v[68:69], v[172:173], v[48:49] op_sel:[0,1,0] op_sel_hi:[1,1,1] neg_lo:[0,1,0] neg_hi:[0,1,0]
	v_pk_fma_f32 v[14:15], v[78:79], v[168:169], v[14:15] op_sel:[0,1,0] op_sel_hi:[1,1,1]
	v_pk_fma_f32 v[30:31], v[74:75], v[172:173], v[30:31] op_sel:[0,1,0] op_sel_hi:[1,1,1]
	v_pk_fma_f32 v[16:17], v[70:71], v[168:169], v[16:17] op_sel:[0,1,0] op_sel_hi:[1,1,1]
	v_pk_fma_f32 v[32:33], v[66:67], v[172:173], v[32:33] op_sel:[0,1,0] op_sel_hi:[1,1,1]
	v_mov_b32_e32 v156, v65
	v_mov_b32_e32 v157, v17
	v_mov_b32_e32 v166, v65
	v_mov_b32_e32 v167, v17
	s_nop 1
	v_permlane32_swap_b32_e32 v156, v166
	v_permlane32_swap_b32_e32 v157, v167
	v_mov_b32_e32 v156, v49
	v_mov_b32_e32 v157, v33
	v_mov_b32_e32 v150, v49
	v_mov_b32_e32 v151, v33
	s_nop 1
	v_permlane32_swap_b32_e32 v156, v150
	v_permlane32_swap_b32_e32 v157, v151
	v_cvt_pk_bf16_f32 v1, v50, v2
	ds_write_b32 v174, v1
	v_cvt_pk_bf16_f32 v146, v34, v18
	ds_write_b32 v174, v146 offset:128
	v_cvt_pk_bf16_f32 v178, v51, v3
	ds_write_b32 v174, v178 offset:272
	v_cvt_pk_bf16_f32 v1, v35, v19
	ds_write_b32 v174, v1 offset:400
	v_cvt_pk_bf16_f32 v146, v52, v4
	ds_write_b32 v174, v146 offset:544
	v_cvt_pk_bf16_f32 v178, v36, v20
	ds_write_b32 v174, v178 offset:672
	v_cvt_pk_bf16_f32 v1, v53, v5
	ds_write_b32 v174, v1 offset:816
	v_cvt_pk_bf16_f32 v146, v37, v21
	ds_write_b32 v174, v146 offset:944
	v_cvt_pk_bf16_f32 v178, v54, v6
	ds_write_b32 v174, v178 offset:1088
	v_cvt_pk_bf16_f32 v1, v38, v22
	ds_write_b32 v174, v1 offset:1216
	v_cvt_pk_bf16_f32 v146, v55, v7
	ds_write_b32 v174, v146 offset:1360
	v_cvt_pk_bf16_f32 v178, v39, v23
	ds_write_b32 v174, v178 offset:1488
	v_cvt_pk_bf16_f32 v1, v56, v8
	ds_write_b32 v174, v1 offset:1632
	v_cvt_pk_bf16_f32 v146, v40, v24
	ds_write_b32 v174, v146 offset:1760
	v_cvt_pk_bf16_f32 v178, v57, v9
	ds_write_b32 v174, v178 offset:1904
	v_cvt_pk_bf16_f32 v1, v41, v25
	ds_write_b32 v174, v1 offset:2032
	v_cvt_pk_bf16_f32 v146, v58, v10
	ds_write_b32 v174, v146 offset:2176
	v_cvt_pk_bf16_f32 v178, v42, v26
	ds_write_b32 v174, v178 offset:2304
	v_cvt_pk_bf16_f32 v1, v59, v11
	ds_write_b32 v174, v1 offset:2448
	v_cvt_pk_bf16_f32 v146, v43, v27
	ds_write_b32 v174, v146 offset:2576
	v_cvt_pk_bf16_f32 v178, v60, v12
	ds_write_b32 v174, v178 offset:2720
	v_cvt_pk_bf16_f32 v1, v44, v28
	ds_write_b32 v174, v1 offset:2848
	v_cvt_pk_bf16_f32 v146, v61, v13
	ds_write_b32 v174, v146 offset:2992
	v_cvt_pk_bf16_f32 v178, v45, v29
	ds_write_b32 v174, v178 offset:3120
	v_cvt_pk_bf16_f32 v1, v62, v14
	ds_write_b32 v174, v1 offset:3264
	v_cvt_pk_bf16_f32 v146, v46, v30
	ds_write_b32 v174, v146 offset:3392
	v_cvt_pk_bf16_f32 v178, v63, v15
	ds_write_b32 v174, v178 offset:3536
	v_cvt_pk_bf16_f32 v1, v47, v31
	ds_write_b32 v174, v1 offset:3664
	v_cvt_pk_bf16_f32 v146, v64, v16
	ds_write_b32 v174, v146 offset:3808
	v_cvt_pk_bf16_f32 v178, v48, v32
	ds_write_b32 v174, v178 offset:3936
	v_cvt_pk_bf16_f32 v1, v65, v17
	ds_write_b32 v174, v1 offset:4080
	v_cvt_pk_bf16_f32 v146, v49, v33
	ds_write_b32 v174, v146 offset:4208
	s_waitcnt lgkmcnt(0)
	ds_read_b128 v[2:5], v175
	ds_read_b128 v[6:9], v175 offset:64
	ds_read_b128 v[10:13], v175 offset:128
	ds_read_b128 v[14:17], v175 offset:192
	ds_read_b128 v[18:21], v175 offset:4352
	ds_read_b128 v[22:25], v175 offset:4416
	ds_read_b128 v[26:29], v175 offset:4480
	ds_read_b128 v[30:33], v175 offset:4544
	s_waitcnt vmcnt(0)
	s_waitcnt lgkmcnt(7)
	v_mfma_f32_16x16x32_bf16 v[34:37], v[94:97], v[2:5], 0
	s_waitcnt lgkmcnt(6)
	v_mfma_f32_16x16x32_bf16 v[34:37], v[90:93], v[6:9], v[34:37]
	s_waitcnt lgkmcnt(5)
	v_mfma_f32_16x16x32_bf16 v[34:37], v[86:89], v[10:13], v[34:37]
	s_waitcnt lgkmcnt(4)
	v_mfma_f32_16x16x32_bf16 v[34:37], v[82:85], v[14:17], v[34:37]
	s_waitcnt lgkmcnt(3)
	v_mfma_f32_16x16x32_bf16 v[38:41], v[94:97], v[18:21], 0
	s_waitcnt lgkmcnt(2)
	v_mfma_f32_16x16x32_bf16 v[38:41], v[90:93], v[22:25], v[38:41]
	s_waitcnt lgkmcnt(1)
	v_mfma_f32_16x16x32_bf16 v[38:41], v[86:89], v[26:29], v[38:41]
	s_waitcnt lgkmcnt(0)
	v_mfma_f32_16x16x32_bf16 v[38:41], v[82:85], v[30:33], v[38:41]
	s_add_u32 s6, s6, 0x8000
	s_addc_u32 s7, s7, 0
	v_lshlrev_b32_e32 v42, 16, v160
	v_and_b32_e32 v43, 0xffff0000, v160
	v_lshlrev_b32_e32 v44, 16, v161
	v_and_b32_e32 v45, 0xffff0000, v161
	v_lshlrev_b32_e32 v46, 16, v162
	v_and_b32_e32 v47, 0xffff0000, v162
	v_lshlrev_b32_e32 v48, 16, v163
	v_and_b32_e32 v49, 0xffff0000, v163
	s_nop 1
	v_fma_f32 v50, v98, v42, v34
	v_fma_f32 v51, v99, v43, v35
	v_fma_f32 v52, v100, v44, v36
	v_fma_f32 v53, v101, v45, v37
	v_fma_f32 v54, v98, v46, v38
	v_fma_f32 v55, v99, v47, v39
	v_fma_f32 v56, v100, v48, v40
	v_fma_f32 v57, v101, v49, v41
	v_mul_f32_e32 v2, 0x3d372713, v50
	v_mul_f32_e32 v3, 0x3d372713, v51
	v_mul_f32_e32 v4, 0x3d372713, v52
	v_mul_f32_e32 v5, 0x3d372713, v53
	v_mul_f32_e32 v6, 0x3d372713, v54
	v_mul_f32_e32 v7, 0x3d372713, v55
	v_mul_f32_e32 v8, 0x3d372713, v56
	v_mul_f32_e32 v9, 0x3d372713, v57
	v_mul_f32_e32 v2, v50, v2
	v_mul_f32_e32 v3, v51, v3
	v_mul_f32_e32 v4, v52, v4
	v_mul_f32_e32 v5, v53, v5
	v_mul_f32_e32 v6, v54, v6
	v_mul_f32_e32 v7, v55, v7
	v_mul_f32_e32 v8, v56, v8
	v_mul_f32_e32 v9, v57, v9
	v_fma_f32 v2, v50, v2, v50
	v_fma_f32 v3, v51, v3, v51
	v_fma_f32 v4, v52, v4, v52
	v_fma_f32 v5, v53, v5, v53
	v_fma_f32 v6, v54, v6, v54
	v_fma_f32 v7, v55, v7, v55
	v_fma_f32 v8, v56, v8, v56
	v_fma_f32 v9, v57, v9, v57
	v_mul_f32_e32 v2, 0xbfcc422a, v2
	v_mul_f32_e32 v3, 0xbfcc422a, v3
	v_mul_f32_e32 v4, 0xbfcc422a, v4
	v_mul_f32_e32 v5, 0xbfcc422a, v5
	v_mul_f32_e32 v6, 0xbfcc422a, v6
	v_mul_f32_e32 v7, 0xbfcc422a, v7
	v_mul_f32_e32 v8, 0xbfcc422a, v8
	v_mul_f32_e32 v9, 0xbfcc422a, v9
	v_mul_f32_e32 v2, 0x3fb8aa3b, v2
	v_mul_f32_e32 v3, 0x3fb8aa3b, v3
	v_mul_f32_e32 v4, 0x3fb8aa3b, v4
	v_mul_f32_e32 v5, 0x3fb8aa3b, v5
	v_mul_f32_e32 v6, 0x3fb8aa3b, v6
	v_mul_f32_e32 v7, 0x3fb8aa3b, v7
	v_mul_f32_e32 v8, 0x3fb8aa3b, v8
	v_mul_f32_e32 v9, 0x3fb8aa3b, v9
	v_exp_f32_e32 v2, v2
	v_exp_f32_e32 v3, v3
	v_exp_f32_e32 v4, v4
	v_exp_f32_e32 v5, v5
	v_exp_f32_e32 v6, v6
	v_exp_f32_e32 v7, v7
	v_exp_f32_e32 v8, v8
	v_exp_f32_e32 v9, v9
	v_add_f32_e32 v2, 1.0, v2
	v_add_f32_e32 v3, 1.0, v3
	v_add_f32_e32 v4, 1.0, v4
	v_add_f32_e32 v5, 1.0, v5
	v_add_f32_e32 v6, 1.0, v6
	v_add_f32_e32 v7, 1.0, v7
	v_add_f32_e32 v8, 1.0, v8
	v_add_f32_e32 v9, 1.0, v9
	v_rcp_f32_e32 v2, v2
	v_rcp_f32_e32 v3, v3
	v_rcp_f32_e32 v4, v4
	v_rcp_f32_e32 v5, v5
	v_rcp_f32_e32 v6, v6
	v_rcp_f32_e32 v7, v7
	v_rcp_f32_e32 v8, v8
	v_rcp_f32_e32 v9, v9
	v_mul_f32_e32 v50, v50, v2
	v_mul_f32_e32 v51, v51, v3
	v_mul_f32_e32 v52, v52, v4
	v_mul_f32_e32 v53, v53, v5
	v_mul_f32_e32 v54, v54, v6
	v_mul_f32_e32 v55, v55, v7
	v_mul_f32_e32 v56, v56, v8
	v_mul_f32_e32 v57, v57, v9
	v_cvt_pk_bf16_f32 v10, v50, v51
	v_cvt_pk_bf16_f32 v11, v52, v53
	v_cvt_pk_bf16_f32 v12, v54, v55
	v_cvt_pk_bf16_f32 v13, v56, v57
	global_store_dwordx2 v176, v[10:11], s[10:11]
	global_store_dwordx2 v177, v[12:13], s[10:11]
	s_add_u32 s10, s10, 0x8000
	s_addc_u32 s11, s11, 0
	s_nop 0
	v_mfma_f32_32x32x16_bf16 v[50:65], v[138:141], v[114:117], 0
	v_mfma_f32_32x32x16_bf16 v[2:17], v[138:141], v[110:113], 0
	v_mfma_f32_32x32x16_bf16 v[34:49], v[138:141], v[106:109], 0
	v_mfma_f32_32x32x16_bf16 v[18:33], v[138:141], v[102:105], 0
	global_load_dwordx2 v[160:161], v176, s[6:7]
	global_load_dwordx2 v[162:163], v177, s[6:7]
	s_nop 9
	v_fmac_f32_e32 v51, v78, v50
	v_fmac_f32_e32 v35, v74, v34
	v_fmac_f32_e32 v3, v80, v50
	v_fmac_f32_e32 v19, v76, v34
	v_fma_f32 v51, -v80, v2, v51
	v_fma_f32 v35, -v76, v18, v35
	v_fmac_f32_e32 v3, v78, v2
	v_fmac_f32_e32 v19, v74, v18
	v_fmac_f32_e32 v52, v78, v51
	v_fmac_f32_e32 v36, v74, v35
	v_fmac_f32_e32 v4, v80, v51
	v_fmac_f32_e32 v20, v76, v35
	v_fma_f32 v52, -v80, v3, v52
	v_fma_f32 v36, -v76, v19, v36
	v_fmac_f32_e32 v4, v78, v3
	v_fmac_f32_e32 v20, v74, v19
	v_fmac_f32_e32 v53, v78, v52
	v_fmac_f32_e32 v37, v74, v36
	v_fmac_f32_e32 v5, v80, v52
	v_fmac_f32_e32 v21, v76, v36
	v_fma_f32 v53, -v80, v4, v53
	v_fma_f32 v37, -v76, v20, v37
	v_fmac_f32_e32 v5, v78, v4
	v_fmac_f32_e32 v21, v74, v20
	v_fmac_f32_e32 v54, v78, v53
	v_fmac_f32_e32 v38, v74, v37
	v_fmac_f32_e32 v6, v80, v53
	v_fmac_f32_e32 v22, v76, v37
	v_fma_f32 v54, -v80, v5, v54
	v_fma_f32 v38, -v76, v21, v38
	v_fmac_f32_e32 v6, v78, v5
	v_fmac_f32_e32 v22, v74, v21
	v_fmac_f32_e32 v55, v78, v54
	v_fmac_f32_e32 v39, v74, v38
	v_fmac_f32_e32 v7, v80, v54
	v_fmac_f32_e32 v23, v76, v38
	v_fma_f32 v55, -v80, v6, v55
	v_fma_f32 v39, -v76, v22, v39
	v_fmac_f32_e32 v7, v78, v6
	v_fmac_f32_e32 v23, v74, v22
	v_fmac_f32_e32 v56, v78, v55
	v_fmac_f32_e32 v40, v74, v39
	v_fmac_f32_e32 v8, v80, v55
	v_fmac_f32_e32 v24, v76, v39
	v_fma_f32 v56, -v80, v7, v56
	v_fma_f32 v40, -v76, v23, v40
	v_fmac_f32_e32 v8, v78, v7
	v_fmac_f32_e32 v24, v74, v23
	v_fmac_f32_e32 v57, v78, v56
	v_fmac_f32_e32 v41, v74, v40
	v_fmac_f32_e32 v9, v80, v56
	v_fmac_f32_e32 v25, v76, v40
	v_fma_f32 v57, -v80, v8, v57
	v_fma_f32 v41, -v76, v24, v41
	v_fmac_f32_e32 v9, v78, v8
	v_fmac_f32_e32 v25, v74, v24
	v_fmac_f32_e32 v58, v78, v57
	v_fmac_f32_e32 v42, v74, v41
	v_fmac_f32_e32 v10, v80, v57
	v_fmac_f32_e32 v26, v76, v41
	v_fma_f32 v58, -v80, v9, v58
	v_fma_f32 v42, -v76, v25, v42
	v_fmac_f32_e32 v10, v78, v9
	v_fmac_f32_e32 v26, v74, v25
	v_fmac_f32_e32 v59, v78, v58
	v_fmac_f32_e32 v43, v74, v42
	v_fmac_f32_e32 v11, v80, v58
	v_fmac_f32_e32 v27, v76, v42
	v_fma_f32 v59, -v80, v10, v59
	v_fma_f32 v43, -v76, v26, v43
	v_fmac_f32_e32 v11, v78, v10
	v_fmac_f32_e32 v27, v74, v26
	v_fmac_f32_e32 v60, v78, v59
	v_fmac_f32_e32 v44, v74, v43
	v_fmac_f32_e32 v12, v80, v59
	v_fmac_f32_e32 v28, v76, v43
	v_fma_f32 v60, -v80, v11, v60
	v_fma_f32 v44, -v76, v27, v44
	v_fmac_f32_e32 v12, v78, v11
	v_fmac_f32_e32 v28, v74, v27
	v_fmac_f32_e32 v61, v78, v60
	v_fmac_f32_e32 v45, v74, v44
	v_fmac_f32_e32 v13, v80, v60
	v_fmac_f32_e32 v29, v76, v44
	v_fma_f32 v61, -v80, v12, v61
	v_fma_f32 v45, -v76, v28, v45
	v_fmac_f32_e32 v13, v78, v12
	v_fmac_f32_e32 v29, v74, v28
	v_fmac_f32_e32 v62, v78, v61
	v_fmac_f32_e32 v46, v74, v45
	v_fmac_f32_e32 v14, v80, v61
	v_fmac_f32_e32 v30, v76, v45
	v_fma_f32 v62, -v80, v13, v62
	v_fma_f32 v46, -v76, v29, v46
	v_fmac_f32_e32 v14, v78, v13
	v_fmac_f32_e32 v30, v74, v29
	v_fmac_f32_e32 v63, v78, v62
	v_fmac_f32_e32 v47, v74, v46
	v_fmac_f32_e32 v15, v80, v62
	v_fmac_f32_e32 v31, v76, v46
	v_fma_f32 v63, -v80, v14, v63
	v_fma_f32 v47, -v76, v30, v47
	v_fmac_f32_e32 v15, v78, v14
	v_fmac_f32_e32 v31, v74, v30
	v_fmac_f32_e32 v64, v78, v63
	v_fmac_f32_e32 v48, v74, v47
	v_fmac_f32_e32 v16, v80, v63
	v_fmac_f32_e32 v32, v76, v47
	v_fma_f32 v64, -v80, v15, v64
	v_fma_f32 v48, -v76, v31, v48
	v_fmac_f32_e32 v16, v78, v15
	v_fmac_f32_e32 v32, v74, v31
	v_fmac_f32_e32 v65, v78, v64
	v_fmac_f32_e32 v49, v74, v48
	v_fmac_f32_e32 v17, v80, v64
	v_fmac_f32_e32 v33, v76, v48
	v_fma_f32 v65, -v80, v16, v65
	v_fma_f32 v49, -v76, v32, v49
	v_fmac_f32_e32 v17, v78, v16
	v_fmac_f32_e32 v33, v74, v32
	v_mov_b32_e32 v156, v65
	v_mov_b32_e32 v157, v17
	v_mov_b32_e32 v158, v65
	v_mov_b32_e32 v159, v17
	s_nop 1
	v_permlane32_swap_b32_e32 v156, v158
	v_permlane32_swap_b32_e32 v157, v159
	v_pk_fma_f32 v[164:165], v[166:167], v[152:153], v[156:157] op_sel_hi:[1,0,1]
	v_pk_fma_f32 v[164:165], v[166:167], v[152:153], v[164:165] op_sel:[1,1,0] op_sel_hi:[0,1,1] neg_lo:[0,1,0]
	v_cndmask_b32_e32 v164, v166, v164, vcc
	v_cndmask_b32_e32 v165, v167, v165, vcc
	v_mov_b32_e32 v156, v49
	v_mov_b32_e32 v157, v33
	v_mov_b32_e32 v158, v49
	v_mov_b32_e32 v159, v33
	s_nop 1
	v_permlane32_swap_b32_e32 v156, v158
	v_permlane32_swap_b32_e32 v157, v159
	v_pk_fma_f32 v[170:171], v[150:151], v[154:155], v[156:157] op_sel_hi:[1,0,1]
	v_pk_fma_f32 v[170:171], v[150:151], v[154:155], v[170:171] op_sel:[1,1,0] op_sel_hi:[0,1,1] neg_lo:[0,1,0]
	v_cndmask_b32_e32 v170, v150, v170, vcc
	v_cndmask_b32_e32 v171, v151, v171, vcc
	v_pk_mul_f32 v[168:169], v[164:165], v[70:71] op_sel:[0,1] op_sel_hi:[1,1]
	v_pk_mul_f32 v[172:173], v[170:171], v[66:67] op_sel:[0,1] op_sel_hi:[1,1]
	v_pk_fma_f32 v[168:169], v[164:165], v[72:73], v[168:169] op_sel:[1,1,0] op_sel_hi:[0,1,1] neg_lo:[0,1,0]
	v_pk_fma_f32 v[172:173], v[170:171], v[68:69], v[172:173] op_sel:[1,1,0] op_sel_hi:[0,1,1] neg_lo:[0,1,0]
	v_pk_fma_f32 v[50:51], v[78:79], v[164:165], v[50:51] op_sel_hi:[1,0,1]
	v_pk_fma_f32 v[34:35], v[74:75], v[170:171], v[34:35] op_sel_hi:[1,0,1]
	v_pk_fma_f32 v[52:53], v[70:71], v[164:165], v[52:53] op_sel_hi:[1,0,1]
	v_pk_fma_f32 v[36:37], v[66:67], v[170:171], v[36:37] op_sel_hi:[1,0,1]
	v_pk_fma_f32 v[2:3], v[80:81], v[164:165], v[2:3] op_sel_hi:[1,0,1]
	v_pk_fma_f32 v[18:19], v[76:77], v[170:171], v[18:19] op_sel_hi:[1,0,1]
	v_pk_fma_f32 v[4:5], v[72:73], v[164:165], v[4:5] op_sel_hi:[1,0,1]
	v_pk_fma_f32 v[20:21], v[68:69], v[170:171], v[20:21] op_sel_hi:[1,0,1]
	v_pk_fma_f32 v[50:51], v[80:81], v[164:165], v[50:51] op_sel:[0,1,0] op_sel_hi:[1,1,1] neg_lo:[0,1,0] neg_hi:[0,1,0]
	v_pk_fma_f32 v[34:35], v[76:77], v[170:171], v[34:35] op_sel:[0,1,0] op_sel_hi:[1,1,1] neg_lo:[0,1,0] neg_hi:[0,1,0]
	v_pk_fma_f32 v[52:53], v[72:73], v[164:165], v[52:53] op_sel:[0,1,0] op_sel_hi:[1,1,1] neg_lo:[0,1,0] neg_hi:[0,1,0]
	v_pk_fma_f32 v[36:37], v[68:69], v[170:171], v[36:37] op_sel:[0,1,0] op_sel_hi:[1,1,1] neg_lo:[0,1,0] neg_hi:[0,1,0]
	v_pk_fma_f32 v[2:3], v[78:79], v[164:165], v[2:3] op_sel:[0,1,0] op_sel_hi:[1,1,1]
	v_pk_fma_f32 v[18:19], v[74:75], v[170:171], v[18:19] op_sel:[0,1,0] op_sel_hi:[1,1,1]
	v_pk_fma_f32 v[4:5], v[70:71], v[164:165], v[4:5] op_sel:[0,1,0] op_sel_hi:[1,1,1]
	v_pk_fma_f32 v[20:21], v[66:67], v[170:171], v[20:21] op_sel:[0,1,0] op_sel_hi:[1,1,1]
	v_pk_mul_f32 v[164:165], v[168:169], v[70:71] op_sel:[0,1] op_sel_hi:[1,1]
	v_pk_mul_f32 v[170:171], v[172:173], v[66:67] op_sel:[0,1] op_sel_hi:[1,1]
	v_pk_fma_f32 v[164:165], v[168:169], v[72:73], v[164:165] op_sel:[1,1,0] op_sel_hi:[0,1,1] neg_lo:[0,1,0]
	v_pk_fma_f32 v[170:171], v[172:173], v[68:69], v[170:171] op_sel:[1,1,0] op_sel_hi:[0,1,1] neg_lo:[0,1,0]
	v_pk_fma_f32 v[54:55], v[78:79], v[168:169], v[54:55] op_sel_hi:[1,0,1]
	v_pk_fma_f32 v[38:39], v[74:75], v[172:173], v[38:39] op_sel_hi:[1,0,1]
	v_pk_fma_f32 v[56:57], v[70:71], v[168:169], v[56:57] op_sel_hi:[1,0,1]
	v_pk_fma_f32 v[40:41], v[66:67], v[172:173], v[40:41] op_sel_hi:[1,0,1]
	v_pk_fma_f32 v[6:7], v[80:81], v[168:169], v[6:7] op_sel_hi:[1,0,1]
	v_pk_fma_f32 v[22:23], v[76:77], v[172:173], v[22:23] op_sel_hi:[1,0,1]
	v_pk_fma_f32 v[8:9], v[72:73], v[168:169], v[8:9] op_sel_hi:[1,0,1]
	v_pk_fma_f32 v[24:25], v[68:69], v[172:173], v[24:25] op_sel_hi:[1,0,1]
	v_pk_fma_f32 v[54:55], v[80:81], v[168:169], v[54:55] op_sel:[0,1,0] op_sel_hi:[1,1,1] neg_lo:[0,1,0] neg_hi:[0,1,0]
	v_pk_fma_f32 v[38:39], v[76:77], v[172:173], v[38:39] op_sel:[0,1,0] op_sel_hi:[1,1,1] neg_lo:[0,1,0] neg_hi:[0,1,0]
	v_pk_fma_f32 v[56:57], v[72:73], v[168:169], v[56:57] op_sel:[0,1,0] op_sel_hi:[1,1,1] neg_lo:[0,1,0] neg_hi:[0,1,0]
	v_pk_fma_f32 v[40:41], v[68:69], v[172:173], v[40:41] op_sel:[0,1,0] op_sel_hi:[1,1,1] neg_lo:[0,1,0] neg_hi:[0,1,0]
	v_pk_fma_f32 v[6:7], v[78:79], v[168:169], v[6:7] op_sel:[0,1,0] op_sel_hi:[1,1,1]
	v_pk_fma_f32 v[22:23], v[74:75], v[172:173], v[22:23] op_sel:[0,1,0] op_sel_hi:[1,1,1]
	v_pk_fma_f32 v[8:9], v[70:71], v[168:169], v[8:9] op_sel:[0,1,0] op_sel_hi:[1,1,1]
	v_pk_fma_f32 v[24:25], v[66:67], v[172:173], v[24:25] op_sel:[0,1,0] op_sel_hi:[1,1,1]
	v_pk_mul_f32 v[168:169], v[164:165], v[70:71] op_sel:[0,1] op_sel_hi:[1,1]
	v_pk_mul_f32 v[172:173], v[170:171], v[66:67] op_sel:[0,1] op_sel_hi:[1,1]
	v_pk_fma_f32 v[168:169], v[164:165], v[72:73], v[168:169] op_sel:[1,1,0] op_sel_hi:[0,1,1] neg_lo:[0,1,0]
	v_pk_fma_f32 v[172:173], v[170:171], v[68:69], v[172:173] op_sel:[1,1,0] op_sel_hi:[0,1,1] neg_lo:[0,1,0]
	v_pk_fma_f32 v[58:59], v[78:79], v[164:165], v[58:59] op_sel_hi:[1,0,1]
	v_pk_fma_f32 v[42:43], v[74:75], v[170:171], v[42:43] op_sel_hi:[1,0,1]
	v_pk_fma_f32 v[60:61], v[70:71], v[164:165], v[60:61] op_sel_hi:[1,0,1]
	v_pk_fma_f32 v[44:45], v[66:67], v[170:171], v[44:45] op_sel_hi:[1,0,1]
	v_pk_fma_f32 v[10:11], v[80:81], v[164:165], v[10:11] op_sel_hi:[1,0,1]
	v_pk_fma_f32 v[26:27], v[76:77], v[170:171], v[26:27] op_sel_hi:[1,0,1]
	v_pk_fma_f32 v[12:13], v[72:73], v[164:165], v[12:13] op_sel_hi:[1,0,1]
	v_pk_fma_f32 v[28:29], v[68:69], v[170:171], v[28:29] op_sel_hi:[1,0,1]
	v_pk_fma_f32 v[58:59], v[80:81], v[164:165], v[58:59] op_sel:[0,1,0] op_sel_hi:[1,1,1] neg_lo:[0,1,0] neg_hi:[0,1,0]
	v_pk_fma_f32 v[42:43], v[76:77], v[170:171], v[42:43] op_sel:[0,1,0] op_sel_hi:[1,1,1] neg_lo:[0,1,0] neg_hi:[0,1,0]
	v_pk_fma_f32 v[60:61], v[72:73], v[164:165], v[60:61] op_sel:[0,1,0] op_sel_hi:[1,1,1] neg_lo:[0,1,0] neg_hi:[0,1,0]
	v_pk_fma_f32 v[44:45], v[68:69], v[170:171], v[44:45] op_sel:[0,1,0] op_sel_hi:[1,1,1] neg_lo:[0,1,0] neg_hi:[0,1,0]
	v_pk_fma_f32 v[10:11], v[78:79], v[164:165], v[10:11] op_sel:[0,1,0] op_sel_hi:[1,1,1]
	v_pk_fma_f32 v[26:27], v[74:75], v[170:171], v[26:27] op_sel:[0,1,0] op_sel_hi:[1,1,1]
	v_pk_fma_f32 v[12:13], v[70:71], v[164:165], v[12:13] op_sel:[0,1,0] op_sel_hi:[1,1,1]
	v_pk_fma_f32 v[28:29], v[66:67], v[170:171], v[28:29] op_sel:[0,1,0] op_sel_hi:[1,1,1]
	v_pk_fma_f32 v[62:63], v[78:79], v[168:169], v[62:63] op_sel_hi:[1,0,1]
	v_pk_fma_f32 v[46:47], v[74:75], v[172:173], v[46:47] op_sel_hi:[1,0,1]
	v_pk_fma_f32 v[64:65], v[70:71], v[168:169], v[64:65] op_sel_hi:[1,0,1]
	v_pk_fma_f32 v[48:49], v[66:67], v[172:173], v[48:49] op_sel_hi:[1,0,1]
	v_pk_fma_f32 v[14:15], v[80:81], v[168:169], v[14:15] op_sel_hi:[1,0,1]
	v_pk_fma_f32 v[30:31], v[76:77], v[172:173], v[30:31] op_sel_hi:[1,0,1]
	v_pk_fma_f32 v[16:17], v[72:73], v[168:169], v[16:17] op_sel_hi:[1,0,1]
	v_pk_fma_f32 v[32:33], v[68:69], v[172:173], v[32:33] op_sel_hi:[1,0,1]
	v_pk_fma_f32 v[62:63], v[80:81], v[168:169], v[62:63] op_sel:[0,1,0] op_sel_hi:[1,1,1] neg_lo:[0,1,0] neg_hi:[0,1,0]
	v_pk_fma_f32 v[46:47], v[76:77], v[172:173], v[46:47] op_sel:[0,1,0] op_sel_hi:[1,1,1] neg_lo:[0,1,0] neg_hi:[0,1,0]
	v_pk_fma_f32 v[64:65], v[72:73], v[168:169], v[64:65] op_sel:[0,1,0] op_sel_hi:[1,1,1] neg_lo:[0,1,0] neg_hi:[0,1,0]
	v_pk_fma_f32 v[48:49], v[68:69], v[172:173], v[48:49] op_sel:[0,1,0] op_sel_hi:[1,1,1] neg_lo:[0,1,0] neg_hi:[0,1,0]
	v_pk_fma_f32 v[14:15], v[78:79], v[168:169], v[14:15] op_sel:[0,1,0] op_sel_hi:[1,1,1]
	v_pk_fma_f32 v[30:31], v[74:75], v[172:173], v[30:31] op_sel:[0,1,0] op_sel_hi:[1,1,1]
	v_pk_fma_f32 v[16:17], v[70:71], v[168:169], v[16:17] op_sel:[0,1,0] op_sel_hi:[1,1,1]
	v_pk_fma_f32 v[32:33], v[66:67], v[172:173], v[32:33] op_sel:[0,1,0] op_sel_hi:[1,1,1]
	v_mov_b32_e32 v156, v65
	v_mov_b32_e32 v157, v17
	v_mov_b32_e32 v166, v65
	v_mov_b32_e32 v167, v17
	s_nop 1
	v_permlane32_swap_b32_e32 v156, v166
	v_permlane32_swap_b32_e32 v157, v167
	v_mov_b32_e32 v156, v49
	v_mov_b32_e32 v157, v33
	v_mov_b32_e32 v150, v49
	v_mov_b32_e32 v151, v33
	s_nop 1
	v_permlane32_swap_b32_e32 v156, v150
	v_permlane32_swap_b32_e32 v157, v151
	v_cvt_pk_bf16_f32 v1, v50, v2
	ds_write_b32 v174, v1
	v_cvt_pk_bf16_f32 v146, v34, v18
	ds_write_b32 v174, v146 offset:128
	v_cvt_pk_bf16_f32 v178, v51, v3
	ds_write_b32 v174, v178 offset:272
	v_cvt_pk_bf16_f32 v1, v35, v19
	ds_write_b32 v174, v1 offset:400
	v_cvt_pk_bf16_f32 v146, v52, v4
	ds_write_b32 v174, v146 offset:544
	v_cvt_pk_bf16_f32 v178, v36, v20
	ds_write_b32 v174, v178 offset:672
	v_cvt_pk_bf16_f32 v1, v53, v5
	ds_write_b32 v174, v1 offset:816
	v_cvt_pk_bf16_f32 v146, v37, v21
	ds_write_b32 v174, v146 offset:944
	v_cvt_pk_bf16_f32 v178, v54, v6
	ds_write_b32 v174, v178 offset:1088
	v_cvt_pk_bf16_f32 v1, v38, v22
	ds_write_b32 v174, v1 offset:1216
	v_cvt_pk_bf16_f32 v146, v55, v7
	ds_write_b32 v174, v146 offset:1360
	v_cvt_pk_bf16_f32 v178, v39, v23
	ds_write_b32 v174, v178 offset:1488
	v_cvt_pk_bf16_f32 v1, v56, v8
	ds_write_b32 v174, v1 offset:1632
	v_cvt_pk_bf16_f32 v146, v40, v24
	ds_write_b32 v174, v146 offset:1760
	v_cvt_pk_bf16_f32 v178, v57, v9
	ds_write_b32 v174, v178 offset:1904
	v_cvt_pk_bf16_f32 v1, v41, v25
	ds_write_b32 v174, v1 offset:2032
	v_cvt_pk_bf16_f32 v146, v58, v10
	ds_write_b32 v174, v146 offset:2176
	v_cvt_pk_bf16_f32 v178, v42, v26
	ds_write_b32 v174, v178 offset:2304
	v_cvt_pk_bf16_f32 v1, v59, v11
	ds_write_b32 v174, v1 offset:2448
	v_cvt_pk_bf16_f32 v146, v43, v27
	ds_write_b32 v174, v146 offset:2576
	v_cvt_pk_bf16_f32 v178, v60, v12
	ds_write_b32 v174, v178 offset:2720
	v_cvt_pk_bf16_f32 v1, v44, v28
	ds_write_b32 v174, v1 offset:2848
	v_cvt_pk_bf16_f32 v146, v61, v13
	ds_write_b32 v174, v146 offset:2992
	v_cvt_pk_bf16_f32 v178, v45, v29
	ds_write_b32 v174, v178 offset:3120
	v_cvt_pk_bf16_f32 v1, v62, v14
	ds_write_b32 v174, v1 offset:3264
	v_cvt_pk_bf16_f32 v146, v46, v30
	ds_write_b32 v174, v146 offset:3392
	v_cvt_pk_bf16_f32 v178, v63, v15
	ds_write_b32 v174, v178 offset:3536
	v_cvt_pk_bf16_f32 v1, v47, v31
	ds_write_b32 v174, v1 offset:3664
	v_cvt_pk_bf16_f32 v146, v64, v16
	ds_write_b32 v174, v146 offset:3808
	v_cvt_pk_bf16_f32 v178, v48, v32
	ds_write_b32 v174, v178 offset:3936
	v_cvt_pk_bf16_f32 v1, v65, v17
	ds_write_b32 v174, v1 offset:4080
	v_cvt_pk_bf16_f32 v146, v49, v33
	ds_write_b32 v174, v146 offset:4208
	s_waitcnt lgkmcnt(0)
	ds_read_b128 v[2:5], v175
	ds_read_b128 v[6:9], v175 offset:64
	ds_read_b128 v[10:13], v175 offset:128
	ds_read_b128 v[14:17], v175 offset:192
	ds_read_b128 v[18:21], v175 offset:4352
	ds_read_b128 v[22:25], v175 offset:4416
	ds_read_b128 v[26:29], v175 offset:4480
	ds_read_b128 v[30:33], v175 offset:4544
	s_waitcnt vmcnt(0)
	s_waitcnt lgkmcnt(7)
	v_mfma_f32_16x16x32_bf16 v[34:37], v[94:97], v[2:5], 0
	s_waitcnt lgkmcnt(6)
	v_mfma_f32_16x16x32_bf16 v[34:37], v[90:93], v[6:9], v[34:37]
	s_waitcnt lgkmcnt(5)
	v_mfma_f32_16x16x32_bf16 v[34:37], v[86:89], v[10:13], v[34:37]
	s_waitcnt lgkmcnt(4)
	v_mfma_f32_16x16x32_bf16 v[34:37], v[82:85], v[14:17], v[34:37]
	s_waitcnt lgkmcnt(3)
	v_mfma_f32_16x16x32_bf16 v[38:41], v[94:97], v[18:21], 0
	s_waitcnt lgkmcnt(2)
	v_mfma_f32_16x16x32_bf16 v[38:41], v[90:93], v[22:25], v[38:41]
	s_waitcnt lgkmcnt(1)
	v_mfma_f32_16x16x32_bf16 v[38:41], v[86:89], v[26:29], v[38:41]
	s_waitcnt lgkmcnt(0)
	v_mfma_f32_16x16x32_bf16 v[38:41], v[82:85], v[30:33], v[38:41]
	s_add_u32 s6, s6, 0x8000
	s_addc_u32 s7, s7, 0
	v_lshlrev_b32_e32 v42, 16, v160
	v_and_b32_e32 v43, 0xffff0000, v160
	v_lshlrev_b32_e32 v44, 16, v161
	v_and_b32_e32 v45, 0xffff0000, v161
	v_lshlrev_b32_e32 v46, 16, v162
	v_and_b32_e32 v47, 0xffff0000, v162
	v_lshlrev_b32_e32 v48, 16, v163
	v_and_b32_e32 v49, 0xffff0000, v163
	s_nop 1
	v_fma_f32 v50, v98, v42, v34
	v_fma_f32 v51, v99, v43, v35
	v_fma_f32 v52, v100, v44, v36
	v_fma_f32 v53, v101, v45, v37
	v_fma_f32 v54, v98, v46, v38
	v_fma_f32 v55, v99, v47, v39
	v_fma_f32 v56, v100, v48, v40
	v_fma_f32 v57, v101, v49, v41
	v_mul_f32_e32 v2, 0x3d372713, v50
	v_mul_f32_e32 v3, 0x3d372713, v51
	v_mul_f32_e32 v4, 0x3d372713, v52
	v_mul_f32_e32 v5, 0x3d372713, v53
	v_mul_f32_e32 v6, 0x3d372713, v54
	v_mul_f32_e32 v7, 0x3d372713, v55
	v_mul_f32_e32 v8, 0x3d372713, v56
	v_mul_f32_e32 v9, 0x3d372713, v57
	v_mul_f32_e32 v2, v50, v2
	v_mul_f32_e32 v3, v51, v3
	v_mul_f32_e32 v4, v52, v4
	v_mul_f32_e32 v5, v53, v5
	v_mul_f32_e32 v6, v54, v6
	v_mul_f32_e32 v7, v55, v7
	v_mul_f32_e32 v8, v56, v8
	v_mul_f32_e32 v9, v57, v9
	v_fma_f32 v2, v50, v2, v50
	v_fma_f32 v3, v51, v3, v51
	v_fma_f32 v4, v52, v4, v52
	v_fma_f32 v5, v53, v5, v53
	v_fma_f32 v6, v54, v6, v54
	v_fma_f32 v7, v55, v7, v55
	v_fma_f32 v8, v56, v8, v56
	v_fma_f32 v9, v57, v9, v57
	v_mul_f32_e32 v2, 0xbfcc422a, v2
	v_mul_f32_e32 v3, 0xbfcc422a, v3
	v_mul_f32_e32 v4, 0xbfcc422a, v4
	v_mul_f32_e32 v5, 0xbfcc422a, v5
	v_mul_f32_e32 v6, 0xbfcc422a, v6
	v_mul_f32_e32 v7, 0xbfcc422a, v7
	v_mul_f32_e32 v8, 0xbfcc422a, v8
	v_mul_f32_e32 v9, 0xbfcc422a, v9
	v_mul_f32_e32 v2, 0x3fb8aa3b, v2
	v_mul_f32_e32 v3, 0x3fb8aa3b, v3
	v_mul_f32_e32 v4, 0x3fb8aa3b, v4
	v_mul_f32_e32 v5, 0x3fb8aa3b, v5
	v_mul_f32_e32 v6, 0x3fb8aa3b, v6
	v_mul_f32_e32 v7, 0x3fb8aa3b, v7
	v_mul_f32_e32 v8, 0x3fb8aa3b, v8
	v_mul_f32_e32 v9, 0x3fb8aa3b, v9
	v_exp_f32_e32 v2, v2
	v_exp_f32_e32 v3, v3
	v_exp_f32_e32 v4, v4
	v_exp_f32_e32 v5, v5
	v_exp_f32_e32 v6, v6
	v_exp_f32_e32 v7, v7
	v_exp_f32_e32 v8, v8
	v_exp_f32_e32 v9, v9
	v_add_f32_e32 v2, 1.0, v2
	v_add_f32_e32 v3, 1.0, v3
	v_add_f32_e32 v4, 1.0, v4
	v_add_f32_e32 v5, 1.0, v5
	v_add_f32_e32 v6, 1.0, v6
	v_add_f32_e32 v7, 1.0, v7
	v_add_f32_e32 v8, 1.0, v8
	v_add_f32_e32 v9, 1.0, v9
	v_rcp_f32_e32 v2, v2
	v_rcp_f32_e32 v3, v3
	v_rcp_f32_e32 v4, v4
	v_rcp_f32_e32 v5, v5
	v_rcp_f32_e32 v6, v6
	v_rcp_f32_e32 v7, v7
	v_rcp_f32_e32 v8, v8
	v_rcp_f32_e32 v9, v9
	v_mul_f32_e32 v50, v50, v2
	v_mul_f32_e32 v51, v51, v3
	v_mul_f32_e32 v52, v52, v4
	v_mul_f32_e32 v53, v53, v5
	v_mul_f32_e32 v54, v54, v6
	v_mul_f32_e32 v55, v55, v7
	v_mul_f32_e32 v56, v56, v8
	v_mul_f32_e32 v57, v57, v9
	v_cvt_pk_bf16_f32 v10, v50, v51
	v_cvt_pk_bf16_f32 v11, v52, v53
	v_cvt_pk_bf16_f32 v12, v54, v55
	v_cvt_pk_bf16_f32 v13, v56, v57
	global_store_dwordx2 v176, v[10:11], s[10:11]
	global_store_dwordx2 v177, v[12:13], s[10:11]
	s_add_u32 s10, s10, 0x8000
	s_addc_u32 s11, s11, 0
	s_nop 0
	v_mfma_f32_32x32x16_bf16 v[50:65], v[134:137], v[114:117], 0
	v_mfma_f32_32x32x16_bf16 v[2:17], v[134:137], v[110:113], 0
	v_mfma_f32_32x32x16_bf16 v[34:49], v[134:137], v[106:109], 0
	v_mfma_f32_32x32x16_bf16 v[18:33], v[134:137], v[102:105], 0
	global_load_dwordx2 v[160:161], v176, s[6:7]
	global_load_dwordx2 v[162:163], v177, s[6:7]
	s_nop 9
	v_fmac_f32_e32 v51, v78, v50
	v_fmac_f32_e32 v35, v74, v34
	v_fmac_f32_e32 v3, v80, v50
	v_fmac_f32_e32 v19, v76, v34
	v_fma_f32 v51, -v80, v2, v51
	v_fma_f32 v35, -v76, v18, v35
	v_fmac_f32_e32 v3, v78, v2
	v_fmac_f32_e32 v19, v74, v18
	v_fmac_f32_e32 v52, v78, v51
	v_fmac_f32_e32 v36, v74, v35
	v_fmac_f32_e32 v4, v80, v51
	v_fmac_f32_e32 v20, v76, v35
	v_fma_f32 v52, -v80, v3, v52
	v_fma_f32 v36, -v76, v19, v36
	v_fmac_f32_e32 v4, v78, v3
	v_fmac_f32_e32 v20, v74, v19
	v_fmac_f32_e32 v53, v78, v52
	v_fmac_f32_e32 v37, v74, v36
	v_fmac_f32_e32 v5, v80, v52
	v_fmac_f32_e32 v21, v76, v36
	v_fma_f32 v53, -v80, v4, v53
	v_fma_f32 v37, -v76, v20, v37
	v_fmac_f32_e32 v5, v78, v4
	v_fmac_f32_e32 v21, v74, v20
	v_fmac_f32_e32 v54, v78, v53
	v_fmac_f32_e32 v38, v74, v37
	v_fmac_f32_e32 v6, v80, v53
	v_fmac_f32_e32 v22, v76, v37
	v_fma_f32 v54, -v80, v5, v54
	v_fma_f32 v38, -v76, v21, v38
	v_fmac_f32_e32 v6, v78, v5
	v_fmac_f32_e32 v22, v74, v21
	v_fmac_f32_e32 v55, v78, v54
	v_fmac_f32_e32 v39, v74, v38
	v_fmac_f32_e32 v7, v80, v54
	v_fmac_f32_e32 v23, v76, v38
	v_fma_f32 v55, -v80, v6, v55
	v_fma_f32 v39, -v76, v22, v39
	v_fmac_f32_e32 v7, v78, v6
	v_fmac_f32_e32 v23, v74, v22
	v_fmac_f32_e32 v56, v78, v55
	v_fmac_f32_e32 v40, v74, v39
	v_fmac_f32_e32 v8, v80, v55
	v_fmac_f32_e32 v24, v76, v39
	v_fma_f32 v56, -v80, v7, v56
	v_fma_f32 v40, -v76, v23, v40
	v_fmac_f32_e32 v8, v78, v7
	v_fmac_f32_e32 v24, v74, v23
	v_fmac_f32_e32 v57, v78, v56
	v_fmac_f32_e32 v41, v74, v40
	v_fmac_f32_e32 v9, v80, v56
	v_fmac_f32_e32 v25, v76, v40
	v_fma_f32 v57, -v80, v8, v57
	v_fma_f32 v41, -v76, v24, v41
	v_fmac_f32_e32 v9, v78, v8
	v_fmac_f32_e32 v25, v74, v24
	v_fmac_f32_e32 v58, v78, v57
	v_fmac_f32_e32 v42, v74, v41
	v_fmac_f32_e32 v10, v80, v57
	v_fmac_f32_e32 v26, v76, v41
	v_fma_f32 v58, -v80, v9, v58
	v_fma_f32 v42, -v76, v25, v42
	v_fmac_f32_e32 v10, v78, v9
	v_fmac_f32_e32 v26, v74, v25
	v_fmac_f32_e32 v59, v78, v58
	v_fmac_f32_e32 v43, v74, v42
	v_fmac_f32_e32 v11, v80, v58
	v_fmac_f32_e32 v27, v76, v42
	v_fma_f32 v59, -v80, v10, v59
	v_fma_f32 v43, -v76, v26, v43
	v_fmac_f32_e32 v11, v78, v10
	v_fmac_f32_e32 v27, v74, v26
	v_fmac_f32_e32 v60, v78, v59
	v_fmac_f32_e32 v44, v74, v43
	v_fmac_f32_e32 v12, v80, v59
	v_fmac_f32_e32 v28, v76, v43
	v_fma_f32 v60, -v80, v11, v60
	v_fma_f32 v44, -v76, v27, v44
	v_fmac_f32_e32 v12, v78, v11
	v_fmac_f32_e32 v28, v74, v27
	v_fmac_f32_e32 v61, v78, v60
	v_fmac_f32_e32 v45, v74, v44
	v_fmac_f32_e32 v13, v80, v60
	v_fmac_f32_e32 v29, v76, v44
	v_fma_f32 v61, -v80, v12, v61
	v_fma_f32 v45, -v76, v28, v45
	v_fmac_f32_e32 v13, v78, v12
	v_fmac_f32_e32 v29, v74, v28
	v_fmac_f32_e32 v62, v78, v61
	v_fmac_f32_e32 v46, v74, v45
	v_fmac_f32_e32 v14, v80, v61
	v_fmac_f32_e32 v30, v76, v45
	v_fma_f32 v62, -v80, v13, v62
	v_fma_f32 v46, -v76, v29, v46
	v_fmac_f32_e32 v14, v78, v13
	v_fmac_f32_e32 v30, v74, v29
	v_fmac_f32_e32 v63, v78, v62
	v_fmac_f32_e32 v47, v74, v46
	v_fmac_f32_e32 v15, v80, v62
	v_fmac_f32_e32 v31, v76, v46
	v_fma_f32 v63, -v80, v14, v63
	v_fma_f32 v47, -v76, v30, v47
	v_fmac_f32_e32 v15, v78, v14
	v_fmac_f32_e32 v31, v74, v30
	v_fmac_f32_e32 v64, v78, v63
	v_fmac_f32_e32 v48, v74, v47
	v_fmac_f32_e32 v16, v80, v63
	v_fmac_f32_e32 v32, v76, v47
	v_fma_f32 v64, -v80, v15, v64
	v_fma_f32 v48, -v76, v31, v48
	v_fmac_f32_e32 v16, v78, v15
	v_fmac_f32_e32 v32, v74, v31
	v_fmac_f32_e32 v65, v78, v64
	v_fmac_f32_e32 v49, v74, v48
	v_fmac_f32_e32 v17, v80, v64
	v_fmac_f32_e32 v33, v76, v48
	v_fma_f32 v65, -v80, v16, v65
	v_fma_f32 v49, -v76, v32, v49
	v_fmac_f32_e32 v17, v78, v16
	v_fmac_f32_e32 v33, v74, v32
	v_mov_b32_e32 v156, v65
	v_mov_b32_e32 v157, v17
	v_mov_b32_e32 v158, v65
	v_mov_b32_e32 v159, v17
	s_nop 1
	v_permlane32_swap_b32_e32 v156, v158
	v_permlane32_swap_b32_e32 v157, v159
	v_pk_fma_f32 v[164:165], v[166:167], v[152:153], v[156:157] op_sel_hi:[1,0,1]
	v_pk_fma_f32 v[164:165], v[166:167], v[152:153], v[164:165] op_sel:[1,1,0] op_sel_hi:[0,1,1] neg_lo:[0,1,0]
	v_cndmask_b32_e32 v164, v166, v164, vcc
	v_cndmask_b32_e32 v165, v167, v165, vcc
	v_mov_b32_e32 v156, v49
	v_mov_b32_e32 v157, v33
	v_mov_b32_e32 v158, v49
	v_mov_b32_e32 v159, v33
	s_nop 1
	v_permlane32_swap_b32_e32 v156, v158
	v_permlane32_swap_b32_e32 v157, v159
	v_pk_fma_f32 v[170:171], v[150:151], v[154:155], v[156:157] op_sel_hi:[1,0,1]
	v_pk_fma_f32 v[170:171], v[150:151], v[154:155], v[170:171] op_sel:[1,1,0] op_sel_hi:[0,1,1] neg_lo:[0,1,0]
	v_cndmask_b32_e32 v170, v150, v170, vcc
	v_cndmask_b32_e32 v171, v151, v171, vcc
	v_pk_mul_f32 v[168:169], v[164:165], v[70:71] op_sel:[0,1] op_sel_hi:[1,1]
	v_pk_mul_f32 v[172:173], v[170:171], v[66:67] op_sel:[0,1] op_sel_hi:[1,1]
	v_pk_fma_f32 v[168:169], v[164:165], v[72:73], v[168:169] op_sel:[1,1,0] op_sel_hi:[0,1,1] neg_lo:[0,1,0]
	v_pk_fma_f32 v[172:173], v[170:171], v[68:69], v[172:173] op_sel:[1,1,0] op_sel_hi:[0,1,1] neg_lo:[0,1,0]
	v_pk_fma_f32 v[50:51], v[78:79], v[164:165], v[50:51] op_sel_hi:[1,0,1]
	v_pk_fma_f32 v[34:35], v[74:75], v[170:171], v[34:35] op_sel_hi:[1,0,1]
	v_pk_fma_f32 v[52:53], v[70:71], v[164:165], v[52:53] op_sel_hi:[1,0,1]
	v_pk_fma_f32 v[36:37], v[66:67], v[170:171], v[36:37] op_sel_hi:[1,0,1]
	v_pk_fma_f32 v[2:3], v[80:81], v[164:165], v[2:3] op_sel_hi:[1,0,1]
	v_pk_fma_f32 v[18:19], v[76:77], v[170:171], v[18:19] op_sel_hi:[1,0,1]
	v_pk_fma_f32 v[4:5], v[72:73], v[164:165], v[4:5] op_sel_hi:[1,0,1]
	v_pk_fma_f32 v[20:21], v[68:69], v[170:171], v[20:21] op_sel_hi:[1,0,1]
	v_pk_fma_f32 v[50:51], v[80:81], v[164:165], v[50:51] op_sel:[0,1,0] op_sel_hi:[1,1,1] neg_lo:[0,1,0] neg_hi:[0,1,0]
	v_pk_fma_f32 v[34:35], v[76:77], v[170:171], v[34:35] op_sel:[0,1,0] op_sel_hi:[1,1,1] neg_lo:[0,1,0] neg_hi:[0,1,0]
	v_pk_fma_f32 v[52:53], v[72:73], v[164:165], v[52:53] op_sel:[0,1,0] op_sel_hi:[1,1,1] neg_lo:[0,1,0] neg_hi:[0,1,0]
	v_pk_fma_f32 v[36:37], v[68:69], v[170:171], v[36:37] op_sel:[0,1,0] op_sel_hi:[1,1,1] neg_lo:[0,1,0] neg_hi:[0,1,0]
	v_pk_fma_f32 v[2:3], v[78:79], v[164:165], v[2:3] op_sel:[0,1,0] op_sel_hi:[1,1,1]
	v_pk_fma_f32 v[18:19], v[74:75], v[170:171], v[18:19] op_sel:[0,1,0] op_sel_hi:[1,1,1]
	v_pk_fma_f32 v[4:5], v[70:71], v[164:165], v[4:5] op_sel:[0,1,0] op_sel_hi:[1,1,1]
	v_pk_fma_f32 v[20:21], v[66:67], v[170:171], v[20:21] op_sel:[0,1,0] op_sel_hi:[1,1,1]
	v_pk_mul_f32 v[164:165], v[168:169], v[70:71] op_sel:[0,1] op_sel_hi:[1,1]
	v_pk_mul_f32 v[170:171], v[172:173], v[66:67] op_sel:[0,1] op_sel_hi:[1,1]
	v_pk_fma_f32 v[164:165], v[168:169], v[72:73], v[164:165] op_sel:[1,1,0] op_sel_hi:[0,1,1] neg_lo:[0,1,0]
	v_pk_fma_f32 v[170:171], v[172:173], v[68:69], v[170:171] op_sel:[1,1,0] op_sel_hi:[0,1,1] neg_lo:[0,1,0]
	v_pk_fma_f32 v[54:55], v[78:79], v[168:169], v[54:55] op_sel_hi:[1,0,1]
	v_pk_fma_f32 v[38:39], v[74:75], v[172:173], v[38:39] op_sel_hi:[1,0,1]
	v_pk_fma_f32 v[56:57], v[70:71], v[168:169], v[56:57] op_sel_hi:[1,0,1]
	v_pk_fma_f32 v[40:41], v[66:67], v[172:173], v[40:41] op_sel_hi:[1,0,1]
	v_pk_fma_f32 v[6:7], v[80:81], v[168:169], v[6:7] op_sel_hi:[1,0,1]
	v_pk_fma_f32 v[22:23], v[76:77], v[172:173], v[22:23] op_sel_hi:[1,0,1]
	v_pk_fma_f32 v[8:9], v[72:73], v[168:169], v[8:9] op_sel_hi:[1,0,1]
	v_pk_fma_f32 v[24:25], v[68:69], v[172:173], v[24:25] op_sel_hi:[1,0,1]
	v_pk_fma_f32 v[54:55], v[80:81], v[168:169], v[54:55] op_sel:[0,1,0] op_sel_hi:[1,1,1] neg_lo:[0,1,0] neg_hi:[0,1,0]
	v_pk_fma_f32 v[38:39], v[76:77], v[172:173], v[38:39] op_sel:[0,1,0] op_sel_hi:[1,1,1] neg_lo:[0,1,0] neg_hi:[0,1,0]
	v_pk_fma_f32 v[56:57], v[72:73], v[168:169], v[56:57] op_sel:[0,1,0] op_sel_hi:[1,1,1] neg_lo:[0,1,0] neg_hi:[0,1,0]
	v_pk_fma_f32 v[40:41], v[68:69], v[172:173], v[40:41] op_sel:[0,1,0] op_sel_hi:[1,1,1] neg_lo:[0,1,0] neg_hi:[0,1,0]
	v_pk_fma_f32 v[6:7], v[78:79], v[168:169], v[6:7] op_sel:[0,1,0] op_sel_hi:[1,1,1]
	v_pk_fma_f32 v[22:23], v[74:75], v[172:173], v[22:23] op_sel:[0,1,0] op_sel_hi:[1,1,1]
	v_pk_fma_f32 v[8:9], v[70:71], v[168:169], v[8:9] op_sel:[0,1,0] op_sel_hi:[1,1,1]
	v_pk_fma_f32 v[24:25], v[66:67], v[172:173], v[24:25] op_sel:[0,1,0] op_sel_hi:[1,1,1]
	v_pk_mul_f32 v[168:169], v[164:165], v[70:71] op_sel:[0,1] op_sel_hi:[1,1]
	v_pk_mul_f32 v[172:173], v[170:171], v[66:67] op_sel:[0,1] op_sel_hi:[1,1]
	v_pk_fma_f32 v[168:169], v[164:165], v[72:73], v[168:169] op_sel:[1,1,0] op_sel_hi:[0,1,1] neg_lo:[0,1,0]
	v_pk_fma_f32 v[172:173], v[170:171], v[68:69], v[172:173] op_sel:[1,1,0] op_sel_hi:[0,1,1] neg_lo:[0,1,0]
	v_pk_fma_f32 v[58:59], v[78:79], v[164:165], v[58:59] op_sel_hi:[1,0,1]
	v_pk_fma_f32 v[42:43], v[74:75], v[170:171], v[42:43] op_sel_hi:[1,0,1]
	v_pk_fma_f32 v[60:61], v[70:71], v[164:165], v[60:61] op_sel_hi:[1,0,1]
	v_pk_fma_f32 v[44:45], v[66:67], v[170:171], v[44:45] op_sel_hi:[1,0,1]
	v_pk_fma_f32 v[10:11], v[80:81], v[164:165], v[10:11] op_sel_hi:[1,0,1]
	v_pk_fma_f32 v[26:27], v[76:77], v[170:171], v[26:27] op_sel_hi:[1,0,1]
	v_pk_fma_f32 v[12:13], v[72:73], v[164:165], v[12:13] op_sel_hi:[1,0,1]
	v_pk_fma_f32 v[28:29], v[68:69], v[170:171], v[28:29] op_sel_hi:[1,0,1]
	v_pk_fma_f32 v[58:59], v[80:81], v[164:165], v[58:59] op_sel:[0,1,0] op_sel_hi:[1,1,1] neg_lo:[0,1,0] neg_hi:[0,1,0]
	v_pk_fma_f32 v[42:43], v[76:77], v[170:171], v[42:43] op_sel:[0,1,0] op_sel_hi:[1,1,1] neg_lo:[0,1,0] neg_hi:[0,1,0]
	v_pk_fma_f32 v[60:61], v[72:73], v[164:165], v[60:61] op_sel:[0,1,0] op_sel_hi:[1,1,1] neg_lo:[0,1,0] neg_hi:[0,1,0]
	v_pk_fma_f32 v[44:45], v[68:69], v[170:171], v[44:45] op_sel:[0,1,0] op_sel_hi:[1,1,1] neg_lo:[0,1,0] neg_hi:[0,1,0]
	v_pk_fma_f32 v[10:11], v[78:79], v[164:165], v[10:11] op_sel:[0,1,0] op_sel_hi:[1,1,1]
	v_pk_fma_f32 v[26:27], v[74:75], v[170:171], v[26:27] op_sel:[0,1,0] op_sel_hi:[1,1,1]
	v_pk_fma_f32 v[12:13], v[70:71], v[164:165], v[12:13] op_sel:[0,1,0] op_sel_hi:[1,1,1]
	v_pk_fma_f32 v[28:29], v[66:67], v[170:171], v[28:29] op_sel:[0,1,0] op_sel_hi:[1,1,1]
	v_pk_fma_f32 v[62:63], v[78:79], v[168:169], v[62:63] op_sel_hi:[1,0,1]
	v_pk_fma_f32 v[46:47], v[74:75], v[172:173], v[46:47] op_sel_hi:[1,0,1]
	v_pk_fma_f32 v[64:65], v[70:71], v[168:169], v[64:65] op_sel_hi:[1,0,1]
	v_pk_fma_f32 v[48:49], v[66:67], v[172:173], v[48:49] op_sel_hi:[1,0,1]
	v_pk_fma_f32 v[14:15], v[80:81], v[168:169], v[14:15] op_sel_hi:[1,0,1]
	v_pk_fma_f32 v[30:31], v[76:77], v[172:173], v[30:31] op_sel_hi:[1,0,1]
	v_pk_fma_f32 v[16:17], v[72:73], v[168:169], v[16:17] op_sel_hi:[1,0,1]
	v_pk_fma_f32 v[32:33], v[68:69], v[172:173], v[32:33] op_sel_hi:[1,0,1]
	v_pk_fma_f32 v[62:63], v[80:81], v[168:169], v[62:63] op_sel:[0,1,0] op_sel_hi:[1,1,1] neg_lo:[0,1,0] neg_hi:[0,1,0]
	v_pk_fma_f32 v[46:47], v[76:77], v[172:173], v[46:47] op_sel:[0,1,0] op_sel_hi:[1,1,1] neg_lo:[0,1,0] neg_hi:[0,1,0]
	v_pk_fma_f32 v[64:65], v[72:73], v[168:169], v[64:65] op_sel:[0,1,0] op_sel_hi:[1,1,1] neg_lo:[0,1,0] neg_hi:[0,1,0]
	v_pk_fma_f32 v[48:49], v[68:69], v[172:173], v[48:49] op_sel:[0,1,0] op_sel_hi:[1,1,1] neg_lo:[0,1,0] neg_hi:[0,1,0]
	v_pk_fma_f32 v[14:15], v[78:79], v[168:169], v[14:15] op_sel:[0,1,0] op_sel_hi:[1,1,1]
	v_pk_fma_f32 v[30:31], v[74:75], v[172:173], v[30:31] op_sel:[0,1,0] op_sel_hi:[1,1,1]
	v_pk_fma_f32 v[16:17], v[70:71], v[168:169], v[16:17] op_sel:[0,1,0] op_sel_hi:[1,1,1]
	v_pk_fma_f32 v[32:33], v[66:67], v[172:173], v[32:33] op_sel:[0,1,0] op_sel_hi:[1,1,1]
	v_mov_b32_e32 v156, v65
	v_mov_b32_e32 v157, v17
	v_mov_b32_e32 v166, v65
	v_mov_b32_e32 v167, v17
	s_nop 1
	v_permlane32_swap_b32_e32 v156, v166
	v_permlane32_swap_b32_e32 v157, v167
	v_mov_b32_e32 v156, v49
	v_mov_b32_e32 v157, v33
	v_mov_b32_e32 v150, v49
	v_mov_b32_e32 v151, v33
	s_nop 1
	v_permlane32_swap_b32_e32 v156, v150
	v_permlane32_swap_b32_e32 v157, v151
	v_cvt_pk_bf16_f32 v1, v50, v2
	ds_write_b32 v174, v1
	v_cvt_pk_bf16_f32 v146, v34, v18
	ds_write_b32 v174, v146 offset:128
	v_cvt_pk_bf16_f32 v178, v51, v3
	ds_write_b32 v174, v178 offset:272
	v_cvt_pk_bf16_f32 v1, v35, v19
	ds_write_b32 v174, v1 offset:400
	v_cvt_pk_bf16_f32 v146, v52, v4
	ds_write_b32 v174, v146 offset:544
	v_cvt_pk_bf16_f32 v178, v36, v20
	ds_write_b32 v174, v178 offset:672
	v_cvt_pk_bf16_f32 v1, v53, v5
	ds_write_b32 v174, v1 offset:816
	v_cvt_pk_bf16_f32 v146, v37, v21
	ds_write_b32 v174, v146 offset:944
	v_cvt_pk_bf16_f32 v178, v54, v6
	ds_write_b32 v174, v178 offset:1088
	v_cvt_pk_bf16_f32 v1, v38, v22
	ds_write_b32 v174, v1 offset:1216
	v_cvt_pk_bf16_f32 v146, v55, v7
	ds_write_b32 v174, v146 offset:1360
	v_cvt_pk_bf16_f32 v178, v39, v23
	ds_write_b32 v174, v178 offset:1488
	v_cvt_pk_bf16_f32 v1, v56, v8
	ds_write_b32 v174, v1 offset:1632
	v_cvt_pk_bf16_f32 v146, v40, v24
	ds_write_b32 v174, v146 offset:1760
	v_cvt_pk_bf16_f32 v178, v57, v9
	ds_write_b32 v174, v178 offset:1904
	v_cvt_pk_bf16_f32 v1, v41, v25
	ds_write_b32 v174, v1 offset:2032
	v_cvt_pk_bf16_f32 v146, v58, v10
	ds_write_b32 v174, v146 offset:2176
	v_cvt_pk_bf16_f32 v178, v42, v26
	ds_write_b32 v174, v178 offset:2304
	v_cvt_pk_bf16_f32 v1, v59, v11
	ds_write_b32 v174, v1 offset:2448
	v_cvt_pk_bf16_f32 v146, v43, v27
	ds_write_b32 v174, v146 offset:2576
	v_cvt_pk_bf16_f32 v178, v60, v12
	ds_write_b32 v174, v178 offset:2720
	v_cvt_pk_bf16_f32 v1, v44, v28
	ds_write_b32 v174, v1 offset:2848
	v_cvt_pk_bf16_f32 v146, v61, v13
	ds_write_b32 v174, v146 offset:2992
	v_cvt_pk_bf16_f32 v178, v45, v29
	ds_write_b32 v174, v178 offset:3120
	v_cvt_pk_bf16_f32 v1, v62, v14
	ds_write_b32 v174, v1 offset:3264
	v_cvt_pk_bf16_f32 v146, v46, v30
	ds_write_b32 v174, v146 offset:3392
	v_cvt_pk_bf16_f32 v178, v63, v15
	ds_write_b32 v174, v178 offset:3536
	v_cvt_pk_bf16_f32 v1, v47, v31
	ds_write_b32 v174, v1 offset:3664
	v_cvt_pk_bf16_f32 v146, v64, v16
	ds_write_b32 v174, v146 offset:3808
	v_cvt_pk_bf16_f32 v178, v48, v32
	ds_write_b32 v174, v178 offset:3936
	v_cvt_pk_bf16_f32 v1, v65, v17
	ds_write_b32 v174, v1 offset:4080
	v_cvt_pk_bf16_f32 v146, v49, v33
	ds_write_b32 v174, v146 offset:4208
	s_waitcnt lgkmcnt(0)
	ds_read_b128 v[2:5], v175
	ds_read_b128 v[6:9], v175 offset:64
	ds_read_b128 v[10:13], v175 offset:128
	ds_read_b128 v[14:17], v175 offset:192
	ds_read_b128 v[18:21], v175 offset:4352
	ds_read_b128 v[22:25], v175 offset:4416
	ds_read_b128 v[26:29], v175 offset:4480
	ds_read_b128 v[30:33], v175 offset:4544
	s_waitcnt vmcnt(0)
	s_waitcnt lgkmcnt(7)
	v_mfma_f32_16x16x32_bf16 v[34:37], v[94:97], v[2:5], 0
	s_waitcnt lgkmcnt(6)
	v_mfma_f32_16x16x32_bf16 v[34:37], v[90:93], v[6:9], v[34:37]
	s_waitcnt lgkmcnt(5)
	v_mfma_f32_16x16x32_bf16 v[34:37], v[86:89], v[10:13], v[34:37]
	s_waitcnt lgkmcnt(4)
	v_mfma_f32_16x16x32_bf16 v[34:37], v[82:85], v[14:17], v[34:37]
	s_waitcnt lgkmcnt(3)
	v_mfma_f32_16x16x32_bf16 v[38:41], v[94:97], v[18:21], 0
	s_waitcnt lgkmcnt(2)
	v_mfma_f32_16x16x32_bf16 v[38:41], v[90:93], v[22:25], v[38:41]
	s_waitcnt lgkmcnt(1)
	v_mfma_f32_16x16x32_bf16 v[38:41], v[86:89], v[26:29], v[38:41]
	s_waitcnt lgkmcnt(0)
	v_mfma_f32_16x16x32_bf16 v[38:41], v[82:85], v[30:33], v[38:41]
	s_add_u32 s6, s6, 0x8000
	s_addc_u32 s7, s7, 0
	v_lshlrev_b32_e32 v42, 16, v160
	v_and_b32_e32 v43, 0xffff0000, v160
	v_lshlrev_b32_e32 v44, 16, v161
	v_and_b32_e32 v45, 0xffff0000, v161
	v_lshlrev_b32_e32 v46, 16, v162
	v_and_b32_e32 v47, 0xffff0000, v162
	v_lshlrev_b32_e32 v48, 16, v163
	v_and_b32_e32 v49, 0xffff0000, v163
	s_nop 1
	v_fma_f32 v50, v98, v42, v34
	v_fma_f32 v51, v99, v43, v35
	v_fma_f32 v52, v100, v44, v36
	v_fma_f32 v53, v101, v45, v37
	v_fma_f32 v54, v98, v46, v38
	v_fma_f32 v55, v99, v47, v39
	v_fma_f32 v56, v100, v48, v40
	v_fma_f32 v57, v101, v49, v41
	v_mul_f32_e32 v2, 0x3d372713, v50
	v_mul_f32_e32 v3, 0x3d372713, v51
	v_mul_f32_e32 v4, 0x3d372713, v52
	v_mul_f32_e32 v5, 0x3d372713, v53
	v_mul_f32_e32 v6, 0x3d372713, v54
	v_mul_f32_e32 v7, 0x3d372713, v55
	v_mul_f32_e32 v8, 0x3d372713, v56
	v_mul_f32_e32 v9, 0x3d372713, v57
	v_mul_f32_e32 v2, v50, v2
	v_mul_f32_e32 v3, v51, v3
	v_mul_f32_e32 v4, v52, v4
	v_mul_f32_e32 v5, v53, v5
	v_mul_f32_e32 v6, v54, v6
	v_mul_f32_e32 v7, v55, v7
	v_mul_f32_e32 v8, v56, v8
	v_mul_f32_e32 v9, v57, v9
	v_fma_f32 v2, v50, v2, v50
	v_fma_f32 v3, v51, v3, v51
	v_fma_f32 v4, v52, v4, v52
	v_fma_f32 v5, v53, v5, v53
	v_fma_f32 v6, v54, v6, v54
	v_fma_f32 v7, v55, v7, v55
	v_fma_f32 v8, v56, v8, v56
	v_fma_f32 v9, v57, v9, v57
	v_mul_f32_e32 v2, 0xbfcc422a, v2
	v_mul_f32_e32 v3, 0xbfcc422a, v3
	v_mul_f32_e32 v4, 0xbfcc422a, v4
	v_mul_f32_e32 v5, 0xbfcc422a, v5
	v_mul_f32_e32 v6, 0xbfcc422a, v6
	v_mul_f32_e32 v7, 0xbfcc422a, v7
	v_mul_f32_e32 v8, 0xbfcc422a, v8
	v_mul_f32_e32 v9, 0xbfcc422a, v9
	v_mul_f32_e32 v2, 0x3fb8aa3b, v2
	v_mul_f32_e32 v3, 0x3fb8aa3b, v3
	v_mul_f32_e32 v4, 0x3fb8aa3b, v4
	v_mul_f32_e32 v5, 0x3fb8aa3b, v5
	v_mul_f32_e32 v6, 0x3fb8aa3b, v6
	v_mul_f32_e32 v7, 0x3fb8aa3b, v7
	v_mul_f32_e32 v8, 0x3fb8aa3b, v8
	v_mul_f32_e32 v9, 0x3fb8aa3b, v9
	v_exp_f32_e32 v2, v2
	v_exp_f32_e32 v3, v3
	v_exp_f32_e32 v4, v4
	v_exp_f32_e32 v5, v5
	v_exp_f32_e32 v6, v6
	v_exp_f32_e32 v7, v7
	v_exp_f32_e32 v8, v8
	v_exp_f32_e32 v9, v9
	v_add_f32_e32 v2, 1.0, v2
	v_add_f32_e32 v3, 1.0, v3
	v_add_f32_e32 v4, 1.0, v4
	v_add_f32_e32 v5, 1.0, v5
	v_add_f32_e32 v6, 1.0, v6
	v_add_f32_e32 v7, 1.0, v7
	v_add_f32_e32 v8, 1.0, v8
	v_add_f32_e32 v9, 1.0, v9
	v_rcp_f32_e32 v2, v2
	v_rcp_f32_e32 v3, v3
	v_rcp_f32_e32 v4, v4
	v_rcp_f32_e32 v5, v5
	v_rcp_f32_e32 v6, v6
	v_rcp_f32_e32 v7, v7
	v_rcp_f32_e32 v8, v8
	v_rcp_f32_e32 v9, v9
	v_mul_f32_e32 v50, v50, v2
	v_mul_f32_e32 v51, v51, v3
	v_mul_f32_e32 v52, v52, v4
	v_mul_f32_e32 v53, v53, v5
	v_mul_f32_e32 v54, v54, v6
	v_mul_f32_e32 v55, v55, v7
	v_mul_f32_e32 v56, v56, v8
	v_mul_f32_e32 v57, v57, v9
	v_cvt_pk_bf16_f32 v10, v50, v51
	v_cvt_pk_bf16_f32 v11, v52, v53
	v_cvt_pk_bf16_f32 v12, v54, v55
	v_cvt_pk_bf16_f32 v13, v56, v57
	global_store_dwordx2 v176, v[10:11], s[10:11]
	global_store_dwordx2 v177, v[12:13], s[10:11]
	s_add_u32 s10, s10, 0x8000
	s_addc_u32 s11, s11, 0
	s_nop 0
	v_mfma_f32_32x32x16_bf16 v[50:65], v[130:133], v[114:117], 0
	v_mfma_f32_32x32x16_bf16 v[2:17], v[130:133], v[110:113], 0
	v_mfma_f32_32x32x16_bf16 v[34:49], v[130:133], v[106:109], 0
	v_mfma_f32_32x32x16_bf16 v[18:33], v[130:133], v[102:105], 0
	global_load_dwordx2 v[160:161], v176, s[6:7]
	global_load_dwordx2 v[162:163], v177, s[6:7]
	s_nop 9
	v_fmac_f32_e32 v51, v78, v50
	v_fmac_f32_e32 v35, v74, v34
	v_fmac_f32_e32 v3, v80, v50
	v_fmac_f32_e32 v19, v76, v34
	v_fma_f32 v51, -v80, v2, v51
	v_fma_f32 v35, -v76, v18, v35
	v_fmac_f32_e32 v3, v78, v2
	v_fmac_f32_e32 v19, v74, v18
	v_fmac_f32_e32 v52, v78, v51
	v_fmac_f32_e32 v36, v74, v35
	v_fmac_f32_e32 v4, v80, v51
	v_fmac_f32_e32 v20, v76, v35
	v_fma_f32 v52, -v80, v3, v52
	v_fma_f32 v36, -v76, v19, v36
	v_fmac_f32_e32 v4, v78, v3
	v_fmac_f32_e32 v20, v74, v19
	v_fmac_f32_e32 v53, v78, v52
	v_fmac_f32_e32 v37, v74, v36
	v_fmac_f32_e32 v5, v80, v52
	v_fmac_f32_e32 v21, v76, v36
	v_fma_f32 v53, -v80, v4, v53
	v_fma_f32 v37, -v76, v20, v37
	v_fmac_f32_e32 v5, v78, v4
	v_fmac_f32_e32 v21, v74, v20
	v_fmac_f32_e32 v54, v78, v53
	v_fmac_f32_e32 v38, v74, v37
	v_fmac_f32_e32 v6, v80, v53
	v_fmac_f32_e32 v22, v76, v37
	v_fma_f32 v54, -v80, v5, v54
	v_fma_f32 v38, -v76, v21, v38
	v_fmac_f32_e32 v6, v78, v5
	v_fmac_f32_e32 v22, v74, v21
	v_fmac_f32_e32 v55, v78, v54
	v_fmac_f32_e32 v39, v74, v38
	v_fmac_f32_e32 v7, v80, v54
	v_fmac_f32_e32 v23, v76, v38
	v_fma_f32 v55, -v80, v6, v55
	v_fma_f32 v39, -v76, v22, v39
	v_fmac_f32_e32 v7, v78, v6
	v_fmac_f32_e32 v23, v74, v22
	v_fmac_f32_e32 v56, v78, v55
	v_fmac_f32_e32 v40, v74, v39
	v_fmac_f32_e32 v8, v80, v55
	v_fmac_f32_e32 v24, v76, v39
	v_fma_f32 v56, -v80, v7, v56
	v_fma_f32 v40, -v76, v23, v40
	v_fmac_f32_e32 v8, v78, v7
	v_fmac_f32_e32 v24, v74, v23
	v_fmac_f32_e32 v57, v78, v56
	v_fmac_f32_e32 v41, v74, v40
	v_fmac_f32_e32 v9, v80, v56
	v_fmac_f32_e32 v25, v76, v40
	v_fma_f32 v57, -v80, v8, v57
	v_fma_f32 v41, -v76, v24, v41
	v_fmac_f32_e32 v9, v78, v8
	v_fmac_f32_e32 v25, v74, v24
	v_fmac_f32_e32 v58, v78, v57
	v_fmac_f32_e32 v42, v74, v41
	v_fmac_f32_e32 v10, v80, v57
	v_fmac_f32_e32 v26, v76, v41
	v_fma_f32 v58, -v80, v9, v58
	v_fma_f32 v42, -v76, v25, v42
	v_fmac_f32_e32 v10, v78, v9
	v_fmac_f32_e32 v26, v74, v25
	v_fmac_f32_e32 v59, v78, v58
	v_fmac_f32_e32 v43, v74, v42
	v_fmac_f32_e32 v11, v80, v58
	v_fmac_f32_e32 v27, v76, v42
	v_fma_f32 v59, -v80, v10, v59
	v_fma_f32 v43, -v76, v26, v43
	v_fmac_f32_e32 v11, v78, v10
	v_fmac_f32_e32 v27, v74, v26
	v_fmac_f32_e32 v60, v78, v59
	v_fmac_f32_e32 v44, v74, v43
	v_fmac_f32_e32 v12, v80, v59
	v_fmac_f32_e32 v28, v76, v43
	v_fma_f32 v60, -v80, v11, v60
	v_fma_f32 v44, -v76, v27, v44
	v_fmac_f32_e32 v12, v78, v11
	v_fmac_f32_e32 v28, v74, v27
	v_fmac_f32_e32 v61, v78, v60
	v_fmac_f32_e32 v45, v74, v44
	v_fmac_f32_e32 v13, v80, v60
	v_fmac_f32_e32 v29, v76, v44
	v_fma_f32 v61, -v80, v12, v61
	v_fma_f32 v45, -v76, v28, v45
	v_fmac_f32_e32 v13, v78, v12
	v_fmac_f32_e32 v29, v74, v28
	v_fmac_f32_e32 v62, v78, v61
	v_fmac_f32_e32 v46, v74, v45
	v_fmac_f32_e32 v14, v80, v61
	v_fmac_f32_e32 v30, v76, v45
	v_fma_f32 v62, -v80, v13, v62
	v_fma_f32 v46, -v76, v29, v46
	v_fmac_f32_e32 v14, v78, v13
	v_fmac_f32_e32 v30, v74, v29
	v_fmac_f32_e32 v63, v78, v62
	v_fmac_f32_e32 v47, v74, v46
	v_fmac_f32_e32 v15, v80, v62
	v_fmac_f32_e32 v31, v76, v46
	v_fma_f32 v63, -v80, v14, v63
	v_fma_f32 v47, -v76, v30, v47
	v_fmac_f32_e32 v15, v78, v14
	v_fmac_f32_e32 v31, v74, v30
	v_fmac_f32_e32 v64, v78, v63
	v_fmac_f32_e32 v48, v74, v47
	v_fmac_f32_e32 v16, v80, v63
	v_fmac_f32_e32 v32, v76, v47
	v_fma_f32 v64, -v80, v15, v64
	v_fma_f32 v48, -v76, v31, v48
	v_fmac_f32_e32 v16, v78, v15
	v_fmac_f32_e32 v32, v74, v31
	v_fmac_f32_e32 v65, v78, v64
	v_fmac_f32_e32 v49, v74, v48
	v_fmac_f32_e32 v17, v80, v64
	v_fmac_f32_e32 v33, v76, v48
	v_fma_f32 v65, -v80, v16, v65
	v_fma_f32 v49, -v76, v32, v49
	v_fmac_f32_e32 v17, v78, v16
	v_fmac_f32_e32 v33, v74, v32
	v_mov_b32_e32 v156, v65
	v_mov_b32_e32 v157, v17
	v_mov_b32_e32 v158, v65
	v_mov_b32_e32 v159, v17
	s_nop 1
	v_permlane32_swap_b32_e32 v156, v158
	v_permlane32_swap_b32_e32 v157, v159
	v_pk_fma_f32 v[164:165], v[166:167], v[152:153], v[156:157] op_sel_hi:[1,0,1]
	v_pk_fma_f32 v[164:165], v[166:167], v[152:153], v[164:165] op_sel:[1,1,0] op_sel_hi:[0,1,1] neg_lo:[0,1,0]
	v_cndmask_b32_e32 v164, v166, v164, vcc
	v_cndmask_b32_e32 v165, v167, v165, vcc
	v_mov_b32_e32 v156, v49
	v_mov_b32_e32 v157, v33
	v_mov_b32_e32 v158, v49
	v_mov_b32_e32 v159, v33
	s_nop 1
	v_permlane32_swap_b32_e32 v156, v158
	v_permlane32_swap_b32_e32 v157, v159
	v_pk_fma_f32 v[170:171], v[150:151], v[154:155], v[156:157] op_sel_hi:[1,0,1]
	v_pk_fma_f32 v[170:171], v[150:151], v[154:155], v[170:171] op_sel:[1,1,0] op_sel_hi:[0,1,1] neg_lo:[0,1,0]
	v_cndmask_b32_e32 v170, v150, v170, vcc
	v_cndmask_b32_e32 v171, v151, v171, vcc
	v_pk_mul_f32 v[168:169], v[164:165], v[70:71] op_sel:[0,1] op_sel_hi:[1,1]
	v_pk_mul_f32 v[172:173], v[170:171], v[66:67] op_sel:[0,1] op_sel_hi:[1,1]
	v_pk_fma_f32 v[168:169], v[164:165], v[72:73], v[168:169] op_sel:[1,1,0] op_sel_hi:[0,1,1] neg_lo:[0,1,0]
	v_pk_fma_f32 v[172:173], v[170:171], v[68:69], v[172:173] op_sel:[1,1,0] op_sel_hi:[0,1,1] neg_lo:[0,1,0]
	v_pk_fma_f32 v[50:51], v[78:79], v[164:165], v[50:51] op_sel_hi:[1,0,1]
	v_pk_fma_f32 v[34:35], v[74:75], v[170:171], v[34:35] op_sel_hi:[1,0,1]
	v_pk_fma_f32 v[52:53], v[70:71], v[164:165], v[52:53] op_sel_hi:[1,0,1]
	v_pk_fma_f32 v[36:37], v[66:67], v[170:171], v[36:37] op_sel_hi:[1,0,1]
	v_pk_fma_f32 v[2:3], v[80:81], v[164:165], v[2:3] op_sel_hi:[1,0,1]
	v_pk_fma_f32 v[18:19], v[76:77], v[170:171], v[18:19] op_sel_hi:[1,0,1]
	v_pk_fma_f32 v[4:5], v[72:73], v[164:165], v[4:5] op_sel_hi:[1,0,1]
	v_pk_fma_f32 v[20:21], v[68:69], v[170:171], v[20:21] op_sel_hi:[1,0,1]
	v_pk_fma_f32 v[50:51], v[80:81], v[164:165], v[50:51] op_sel:[0,1,0] op_sel_hi:[1,1,1] neg_lo:[0,1,0] neg_hi:[0,1,0]
	v_pk_fma_f32 v[34:35], v[76:77], v[170:171], v[34:35] op_sel:[0,1,0] op_sel_hi:[1,1,1] neg_lo:[0,1,0] neg_hi:[0,1,0]
	v_pk_fma_f32 v[52:53], v[72:73], v[164:165], v[52:53] op_sel:[0,1,0] op_sel_hi:[1,1,1] neg_lo:[0,1,0] neg_hi:[0,1,0]
	v_pk_fma_f32 v[36:37], v[68:69], v[170:171], v[36:37] op_sel:[0,1,0] op_sel_hi:[1,1,1] neg_lo:[0,1,0] neg_hi:[0,1,0]
	v_pk_fma_f32 v[2:3], v[78:79], v[164:165], v[2:3] op_sel:[0,1,0] op_sel_hi:[1,1,1]
	v_pk_fma_f32 v[18:19], v[74:75], v[170:171], v[18:19] op_sel:[0,1,0] op_sel_hi:[1,1,1]
	v_pk_fma_f32 v[4:5], v[70:71], v[164:165], v[4:5] op_sel:[0,1,0] op_sel_hi:[1,1,1]
	v_pk_fma_f32 v[20:21], v[66:67], v[170:171], v[20:21] op_sel:[0,1,0] op_sel_hi:[1,1,1]
	v_pk_mul_f32 v[164:165], v[168:169], v[70:71] op_sel:[0,1] op_sel_hi:[1,1]
	v_pk_mul_f32 v[170:171], v[172:173], v[66:67] op_sel:[0,1] op_sel_hi:[1,1]
	v_pk_fma_f32 v[164:165], v[168:169], v[72:73], v[164:165] op_sel:[1,1,0] op_sel_hi:[0,1,1] neg_lo:[0,1,0]
	v_pk_fma_f32 v[170:171], v[172:173], v[68:69], v[170:171] op_sel:[1,1,0] op_sel_hi:[0,1,1] neg_lo:[0,1,0]
	v_pk_fma_f32 v[54:55], v[78:79], v[168:169], v[54:55] op_sel_hi:[1,0,1]
	v_pk_fma_f32 v[38:39], v[74:75], v[172:173], v[38:39] op_sel_hi:[1,0,1]
	v_pk_fma_f32 v[56:57], v[70:71], v[168:169], v[56:57] op_sel_hi:[1,0,1]
	v_pk_fma_f32 v[40:41], v[66:67], v[172:173], v[40:41] op_sel_hi:[1,0,1]
	v_pk_fma_f32 v[6:7], v[80:81], v[168:169], v[6:7] op_sel_hi:[1,0,1]
	v_pk_fma_f32 v[22:23], v[76:77], v[172:173], v[22:23] op_sel_hi:[1,0,1]
	v_pk_fma_f32 v[8:9], v[72:73], v[168:169], v[8:9] op_sel_hi:[1,0,1]
	v_pk_fma_f32 v[24:25], v[68:69], v[172:173], v[24:25] op_sel_hi:[1,0,1]
	v_pk_fma_f32 v[54:55], v[80:81], v[168:169], v[54:55] op_sel:[0,1,0] op_sel_hi:[1,1,1] neg_lo:[0,1,0] neg_hi:[0,1,0]
	v_pk_fma_f32 v[38:39], v[76:77], v[172:173], v[38:39] op_sel:[0,1,0] op_sel_hi:[1,1,1] neg_lo:[0,1,0] neg_hi:[0,1,0]
	v_pk_fma_f32 v[56:57], v[72:73], v[168:169], v[56:57] op_sel:[0,1,0] op_sel_hi:[1,1,1] neg_lo:[0,1,0] neg_hi:[0,1,0]
	v_pk_fma_f32 v[40:41], v[68:69], v[172:173], v[40:41] op_sel:[0,1,0] op_sel_hi:[1,1,1] neg_lo:[0,1,0] neg_hi:[0,1,0]
	v_pk_fma_f32 v[6:7], v[78:79], v[168:169], v[6:7] op_sel:[0,1,0] op_sel_hi:[1,1,1]
	v_pk_fma_f32 v[22:23], v[74:75], v[172:173], v[22:23] op_sel:[0,1,0] op_sel_hi:[1,1,1]
	v_pk_fma_f32 v[8:9], v[70:71], v[168:169], v[8:9] op_sel:[0,1,0] op_sel_hi:[1,1,1]
	v_pk_fma_f32 v[24:25], v[66:67], v[172:173], v[24:25] op_sel:[0,1,0] op_sel_hi:[1,1,1]
	v_pk_mul_f32 v[168:169], v[164:165], v[70:71] op_sel:[0,1] op_sel_hi:[1,1]
	v_pk_mul_f32 v[172:173], v[170:171], v[66:67] op_sel:[0,1] op_sel_hi:[1,1]
	v_pk_fma_f32 v[168:169], v[164:165], v[72:73], v[168:169] op_sel:[1,1,0] op_sel_hi:[0,1,1] neg_lo:[0,1,0]
	v_pk_fma_f32 v[172:173], v[170:171], v[68:69], v[172:173] op_sel:[1,1,0] op_sel_hi:[0,1,1] neg_lo:[0,1,0]
	v_pk_fma_f32 v[58:59], v[78:79], v[164:165], v[58:59] op_sel_hi:[1,0,1]
	v_pk_fma_f32 v[42:43], v[74:75], v[170:171], v[42:43] op_sel_hi:[1,0,1]
	v_pk_fma_f32 v[60:61], v[70:71], v[164:165], v[60:61] op_sel_hi:[1,0,1]
	v_pk_fma_f32 v[44:45], v[66:67], v[170:171], v[44:45] op_sel_hi:[1,0,1]
	v_pk_fma_f32 v[10:11], v[80:81], v[164:165], v[10:11] op_sel_hi:[1,0,1]
	v_pk_fma_f32 v[26:27], v[76:77], v[170:171], v[26:27] op_sel_hi:[1,0,1]
	v_pk_fma_f32 v[12:13], v[72:73], v[164:165], v[12:13] op_sel_hi:[1,0,1]
	v_pk_fma_f32 v[28:29], v[68:69], v[170:171], v[28:29] op_sel_hi:[1,0,1]
	v_pk_fma_f32 v[58:59], v[80:81], v[164:165], v[58:59] op_sel:[0,1,0] op_sel_hi:[1,1,1] neg_lo:[0,1,0] neg_hi:[0,1,0]
	v_pk_fma_f32 v[42:43], v[76:77], v[170:171], v[42:43] op_sel:[0,1,0] op_sel_hi:[1,1,1] neg_lo:[0,1,0] neg_hi:[0,1,0]
	v_pk_fma_f32 v[60:61], v[72:73], v[164:165], v[60:61] op_sel:[0,1,0] op_sel_hi:[1,1,1] neg_lo:[0,1,0] neg_hi:[0,1,0]
	v_pk_fma_f32 v[44:45], v[68:69], v[170:171], v[44:45] op_sel:[0,1,0] op_sel_hi:[1,1,1] neg_lo:[0,1,0] neg_hi:[0,1,0]
	v_pk_fma_f32 v[10:11], v[78:79], v[164:165], v[10:11] op_sel:[0,1,0] op_sel_hi:[1,1,1]
	v_pk_fma_f32 v[26:27], v[74:75], v[170:171], v[26:27] op_sel:[0,1,0] op_sel_hi:[1,1,1]
	v_pk_fma_f32 v[12:13], v[70:71], v[164:165], v[12:13] op_sel:[0,1,0] op_sel_hi:[1,1,1]
	v_pk_fma_f32 v[28:29], v[66:67], v[170:171], v[28:29] op_sel:[0,1,0] op_sel_hi:[1,1,1]
	v_pk_fma_f32 v[62:63], v[78:79], v[168:169], v[62:63] op_sel_hi:[1,0,1]
	v_pk_fma_f32 v[46:47], v[74:75], v[172:173], v[46:47] op_sel_hi:[1,0,1]
	v_pk_fma_f32 v[64:65], v[70:71], v[168:169], v[64:65] op_sel_hi:[1,0,1]
	v_pk_fma_f32 v[48:49], v[66:67], v[172:173], v[48:49] op_sel_hi:[1,0,1]
	v_pk_fma_f32 v[14:15], v[80:81], v[168:169], v[14:15] op_sel_hi:[1,0,1]
	v_pk_fma_f32 v[30:31], v[76:77], v[172:173], v[30:31] op_sel_hi:[1,0,1]
	v_pk_fma_f32 v[16:17], v[72:73], v[168:169], v[16:17] op_sel_hi:[1,0,1]
	v_pk_fma_f32 v[32:33], v[68:69], v[172:173], v[32:33] op_sel_hi:[1,0,1]
	v_pk_fma_f32 v[62:63], v[80:81], v[168:169], v[62:63] op_sel:[0,1,0] op_sel_hi:[1,1,1] neg_lo:[0,1,0] neg_hi:[0,1,0]
	v_pk_fma_f32 v[46:47], v[76:77], v[172:173], v[46:47] op_sel:[0,1,0] op_sel_hi:[1,1,1] neg_lo:[0,1,0] neg_hi:[0,1,0]
	v_pk_fma_f32 v[64:65], v[72:73], v[168:169], v[64:65] op_sel:[0,1,0] op_sel_hi:[1,1,1] neg_lo:[0,1,0] neg_hi:[0,1,0]
	v_pk_fma_f32 v[48:49], v[68:69], v[172:173], v[48:49] op_sel:[0,1,0] op_sel_hi:[1,1,1] neg_lo:[0,1,0] neg_hi:[0,1,0]
	v_pk_fma_f32 v[14:15], v[78:79], v[168:169], v[14:15] op_sel:[0,1,0] op_sel_hi:[1,1,1]
	v_pk_fma_f32 v[30:31], v[74:75], v[172:173], v[30:31] op_sel:[0,1,0] op_sel_hi:[1,1,1]
	v_pk_fma_f32 v[16:17], v[70:71], v[168:169], v[16:17] op_sel:[0,1,0] op_sel_hi:[1,1,1]
	v_pk_fma_f32 v[32:33], v[66:67], v[172:173], v[32:33] op_sel:[0,1,0] op_sel_hi:[1,1,1]
	v_mov_b32_e32 v156, v65
	v_mov_b32_e32 v157, v17
	v_mov_b32_e32 v166, v65
	v_mov_b32_e32 v167, v17
	s_nop 1
	v_permlane32_swap_b32_e32 v156, v166
	v_permlane32_swap_b32_e32 v157, v167
	v_mov_b32_e32 v156, v49
	v_mov_b32_e32 v157, v33
	v_mov_b32_e32 v150, v49
	v_mov_b32_e32 v151, v33
	s_nop 1
	v_permlane32_swap_b32_e32 v156, v150
	v_permlane32_swap_b32_e32 v157, v151
	v_cvt_pk_bf16_f32 v1, v50, v2
	ds_write_b32 v174, v1
	v_cvt_pk_bf16_f32 v146, v34, v18
	ds_write_b32 v174, v146 offset:128
	v_cvt_pk_bf16_f32 v178, v51, v3
	ds_write_b32 v174, v178 offset:272
	v_cvt_pk_bf16_f32 v1, v35, v19
	ds_write_b32 v174, v1 offset:400
	v_cvt_pk_bf16_f32 v146, v52, v4
	ds_write_b32 v174, v146 offset:544
	v_cvt_pk_bf16_f32 v178, v36, v20
	ds_write_b32 v174, v178 offset:672
	v_cvt_pk_bf16_f32 v1, v53, v5
	ds_write_b32 v174, v1 offset:816
	v_cvt_pk_bf16_f32 v146, v37, v21
	ds_write_b32 v174, v146 offset:944
	v_cvt_pk_bf16_f32 v178, v54, v6
	ds_write_b32 v174, v178 offset:1088
	v_cvt_pk_bf16_f32 v1, v38, v22
	ds_write_b32 v174, v1 offset:1216
	v_cvt_pk_bf16_f32 v146, v55, v7
	ds_write_b32 v174, v146 offset:1360
	v_cvt_pk_bf16_f32 v178, v39, v23
	ds_write_b32 v174, v178 offset:1488
	v_cvt_pk_bf16_f32 v1, v56, v8
	ds_write_b32 v174, v1 offset:1632
	v_cvt_pk_bf16_f32 v146, v40, v24
	ds_write_b32 v174, v146 offset:1760
	v_cvt_pk_bf16_f32 v178, v57, v9
	ds_write_b32 v174, v178 offset:1904
	v_cvt_pk_bf16_f32 v1, v41, v25
	ds_write_b32 v174, v1 offset:2032
	v_cvt_pk_bf16_f32 v146, v58, v10
	ds_write_b32 v174, v146 offset:2176
	v_cvt_pk_bf16_f32 v178, v42, v26
	ds_write_b32 v174, v178 offset:2304
	v_cvt_pk_bf16_f32 v1, v59, v11
	ds_write_b32 v174, v1 offset:2448
	v_cvt_pk_bf16_f32 v146, v43, v27
	ds_write_b32 v174, v146 offset:2576
	v_cvt_pk_bf16_f32 v178, v60, v12
	ds_write_b32 v174, v178 offset:2720
	v_cvt_pk_bf16_f32 v1, v44, v28
	ds_write_b32 v174, v1 offset:2848
	v_cvt_pk_bf16_f32 v146, v61, v13
	ds_write_b32 v174, v146 offset:2992
	v_cvt_pk_bf16_f32 v178, v45, v29
	ds_write_b32 v174, v178 offset:3120
	v_cvt_pk_bf16_f32 v1, v62, v14
	ds_write_b32 v174, v1 offset:3264
	v_cvt_pk_bf16_f32 v146, v46, v30
	ds_write_b32 v174, v146 offset:3392
	v_cvt_pk_bf16_f32 v178, v63, v15
	ds_write_b32 v174, v178 offset:3536
	v_cvt_pk_bf16_f32 v1, v47, v31
	ds_write_b32 v174, v1 offset:3664
	v_cvt_pk_bf16_f32 v146, v64, v16
	ds_write_b32 v174, v146 offset:3808
	v_cvt_pk_bf16_f32 v178, v48, v32
	ds_write_b32 v174, v178 offset:3936
	v_cvt_pk_bf16_f32 v1, v65, v17
	ds_write_b32 v174, v1 offset:4080
	v_cvt_pk_bf16_f32 v146, v49, v33
	ds_write_b32 v174, v146 offset:4208
	s_waitcnt lgkmcnt(0)
	ds_read_b128 v[2:5], v175
	ds_read_b128 v[6:9], v175 offset:64
	ds_read_b128 v[10:13], v175 offset:128
	ds_read_b128 v[14:17], v175 offset:192
	ds_read_b128 v[18:21], v175 offset:4352
	ds_read_b128 v[22:25], v175 offset:4416
	ds_read_b128 v[26:29], v175 offset:4480
	ds_read_b128 v[30:33], v175 offset:4544
	s_waitcnt vmcnt(0)
	s_waitcnt lgkmcnt(7)
	v_mfma_f32_16x16x32_bf16 v[34:37], v[94:97], v[2:5], 0
	s_waitcnt lgkmcnt(6)
	v_mfma_f32_16x16x32_bf16 v[34:37], v[90:93], v[6:9], v[34:37]
	s_waitcnt lgkmcnt(5)
	v_mfma_f32_16x16x32_bf16 v[34:37], v[86:89], v[10:13], v[34:37]
	s_waitcnt lgkmcnt(4)
	v_mfma_f32_16x16x32_bf16 v[34:37], v[82:85], v[14:17], v[34:37]
	s_waitcnt lgkmcnt(3)
	v_mfma_f32_16x16x32_bf16 v[38:41], v[94:97], v[18:21], 0
	s_waitcnt lgkmcnt(2)
	v_mfma_f32_16x16x32_bf16 v[38:41], v[90:93], v[22:25], v[38:41]
	s_waitcnt lgkmcnt(1)
	v_mfma_f32_16x16x32_bf16 v[38:41], v[86:89], v[26:29], v[38:41]
	s_waitcnt lgkmcnt(0)
	v_mfma_f32_16x16x32_bf16 v[38:41], v[82:85], v[30:33], v[38:41]
	s_add_u32 s6, s6, 0x8000
	s_addc_u32 s7, s7, 0
	v_lshlrev_b32_e32 v42, 16, v160
	v_and_b32_e32 v43, 0xffff0000, v160
	v_lshlrev_b32_e32 v44, 16, v161
	v_and_b32_e32 v45, 0xffff0000, v161
	v_lshlrev_b32_e32 v46, 16, v162
	v_and_b32_e32 v47, 0xffff0000, v162
	v_lshlrev_b32_e32 v48, 16, v163
	v_and_b32_e32 v49, 0xffff0000, v163
	s_nop 1
	v_fma_f32 v50, v98, v42, v34
	v_fma_f32 v51, v99, v43, v35
	v_fma_f32 v52, v100, v44, v36
	v_fma_f32 v53, v101, v45, v37
	v_fma_f32 v54, v98, v46, v38
	v_fma_f32 v55, v99, v47, v39
	v_fma_f32 v56, v100, v48, v40
	v_fma_f32 v57, v101, v49, v41
	v_mul_f32_e32 v2, 0x3d372713, v50
	v_mul_f32_e32 v3, 0x3d372713, v51
	v_mul_f32_e32 v4, 0x3d372713, v52
	v_mul_f32_e32 v5, 0x3d372713, v53
	v_mul_f32_e32 v6, 0x3d372713, v54
	v_mul_f32_e32 v7, 0x3d372713, v55
	v_mul_f32_e32 v8, 0x3d372713, v56
	v_mul_f32_e32 v9, 0x3d372713, v57
	v_mul_f32_e32 v2, v50, v2
	v_mul_f32_e32 v3, v51, v3
	v_mul_f32_e32 v4, v52, v4
	v_mul_f32_e32 v5, v53, v5
	v_mul_f32_e32 v6, v54, v6
	v_mul_f32_e32 v7, v55, v7
	v_mul_f32_e32 v8, v56, v8
	v_mul_f32_e32 v9, v57, v9
	v_fma_f32 v2, v50, v2, v50
	v_fma_f32 v3, v51, v3, v51
	v_fma_f32 v4, v52, v4, v52
	v_fma_f32 v5, v53, v5, v53
	v_fma_f32 v6, v54, v6, v54
	v_fma_f32 v7, v55, v7, v55
	v_fma_f32 v8, v56, v8, v56
	v_fma_f32 v9, v57, v9, v57
	v_mul_f32_e32 v2, 0xbfcc422a, v2
	v_mul_f32_e32 v3, 0xbfcc422a, v3
	v_mul_f32_e32 v4, 0xbfcc422a, v4
	v_mul_f32_e32 v5, 0xbfcc422a, v5
	v_mul_f32_e32 v6, 0xbfcc422a, v6
	v_mul_f32_e32 v7, 0xbfcc422a, v7
	v_mul_f32_e32 v8, 0xbfcc422a, v8
	v_mul_f32_e32 v9, 0xbfcc422a, v9
	v_mul_f32_e32 v2, 0x3fb8aa3b, v2
	v_mul_f32_e32 v3, 0x3fb8aa3b, v3
	v_mul_f32_e32 v4, 0x3fb8aa3b, v4
	v_mul_f32_e32 v5, 0x3fb8aa3b, v5
	v_mul_f32_e32 v6, 0x3fb8aa3b, v6
	v_mul_f32_e32 v7, 0x3fb8aa3b, v7
	v_mul_f32_e32 v8, 0x3fb8aa3b, v8
	v_mul_f32_e32 v9, 0x3fb8aa3b, v9
	v_exp_f32_e32 v2, v2
	v_exp_f32_e32 v3, v3
	v_exp_f32_e32 v4, v4
	v_exp_f32_e32 v5, v5
	v_exp_f32_e32 v6, v6
	v_exp_f32_e32 v7, v7
	v_exp_f32_e32 v8, v8
	v_exp_f32_e32 v9, v9
	v_add_f32_e32 v2, 1.0, v2
	v_add_f32_e32 v3, 1.0, v3
	v_add_f32_e32 v4, 1.0, v4
	v_add_f32_e32 v5, 1.0, v5
	v_add_f32_e32 v6, 1.0, v6
	v_add_f32_e32 v7, 1.0, v7
	v_add_f32_e32 v8, 1.0, v8
	v_add_f32_e32 v9, 1.0, v9
	v_rcp_f32_e32 v2, v2
	v_rcp_f32_e32 v3, v3
	v_rcp_f32_e32 v4, v4
	v_rcp_f32_e32 v5, v5
	v_rcp_f32_e32 v6, v6
	v_rcp_f32_e32 v7, v7
	v_rcp_f32_e32 v8, v8
	v_rcp_f32_e32 v9, v9
	v_mul_f32_e32 v50, v50, v2
	v_mul_f32_e32 v51, v51, v3
	v_mul_f32_e32 v52, v52, v4
	v_mul_f32_e32 v53, v53, v5
	v_mul_f32_e32 v54, v54, v6
	v_mul_f32_e32 v55, v55, v7
	v_mul_f32_e32 v56, v56, v8
	v_mul_f32_e32 v57, v57, v9
	v_cvt_pk_bf16_f32 v10, v50, v51
	v_cvt_pk_bf16_f32 v11, v52, v53
	v_cvt_pk_bf16_f32 v12, v54, v55
	v_cvt_pk_bf16_f32 v13, v56, v57
	global_store_dwordx2 v176, v[10:11], s[10:11]
	global_store_dwordx2 v177, v[12:13], s[10:11]
	s_add_u32 s10, s10, 0x8000
	s_addc_u32 s11, s11, 0
	s_nop 0
	v_mfma_f32_32x32x16_bf16 v[50:65], v[126:129], v[114:117], 0
	v_mfma_f32_32x32x16_bf16 v[2:17], v[126:129], v[110:113], 0
	v_mfma_f32_32x32x16_bf16 v[34:49], v[126:129], v[106:109], 0
	v_mfma_f32_32x32x16_bf16 v[18:33], v[126:129], v[102:105], 0
	global_load_dwordx2 v[160:161], v176, s[6:7]
	global_load_dwordx2 v[162:163], v177, s[6:7]
	s_nop 9
	v_fmac_f32_e32 v51, v78, v50
	v_fmac_f32_e32 v35, v74, v34
	v_fmac_f32_e32 v3, v80, v50
	v_fmac_f32_e32 v19, v76, v34
	v_fma_f32 v51, -v80, v2, v51
	v_fma_f32 v35, -v76, v18, v35
	v_fmac_f32_e32 v3, v78, v2
	v_fmac_f32_e32 v19, v74, v18
	v_fmac_f32_e32 v52, v78, v51
	v_fmac_f32_e32 v36, v74, v35
	v_fmac_f32_e32 v4, v80, v51
	v_fmac_f32_e32 v20, v76, v35
	v_fma_f32 v52, -v80, v3, v52
	v_fma_f32 v36, -v76, v19, v36
	v_fmac_f32_e32 v4, v78, v3
	v_fmac_f32_e32 v20, v74, v19
	v_fmac_f32_e32 v53, v78, v52
	v_fmac_f32_e32 v37, v74, v36
	v_fmac_f32_e32 v5, v80, v52
	v_fmac_f32_e32 v21, v76, v36
	v_fma_f32 v53, -v80, v4, v53
	v_fma_f32 v37, -v76, v20, v37
	v_fmac_f32_e32 v5, v78, v4
	v_fmac_f32_e32 v21, v74, v20
	v_fmac_f32_e32 v54, v78, v53
	v_fmac_f32_e32 v38, v74, v37
	v_fmac_f32_e32 v6, v80, v53
	v_fmac_f32_e32 v22, v76, v37
	v_fma_f32 v54, -v80, v5, v54
	v_fma_f32 v38, -v76, v21, v38
	v_fmac_f32_e32 v6, v78, v5
	v_fmac_f32_e32 v22, v74, v21
	v_fmac_f32_e32 v55, v78, v54
	v_fmac_f32_e32 v39, v74, v38
	v_fmac_f32_e32 v7, v80, v54
	v_fmac_f32_e32 v23, v76, v38
	v_fma_f32 v55, -v80, v6, v55
	v_fma_f32 v39, -v76, v22, v39
	v_fmac_f32_e32 v7, v78, v6
	v_fmac_f32_e32 v23, v74, v22
	v_fmac_f32_e32 v56, v78, v55
	v_fmac_f32_e32 v40, v74, v39
	v_fmac_f32_e32 v8, v80, v55
	v_fmac_f32_e32 v24, v76, v39
	v_fma_f32 v56, -v80, v7, v56
	v_fma_f32 v40, -v76, v23, v40
	v_fmac_f32_e32 v8, v78, v7
	v_fmac_f32_e32 v24, v74, v23
	v_fmac_f32_e32 v57, v78, v56
	v_fmac_f32_e32 v41, v74, v40
	v_fmac_f32_e32 v9, v80, v56
	v_fmac_f32_e32 v25, v76, v40
	v_fma_f32 v57, -v80, v8, v57
	v_fma_f32 v41, -v76, v24, v41
	v_fmac_f32_e32 v9, v78, v8
	v_fmac_f32_e32 v25, v74, v24
	v_fmac_f32_e32 v58, v78, v57
	v_fmac_f32_e32 v42, v74, v41
	v_fmac_f32_e32 v10, v80, v57
	v_fmac_f32_e32 v26, v76, v41
	v_fma_f32 v58, -v80, v9, v58
	v_fma_f32 v42, -v76, v25, v42
	v_fmac_f32_e32 v10, v78, v9
	v_fmac_f32_e32 v26, v74, v25
	v_fmac_f32_e32 v59, v78, v58
	v_fmac_f32_e32 v43, v74, v42
	v_fmac_f32_e32 v11, v80, v58
	v_fmac_f32_e32 v27, v76, v42
	v_fma_f32 v59, -v80, v10, v59
	v_fma_f32 v43, -v76, v26, v43
	v_fmac_f32_e32 v11, v78, v10
	v_fmac_f32_e32 v27, v74, v26
	v_fmac_f32_e32 v60, v78, v59
	v_fmac_f32_e32 v44, v74, v43
	v_fmac_f32_e32 v12, v80, v59
	v_fmac_f32_e32 v28, v76, v43
	v_fma_f32 v60, -v80, v11, v60
	v_fma_f32 v44, -v76, v27, v44
	v_fmac_f32_e32 v12, v78, v11
	v_fmac_f32_e32 v28, v74, v27
	v_fmac_f32_e32 v61, v78, v60
	v_fmac_f32_e32 v45, v74, v44
	v_fmac_f32_e32 v13, v80, v60
	v_fmac_f32_e32 v29, v76, v44
	v_fma_f32 v61, -v80, v12, v61
	v_fma_f32 v45, -v76, v28, v45
	v_fmac_f32_e32 v13, v78, v12
	v_fmac_f32_e32 v29, v74, v28
	v_fmac_f32_e32 v62, v78, v61
	v_fmac_f32_e32 v46, v74, v45
	v_fmac_f32_e32 v14, v80, v61
	v_fmac_f32_e32 v30, v76, v45
	v_fma_f32 v62, -v80, v13, v62
	v_fma_f32 v46, -v76, v29, v46
	v_fmac_f32_e32 v14, v78, v13
	v_fmac_f32_e32 v30, v74, v29
	v_fmac_f32_e32 v63, v78, v62
	v_fmac_f32_e32 v47, v74, v46
	v_fmac_f32_e32 v15, v80, v62
	v_fmac_f32_e32 v31, v76, v46
	v_fma_f32 v63, -v80, v14, v63
	v_fma_f32 v47, -v76, v30, v47
	v_fmac_f32_e32 v15, v78, v14
	v_fmac_f32_e32 v31, v74, v30
	v_fmac_f32_e32 v64, v78, v63
	v_fmac_f32_e32 v48, v74, v47
	v_fmac_f32_e32 v16, v80, v63
	v_fmac_f32_e32 v32, v76, v47
	v_fma_f32 v64, -v80, v15, v64
	v_fma_f32 v48, -v76, v31, v48
	v_fmac_f32_e32 v16, v78, v15
	v_fmac_f32_e32 v32, v74, v31
	v_fmac_f32_e32 v65, v78, v64
	v_fmac_f32_e32 v49, v74, v48
	v_fmac_f32_e32 v17, v80, v64
	v_fmac_f32_e32 v33, v76, v48
	v_fma_f32 v65, -v80, v16, v65
	v_fma_f32 v49, -v76, v32, v49
	v_fmac_f32_e32 v17, v78, v16
	v_fmac_f32_e32 v33, v74, v32
	v_mov_b32_e32 v156, v65
	v_mov_b32_e32 v157, v17
	v_mov_b32_e32 v158, v65
	v_mov_b32_e32 v159, v17
	s_nop 1
	v_permlane32_swap_b32_e32 v156, v158
	v_permlane32_swap_b32_e32 v157, v159
	v_pk_fma_f32 v[164:165], v[166:167], v[152:153], v[156:157] op_sel_hi:[1,0,1]
	v_pk_fma_f32 v[164:165], v[166:167], v[152:153], v[164:165] op_sel:[1,1,0] op_sel_hi:[0,1,1] neg_lo:[0,1,0]
	v_cndmask_b32_e32 v164, v166, v164, vcc
	v_cndmask_b32_e32 v165, v167, v165, vcc
	v_mov_b32_e32 v156, v49
	v_mov_b32_e32 v157, v33
	v_mov_b32_e32 v158, v49
	v_mov_b32_e32 v159, v33
	s_nop 1
	v_permlane32_swap_b32_e32 v156, v158
	v_permlane32_swap_b32_e32 v157, v159
	v_pk_fma_f32 v[170:171], v[150:151], v[154:155], v[156:157] op_sel_hi:[1,0,1]
	v_pk_fma_f32 v[170:171], v[150:151], v[154:155], v[170:171] op_sel:[1,1,0] op_sel_hi:[0,1,1] neg_lo:[0,1,0]
	v_cndmask_b32_e32 v170, v150, v170, vcc
	v_cndmask_b32_e32 v171, v151, v171, vcc
	v_pk_mul_f32 v[168:169], v[164:165], v[70:71] op_sel:[0,1] op_sel_hi:[1,1]
	v_pk_mul_f32 v[172:173], v[170:171], v[66:67] op_sel:[0,1] op_sel_hi:[1,1]
	v_pk_fma_f32 v[168:169], v[164:165], v[72:73], v[168:169] op_sel:[1,1,0] op_sel_hi:[0,1,1] neg_lo:[0,1,0]
	v_pk_fma_f32 v[172:173], v[170:171], v[68:69], v[172:173] op_sel:[1,1,0] op_sel_hi:[0,1,1] neg_lo:[0,1,0]
	v_pk_fma_f32 v[50:51], v[78:79], v[164:165], v[50:51] op_sel_hi:[1,0,1]
	v_pk_fma_f32 v[34:35], v[74:75], v[170:171], v[34:35] op_sel_hi:[1,0,1]
	v_pk_fma_f32 v[52:53], v[70:71], v[164:165], v[52:53] op_sel_hi:[1,0,1]
	v_pk_fma_f32 v[36:37], v[66:67], v[170:171], v[36:37] op_sel_hi:[1,0,1]
	v_pk_fma_f32 v[2:3], v[80:81], v[164:165], v[2:3] op_sel_hi:[1,0,1]
	v_pk_fma_f32 v[18:19], v[76:77], v[170:171], v[18:19] op_sel_hi:[1,0,1]
	v_pk_fma_f32 v[4:5], v[72:73], v[164:165], v[4:5] op_sel_hi:[1,0,1]
	v_pk_fma_f32 v[20:21], v[68:69], v[170:171], v[20:21] op_sel_hi:[1,0,1]
	v_pk_fma_f32 v[50:51], v[80:81], v[164:165], v[50:51] op_sel:[0,1,0] op_sel_hi:[1,1,1] neg_lo:[0,1,0] neg_hi:[0,1,0]
	v_pk_fma_f32 v[34:35], v[76:77], v[170:171], v[34:35] op_sel:[0,1,0] op_sel_hi:[1,1,1] neg_lo:[0,1,0] neg_hi:[0,1,0]
	v_pk_fma_f32 v[52:53], v[72:73], v[164:165], v[52:53] op_sel:[0,1,0] op_sel_hi:[1,1,1] neg_lo:[0,1,0] neg_hi:[0,1,0]
	v_pk_fma_f32 v[36:37], v[68:69], v[170:171], v[36:37] op_sel:[0,1,0] op_sel_hi:[1,1,1] neg_lo:[0,1,0] neg_hi:[0,1,0]
	v_pk_fma_f32 v[2:3], v[78:79], v[164:165], v[2:3] op_sel:[0,1,0] op_sel_hi:[1,1,1]
	v_pk_fma_f32 v[18:19], v[74:75], v[170:171], v[18:19] op_sel:[0,1,0] op_sel_hi:[1,1,1]
	v_pk_fma_f32 v[4:5], v[70:71], v[164:165], v[4:5] op_sel:[0,1,0] op_sel_hi:[1,1,1]
	v_pk_fma_f32 v[20:21], v[66:67], v[170:171], v[20:21] op_sel:[0,1,0] op_sel_hi:[1,1,1]
	v_pk_mul_f32 v[164:165], v[168:169], v[70:71] op_sel:[0,1] op_sel_hi:[1,1]
	v_pk_mul_f32 v[170:171], v[172:173], v[66:67] op_sel:[0,1] op_sel_hi:[1,1]
	v_pk_fma_f32 v[164:165], v[168:169], v[72:73], v[164:165] op_sel:[1,1,0] op_sel_hi:[0,1,1] neg_lo:[0,1,0]
	v_pk_fma_f32 v[170:171], v[172:173], v[68:69], v[170:171] op_sel:[1,1,0] op_sel_hi:[0,1,1] neg_lo:[0,1,0]
	v_pk_fma_f32 v[54:55], v[78:79], v[168:169], v[54:55] op_sel_hi:[1,0,1]
	v_pk_fma_f32 v[38:39], v[74:75], v[172:173], v[38:39] op_sel_hi:[1,0,1]
	v_pk_fma_f32 v[56:57], v[70:71], v[168:169], v[56:57] op_sel_hi:[1,0,1]
	v_pk_fma_f32 v[40:41], v[66:67], v[172:173], v[40:41] op_sel_hi:[1,0,1]
	v_pk_fma_f32 v[6:7], v[80:81], v[168:169], v[6:7] op_sel_hi:[1,0,1]
	v_pk_fma_f32 v[22:23], v[76:77], v[172:173], v[22:23] op_sel_hi:[1,0,1]
	v_pk_fma_f32 v[8:9], v[72:73], v[168:169], v[8:9] op_sel_hi:[1,0,1]
	v_pk_fma_f32 v[24:25], v[68:69], v[172:173], v[24:25] op_sel_hi:[1,0,1]
	v_pk_fma_f32 v[54:55], v[80:81], v[168:169], v[54:55] op_sel:[0,1,0] op_sel_hi:[1,1,1] neg_lo:[0,1,0] neg_hi:[0,1,0]
	v_pk_fma_f32 v[38:39], v[76:77], v[172:173], v[38:39] op_sel:[0,1,0] op_sel_hi:[1,1,1] neg_lo:[0,1,0] neg_hi:[0,1,0]
	v_pk_fma_f32 v[56:57], v[72:73], v[168:169], v[56:57] op_sel:[0,1,0] op_sel_hi:[1,1,1] neg_lo:[0,1,0] neg_hi:[0,1,0]
	v_pk_fma_f32 v[40:41], v[68:69], v[172:173], v[40:41] op_sel:[0,1,0] op_sel_hi:[1,1,1] neg_lo:[0,1,0] neg_hi:[0,1,0]
	v_pk_fma_f32 v[6:7], v[78:79], v[168:169], v[6:7] op_sel:[0,1,0] op_sel_hi:[1,1,1]
	v_pk_fma_f32 v[22:23], v[74:75], v[172:173], v[22:23] op_sel:[0,1,0] op_sel_hi:[1,1,1]
	v_pk_fma_f32 v[8:9], v[70:71], v[168:169], v[8:9] op_sel:[0,1,0] op_sel_hi:[1,1,1]
	v_pk_fma_f32 v[24:25], v[66:67], v[172:173], v[24:25] op_sel:[0,1,0] op_sel_hi:[1,1,1]
	v_pk_mul_f32 v[168:169], v[164:165], v[70:71] op_sel:[0,1] op_sel_hi:[1,1]
	v_pk_mul_f32 v[172:173], v[170:171], v[66:67] op_sel:[0,1] op_sel_hi:[1,1]
	v_pk_fma_f32 v[168:169], v[164:165], v[72:73], v[168:169] op_sel:[1,1,0] op_sel_hi:[0,1,1] neg_lo:[0,1,0]
	v_pk_fma_f32 v[172:173], v[170:171], v[68:69], v[172:173] op_sel:[1,1,0] op_sel_hi:[0,1,1] neg_lo:[0,1,0]
	v_pk_fma_f32 v[58:59], v[78:79], v[164:165], v[58:59] op_sel_hi:[1,0,1]
	v_pk_fma_f32 v[42:43], v[74:75], v[170:171], v[42:43] op_sel_hi:[1,0,1]
	v_pk_fma_f32 v[60:61], v[70:71], v[164:165], v[60:61] op_sel_hi:[1,0,1]
	v_pk_fma_f32 v[44:45], v[66:67], v[170:171], v[44:45] op_sel_hi:[1,0,1]
	v_pk_fma_f32 v[10:11], v[80:81], v[164:165], v[10:11] op_sel_hi:[1,0,1]
	v_pk_fma_f32 v[26:27], v[76:77], v[170:171], v[26:27] op_sel_hi:[1,0,1]
	v_pk_fma_f32 v[12:13], v[72:73], v[164:165], v[12:13] op_sel_hi:[1,0,1]
	v_pk_fma_f32 v[28:29], v[68:69], v[170:171], v[28:29] op_sel_hi:[1,0,1]
	v_pk_fma_f32 v[58:59], v[80:81], v[164:165], v[58:59] op_sel:[0,1,0] op_sel_hi:[1,1,1] neg_lo:[0,1,0] neg_hi:[0,1,0]
	v_pk_fma_f32 v[42:43], v[76:77], v[170:171], v[42:43] op_sel:[0,1,0] op_sel_hi:[1,1,1] neg_lo:[0,1,0] neg_hi:[0,1,0]
	v_pk_fma_f32 v[60:61], v[72:73], v[164:165], v[60:61] op_sel:[0,1,0] op_sel_hi:[1,1,1] neg_lo:[0,1,0] neg_hi:[0,1,0]
	v_pk_fma_f32 v[44:45], v[68:69], v[170:171], v[44:45] op_sel:[0,1,0] op_sel_hi:[1,1,1] neg_lo:[0,1,0] neg_hi:[0,1,0]
	v_pk_fma_f32 v[10:11], v[78:79], v[164:165], v[10:11] op_sel:[0,1,0] op_sel_hi:[1,1,1]
	v_pk_fma_f32 v[26:27], v[74:75], v[170:171], v[26:27] op_sel:[0,1,0] op_sel_hi:[1,1,1]
	v_pk_fma_f32 v[12:13], v[70:71], v[164:165], v[12:13] op_sel:[0,1,0] op_sel_hi:[1,1,1]
	v_pk_fma_f32 v[28:29], v[66:67], v[170:171], v[28:29] op_sel:[0,1,0] op_sel_hi:[1,1,1]
	v_pk_fma_f32 v[62:63], v[78:79], v[168:169], v[62:63] op_sel_hi:[1,0,1]
	v_pk_fma_f32 v[46:47], v[74:75], v[172:173], v[46:47] op_sel_hi:[1,0,1]
	v_pk_fma_f32 v[64:65], v[70:71], v[168:169], v[64:65] op_sel_hi:[1,0,1]
	v_pk_fma_f32 v[48:49], v[66:67], v[172:173], v[48:49] op_sel_hi:[1,0,1]
	v_pk_fma_f32 v[14:15], v[80:81], v[168:169], v[14:15] op_sel_hi:[1,0,1]
	v_pk_fma_f32 v[30:31], v[76:77], v[172:173], v[30:31] op_sel_hi:[1,0,1]
	v_pk_fma_f32 v[16:17], v[72:73], v[168:169], v[16:17] op_sel_hi:[1,0,1]
	v_pk_fma_f32 v[32:33], v[68:69], v[172:173], v[32:33] op_sel_hi:[1,0,1]
	v_pk_fma_f32 v[62:63], v[80:81], v[168:169], v[62:63] op_sel:[0,1,0] op_sel_hi:[1,1,1] neg_lo:[0,1,0] neg_hi:[0,1,0]
	v_pk_fma_f32 v[46:47], v[76:77], v[172:173], v[46:47] op_sel:[0,1,0] op_sel_hi:[1,1,1] neg_lo:[0,1,0] neg_hi:[0,1,0]
	v_pk_fma_f32 v[64:65], v[72:73], v[168:169], v[64:65] op_sel:[0,1,0] op_sel_hi:[1,1,1] neg_lo:[0,1,0] neg_hi:[0,1,0]
	v_pk_fma_f32 v[48:49], v[68:69], v[172:173], v[48:49] op_sel:[0,1,0] op_sel_hi:[1,1,1] neg_lo:[0,1,0] neg_hi:[0,1,0]
	v_pk_fma_f32 v[14:15], v[78:79], v[168:169], v[14:15] op_sel:[0,1,0] op_sel_hi:[1,1,1]
	v_pk_fma_f32 v[30:31], v[74:75], v[172:173], v[30:31] op_sel:[0,1,0] op_sel_hi:[1,1,1]
	v_pk_fma_f32 v[16:17], v[70:71], v[168:169], v[16:17] op_sel:[0,1,0] op_sel_hi:[1,1,1]
	v_pk_fma_f32 v[32:33], v[66:67], v[172:173], v[32:33] op_sel:[0,1,0] op_sel_hi:[1,1,1]
	v_mov_b32_e32 v156, v65
	v_mov_b32_e32 v157, v17
	v_mov_b32_e32 v166, v65
	v_mov_b32_e32 v167, v17
	s_nop 1
	v_permlane32_swap_b32_e32 v156, v166
	v_permlane32_swap_b32_e32 v157, v167
	v_mov_b32_e32 v156, v49
	v_mov_b32_e32 v157, v33
	v_mov_b32_e32 v150, v49
	v_mov_b32_e32 v151, v33
	s_nop 1
	v_permlane32_swap_b32_e32 v156, v150
	v_permlane32_swap_b32_e32 v157, v151
	v_cvt_pk_bf16_f32 v1, v50, v2
	ds_write_b32 v174, v1
	v_cvt_pk_bf16_f32 v146, v34, v18
	ds_write_b32 v174, v146 offset:128
	v_cvt_pk_bf16_f32 v178, v51, v3
	ds_write_b32 v174, v178 offset:272
	v_cvt_pk_bf16_f32 v1, v35, v19
	ds_write_b32 v174, v1 offset:400
	v_cvt_pk_bf16_f32 v146, v52, v4
	ds_write_b32 v174, v146 offset:544
	v_cvt_pk_bf16_f32 v178, v36, v20
	ds_write_b32 v174, v178 offset:672
	v_cvt_pk_bf16_f32 v1, v53, v5
	ds_write_b32 v174, v1 offset:816
	v_cvt_pk_bf16_f32 v146, v37, v21
	ds_write_b32 v174, v146 offset:944
	v_cvt_pk_bf16_f32 v178, v54, v6
	ds_write_b32 v174, v178 offset:1088
	v_cvt_pk_bf16_f32 v1, v38, v22
	ds_write_b32 v174, v1 offset:1216
	v_cvt_pk_bf16_f32 v146, v55, v7
	ds_write_b32 v174, v146 offset:1360
	v_cvt_pk_bf16_f32 v178, v39, v23
	ds_write_b32 v174, v178 offset:1488
	v_cvt_pk_bf16_f32 v1, v56, v8
	ds_write_b32 v174, v1 offset:1632
	v_cvt_pk_bf16_f32 v146, v40, v24
	ds_write_b32 v174, v146 offset:1760
	v_cvt_pk_bf16_f32 v178, v57, v9
	ds_write_b32 v174, v178 offset:1904
	v_cvt_pk_bf16_f32 v1, v41, v25
	ds_write_b32 v174, v1 offset:2032
	v_cvt_pk_bf16_f32 v146, v58, v10
	ds_write_b32 v174, v146 offset:2176
	v_cvt_pk_bf16_f32 v178, v42, v26
	ds_write_b32 v174, v178 offset:2304
	v_cvt_pk_bf16_f32 v1, v59, v11
	ds_write_b32 v174, v1 offset:2448
	v_cvt_pk_bf16_f32 v146, v43, v27
	ds_write_b32 v174, v146 offset:2576
	v_cvt_pk_bf16_f32 v178, v60, v12
	ds_write_b32 v174, v178 offset:2720
	v_cvt_pk_bf16_f32 v1, v44, v28
	ds_write_b32 v174, v1 offset:2848
	v_cvt_pk_bf16_f32 v146, v61, v13
	ds_write_b32 v174, v146 offset:2992
	v_cvt_pk_bf16_f32 v178, v45, v29
	ds_write_b32 v174, v178 offset:3120
	v_cvt_pk_bf16_f32 v1, v62, v14
	ds_write_b32 v174, v1 offset:3264
	v_cvt_pk_bf16_f32 v146, v46, v30
	ds_write_b32 v174, v146 offset:3392
	v_cvt_pk_bf16_f32 v178, v63, v15
	ds_write_b32 v174, v178 offset:3536
	v_cvt_pk_bf16_f32 v1, v47, v31
	ds_write_b32 v174, v1 offset:3664
	v_cvt_pk_bf16_f32 v146, v64, v16
	ds_write_b32 v174, v146 offset:3808
	v_cvt_pk_bf16_f32 v178, v48, v32
	ds_write_b32 v174, v178 offset:3936
	v_cvt_pk_bf16_f32 v1, v65, v17
	ds_write_b32 v174, v1 offset:4080
	v_cvt_pk_bf16_f32 v146, v49, v33
	ds_write_b32 v174, v146 offset:4208
	s_waitcnt lgkmcnt(0)
	ds_read_b128 v[2:5], v175
	ds_read_b128 v[6:9], v175 offset:64
	ds_read_b128 v[10:13], v175 offset:128
	ds_read_b128 v[14:17], v175 offset:192
	ds_read_b128 v[18:21], v175 offset:4352
	ds_read_b128 v[22:25], v175 offset:4416
	ds_read_b128 v[26:29], v175 offset:4480
	ds_read_b128 v[30:33], v175 offset:4544
	s_waitcnt vmcnt(0)
	s_waitcnt lgkmcnt(7)
	v_mfma_f32_16x16x32_bf16 v[34:37], v[94:97], v[2:5], 0
	s_waitcnt lgkmcnt(6)
	v_mfma_f32_16x16x32_bf16 v[34:37], v[90:93], v[6:9], v[34:37]
	s_waitcnt lgkmcnt(5)
	v_mfma_f32_16x16x32_bf16 v[34:37], v[86:89], v[10:13], v[34:37]
	s_waitcnt lgkmcnt(4)
	v_mfma_f32_16x16x32_bf16 v[34:37], v[82:85], v[14:17], v[34:37]
	s_waitcnt lgkmcnt(3)
	v_mfma_f32_16x16x32_bf16 v[38:41], v[94:97], v[18:21], 0
	s_waitcnt lgkmcnt(2)
	v_mfma_f32_16x16x32_bf16 v[38:41], v[90:93], v[22:25], v[38:41]
	s_waitcnt lgkmcnt(1)
	v_mfma_f32_16x16x32_bf16 v[38:41], v[86:89], v[26:29], v[38:41]
	s_waitcnt lgkmcnt(0)
	v_mfma_f32_16x16x32_bf16 v[38:41], v[82:85], v[30:33], v[38:41]
	s_add_u32 s6, s6, 0x8000
	s_addc_u32 s7, s7, 0
	v_lshlrev_b32_e32 v42, 16, v160
	v_and_b32_e32 v43, 0xffff0000, v160
	v_lshlrev_b32_e32 v44, 16, v161
	v_and_b32_e32 v45, 0xffff0000, v161
	v_lshlrev_b32_e32 v46, 16, v162
	v_and_b32_e32 v47, 0xffff0000, v162
	v_lshlrev_b32_e32 v48, 16, v163
	v_and_b32_e32 v49, 0xffff0000, v163
	s_nop 1
	v_fma_f32 v50, v98, v42, v34
	v_fma_f32 v51, v99, v43, v35
	v_fma_f32 v52, v100, v44, v36
	v_fma_f32 v53, v101, v45, v37
	v_fma_f32 v54, v98, v46, v38
	v_fma_f32 v55, v99, v47, v39
	v_fma_f32 v56, v100, v48, v40
	v_fma_f32 v57, v101, v49, v41
	v_mul_f32_e32 v2, 0x3d372713, v50
	v_mul_f32_e32 v3, 0x3d372713, v51
	v_mul_f32_e32 v4, 0x3d372713, v52
	v_mul_f32_e32 v5, 0x3d372713, v53
	v_mul_f32_e32 v6, 0x3d372713, v54
	v_mul_f32_e32 v7, 0x3d372713, v55
	v_mul_f32_e32 v8, 0x3d372713, v56
	v_mul_f32_e32 v9, 0x3d372713, v57
	v_mul_f32_e32 v2, v50, v2
	v_mul_f32_e32 v3, v51, v3
	v_mul_f32_e32 v4, v52, v4
	v_mul_f32_e32 v5, v53, v5
	v_mul_f32_e32 v6, v54, v6
	v_mul_f32_e32 v7, v55, v7
	v_mul_f32_e32 v8, v56, v8
	v_mul_f32_e32 v9, v57, v9
	v_fma_f32 v2, v50, v2, v50
	v_fma_f32 v3, v51, v3, v51
	v_fma_f32 v4, v52, v4, v52
	v_fma_f32 v5, v53, v5, v53
	v_fma_f32 v6, v54, v6, v54
	v_fma_f32 v7, v55, v7, v55
	v_fma_f32 v8, v56, v8, v56
	v_fma_f32 v9, v57, v9, v57
	v_mul_f32_e32 v2, 0xbfcc422a, v2
	v_mul_f32_e32 v3, 0xbfcc422a, v3
	v_mul_f32_e32 v4, 0xbfcc422a, v4
	v_mul_f32_e32 v5, 0xbfcc422a, v5
	v_mul_f32_e32 v6, 0xbfcc422a, v6
	v_mul_f32_e32 v7, 0xbfcc422a, v7
	v_mul_f32_e32 v8, 0xbfcc422a, v8
	v_mul_f32_e32 v9, 0xbfcc422a, v9
	v_mul_f32_e32 v2, 0x3fb8aa3b, v2
	v_mul_f32_e32 v3, 0x3fb8aa3b, v3
	v_mul_f32_e32 v4, 0x3fb8aa3b, v4
	v_mul_f32_e32 v5, 0x3fb8aa3b, v5
	v_mul_f32_e32 v6, 0x3fb8aa3b, v6
	v_mul_f32_e32 v7, 0x3fb8aa3b, v7
	v_mul_f32_e32 v8, 0x3fb8aa3b, v8
	v_mul_f32_e32 v9, 0x3fb8aa3b, v9
	v_exp_f32_e32 v2, v2
	v_exp_f32_e32 v3, v3
	v_exp_f32_e32 v4, v4
	v_exp_f32_e32 v5, v5
	v_exp_f32_e32 v6, v6
	v_exp_f32_e32 v7, v7
	v_exp_f32_e32 v8, v8
	v_exp_f32_e32 v9, v9
	v_add_f32_e32 v2, 1.0, v2
	v_add_f32_e32 v3, 1.0, v3
	v_add_f32_e32 v4, 1.0, v4
	v_add_f32_e32 v5, 1.0, v5
	v_add_f32_e32 v6, 1.0, v6
	v_add_f32_e32 v7, 1.0, v7
	v_add_f32_e32 v8, 1.0, v8
	v_add_f32_e32 v9, 1.0, v9
	v_rcp_f32_e32 v2, v2
	v_rcp_f32_e32 v3, v3
	v_rcp_f32_e32 v4, v4
	v_rcp_f32_e32 v5, v5
	v_rcp_f32_e32 v6, v6
	v_rcp_f32_e32 v7, v7
	v_rcp_f32_e32 v8, v8
	v_rcp_f32_e32 v9, v9
	v_mul_f32_e32 v50, v50, v2
	v_mul_f32_e32 v51, v51, v3
	v_mul_f32_e32 v52, v52, v4
	v_mul_f32_e32 v53, v53, v5
	v_mul_f32_e32 v54, v54, v6
	v_mul_f32_e32 v55, v55, v7
	v_mul_f32_e32 v56, v56, v8
	v_mul_f32_e32 v57, v57, v9
	v_cvt_pk_bf16_f32 v10, v50, v51
	v_cvt_pk_bf16_f32 v11, v52, v53
	v_cvt_pk_bf16_f32 v12, v54, v55
	v_cvt_pk_bf16_f32 v13, v56, v57
	global_store_dwordx2 v176, v[10:11], s[10:11]
	global_store_dwordx2 v177, v[12:13], s[10:11]
	s_add_u32 s10, s10, 0x8000
	s_addc_u32 s11, s11, 0
	s_nop 0
	v_mfma_f32_32x32x16_bf16 v[50:65], v[122:125], v[114:117], 0
	v_mfma_f32_32x32x16_bf16 v[2:17], v[122:125], v[110:113], 0
	v_mfma_f32_32x32x16_bf16 v[34:49], v[122:125], v[106:109], 0
	v_mfma_f32_32x32x16_bf16 v[18:33], v[122:125], v[102:105], 0
	global_load_dwordx2 v[160:161], v176, s[6:7]
	global_load_dwordx2 v[162:163], v177, s[6:7]
	s_nop 9
	v_fmac_f32_e32 v51, v78, v50
	v_fmac_f32_e32 v35, v74, v34
	v_fmac_f32_e32 v3, v80, v50
	v_fmac_f32_e32 v19, v76, v34
	v_fma_f32 v51, -v80, v2, v51
	v_fma_f32 v35, -v76, v18, v35
	v_fmac_f32_e32 v3, v78, v2
	v_fmac_f32_e32 v19, v74, v18
	v_fmac_f32_e32 v52, v78, v51
	v_fmac_f32_e32 v36, v74, v35
	v_fmac_f32_e32 v4, v80, v51
	v_fmac_f32_e32 v20, v76, v35
	v_fma_f32 v52, -v80, v3, v52
	v_fma_f32 v36, -v76, v19, v36
	v_fmac_f32_e32 v4, v78, v3
	v_fmac_f32_e32 v20, v74, v19
	v_fmac_f32_e32 v53, v78, v52
	v_fmac_f32_e32 v37, v74, v36
	v_fmac_f32_e32 v5, v80, v52
	v_fmac_f32_e32 v21, v76, v36
	v_fma_f32 v53, -v80, v4, v53
	v_fma_f32 v37, -v76, v20, v37
	v_fmac_f32_e32 v5, v78, v4
	v_fmac_f32_e32 v21, v74, v20
	v_fmac_f32_e32 v54, v78, v53
	v_fmac_f32_e32 v38, v74, v37
	v_fmac_f32_e32 v6, v80, v53
	v_fmac_f32_e32 v22, v76, v37
	v_fma_f32 v54, -v80, v5, v54
	v_fma_f32 v38, -v76, v21, v38
	v_fmac_f32_e32 v6, v78, v5
	v_fmac_f32_e32 v22, v74, v21
	v_fmac_f32_e32 v55, v78, v54
	v_fmac_f32_e32 v39, v74, v38
	v_fmac_f32_e32 v7, v80, v54
	v_fmac_f32_e32 v23, v76, v38
	v_fma_f32 v55, -v80, v6, v55
	v_fma_f32 v39, -v76, v22, v39
	v_fmac_f32_e32 v7, v78, v6
	v_fmac_f32_e32 v23, v74, v22
	v_fmac_f32_e32 v56, v78, v55
	v_fmac_f32_e32 v40, v74, v39
	v_fmac_f32_e32 v8, v80, v55
	v_fmac_f32_e32 v24, v76, v39
	v_fma_f32 v56, -v80, v7, v56
	v_fma_f32 v40, -v76, v23, v40
	v_fmac_f32_e32 v8, v78, v7
	v_fmac_f32_e32 v24, v74, v23
	v_fmac_f32_e32 v57, v78, v56
	v_fmac_f32_e32 v41, v74, v40
	v_fmac_f32_e32 v9, v80, v56
	v_fmac_f32_e32 v25, v76, v40
	v_fma_f32 v57, -v80, v8, v57
	v_fma_f32 v41, -v76, v24, v41
	v_fmac_f32_e32 v9, v78, v8
	v_fmac_f32_e32 v25, v74, v24
	v_fmac_f32_e32 v58, v78, v57
	v_fmac_f32_e32 v42, v74, v41
	v_fmac_f32_e32 v10, v80, v57
	v_fmac_f32_e32 v26, v76, v41
	v_fma_f32 v58, -v80, v9, v58
	v_fma_f32 v42, -v76, v25, v42
	v_fmac_f32_e32 v10, v78, v9
	v_fmac_f32_e32 v26, v74, v25
	v_fmac_f32_e32 v59, v78, v58
	v_fmac_f32_e32 v43, v74, v42
	v_fmac_f32_e32 v11, v80, v58
	v_fmac_f32_e32 v27, v76, v42
	v_fma_f32 v59, -v80, v10, v59
	v_fma_f32 v43, -v76, v26, v43
	v_fmac_f32_e32 v11, v78, v10
	v_fmac_f32_e32 v27, v74, v26
	v_fmac_f32_e32 v60, v78, v59
	v_fmac_f32_e32 v44, v74, v43
	v_fmac_f32_e32 v12, v80, v59
	v_fmac_f32_e32 v28, v76, v43
	v_fma_f32 v60, -v80, v11, v60
	v_fma_f32 v44, -v76, v27, v44
	v_fmac_f32_e32 v12, v78, v11
	v_fmac_f32_e32 v28, v74, v27
	v_fmac_f32_e32 v61, v78, v60
	v_fmac_f32_e32 v45, v74, v44
	v_fmac_f32_e32 v13, v80, v60
	v_fmac_f32_e32 v29, v76, v44
	v_fma_f32 v61, -v80, v12, v61
	v_fma_f32 v45, -v76, v28, v45
	v_fmac_f32_e32 v13, v78, v12
	v_fmac_f32_e32 v29, v74, v28
	v_fmac_f32_e32 v62, v78, v61
	v_fmac_f32_e32 v46, v74, v45
	v_fmac_f32_e32 v14, v80, v61
	v_fmac_f32_e32 v30, v76, v45
	v_fma_f32 v62, -v80, v13, v62
	v_fma_f32 v46, -v76, v29, v46
	v_fmac_f32_e32 v14, v78, v13
	v_fmac_f32_e32 v30, v74, v29
	v_fmac_f32_e32 v63, v78, v62
	v_fmac_f32_e32 v47, v74, v46
	v_fmac_f32_e32 v15, v80, v62
	v_fmac_f32_e32 v31, v76, v46
	v_fma_f32 v63, -v80, v14, v63
	v_fma_f32 v47, -v76, v30, v47
	v_fmac_f32_e32 v15, v78, v14
	v_fmac_f32_e32 v31, v74, v30
	v_fmac_f32_e32 v64, v78, v63
	v_fmac_f32_e32 v48, v74, v47
	v_fmac_f32_e32 v16, v80, v63
	v_fmac_f32_e32 v32, v76, v47
	v_fma_f32 v64, -v80, v15, v64
	v_fma_f32 v48, -v76, v31, v48
	v_fmac_f32_e32 v16, v78, v15
	v_fmac_f32_e32 v32, v74, v31
	v_fmac_f32_e32 v65, v78, v64
	v_fmac_f32_e32 v49, v74, v48
	v_fmac_f32_e32 v17, v80, v64
	v_fmac_f32_e32 v33, v76, v48
	v_fma_f32 v65, -v80, v16, v65
	v_fma_f32 v49, -v76, v32, v49
	v_fmac_f32_e32 v17, v78, v16
	v_fmac_f32_e32 v33, v74, v32
	v_mov_b32_e32 v156, v65
	v_mov_b32_e32 v157, v17
	v_mov_b32_e32 v158, v65
	v_mov_b32_e32 v159, v17
	s_nop 1
	v_permlane32_swap_b32_e32 v156, v158
	v_permlane32_swap_b32_e32 v157, v159
	v_pk_fma_f32 v[164:165], v[166:167], v[152:153], v[156:157] op_sel_hi:[1,0,1]
	v_pk_fma_f32 v[164:165], v[166:167], v[152:153], v[164:165] op_sel:[1,1,0] op_sel_hi:[0,1,1] neg_lo:[0,1,0]
	v_cndmask_b32_e32 v164, v166, v164, vcc
	v_cndmask_b32_e32 v165, v167, v165, vcc
	v_mov_b32_e32 v156, v49
	v_mov_b32_e32 v157, v33
	v_mov_b32_e32 v158, v49
	v_mov_b32_e32 v159, v33
	s_nop 1
	v_permlane32_swap_b32_e32 v156, v158
	v_permlane32_swap_b32_e32 v157, v159
	v_pk_fma_f32 v[170:171], v[150:151], v[154:155], v[156:157] op_sel_hi:[1,0,1]
	v_pk_fma_f32 v[170:171], v[150:151], v[154:155], v[170:171] op_sel:[1,1,0] op_sel_hi:[0,1,1] neg_lo:[0,1,0]
	v_cndmask_b32_e32 v170, v150, v170, vcc
	v_cndmask_b32_e32 v171, v151, v171, vcc
	v_pk_mul_f32 v[168:169], v[164:165], v[70:71] op_sel:[0,1] op_sel_hi:[1,1]
	v_pk_mul_f32 v[172:173], v[170:171], v[66:67] op_sel:[0,1] op_sel_hi:[1,1]
	v_pk_fma_f32 v[168:169], v[164:165], v[72:73], v[168:169] op_sel:[1,1,0] op_sel_hi:[0,1,1] neg_lo:[0,1,0]
	v_pk_fma_f32 v[172:173], v[170:171], v[68:69], v[172:173] op_sel:[1,1,0] op_sel_hi:[0,1,1] neg_lo:[0,1,0]
	v_pk_fma_f32 v[50:51], v[78:79], v[164:165], v[50:51] op_sel_hi:[1,0,1]
	v_pk_fma_f32 v[34:35], v[74:75], v[170:171], v[34:35] op_sel_hi:[1,0,1]
	v_pk_fma_f32 v[52:53], v[70:71], v[164:165], v[52:53] op_sel_hi:[1,0,1]
	v_pk_fma_f32 v[36:37], v[66:67], v[170:171], v[36:37] op_sel_hi:[1,0,1]
	v_pk_fma_f32 v[2:3], v[80:81], v[164:165], v[2:3] op_sel_hi:[1,0,1]
	v_pk_fma_f32 v[18:19], v[76:77], v[170:171], v[18:19] op_sel_hi:[1,0,1]
	v_pk_fma_f32 v[4:5], v[72:73], v[164:165], v[4:5] op_sel_hi:[1,0,1]
	v_pk_fma_f32 v[20:21], v[68:69], v[170:171], v[20:21] op_sel_hi:[1,0,1]
	v_pk_fma_f32 v[50:51], v[80:81], v[164:165], v[50:51] op_sel:[0,1,0] op_sel_hi:[1,1,1] neg_lo:[0,1,0] neg_hi:[0,1,0]
	v_pk_fma_f32 v[34:35], v[76:77], v[170:171], v[34:35] op_sel:[0,1,0] op_sel_hi:[1,1,1] neg_lo:[0,1,0] neg_hi:[0,1,0]
	v_pk_fma_f32 v[52:53], v[72:73], v[164:165], v[52:53] op_sel:[0,1,0] op_sel_hi:[1,1,1] neg_lo:[0,1,0] neg_hi:[0,1,0]
	v_pk_fma_f32 v[36:37], v[68:69], v[170:171], v[36:37] op_sel:[0,1,0] op_sel_hi:[1,1,1] neg_lo:[0,1,0] neg_hi:[0,1,0]
	v_pk_fma_f32 v[2:3], v[78:79], v[164:165], v[2:3] op_sel:[0,1,0] op_sel_hi:[1,1,1]
	v_pk_fma_f32 v[18:19], v[74:75], v[170:171], v[18:19] op_sel:[0,1,0] op_sel_hi:[1,1,1]
	v_pk_fma_f32 v[4:5], v[70:71], v[164:165], v[4:5] op_sel:[0,1,0] op_sel_hi:[1,1,1]
	v_pk_fma_f32 v[20:21], v[66:67], v[170:171], v[20:21] op_sel:[0,1,0] op_sel_hi:[1,1,1]
	v_pk_mul_f32 v[164:165], v[168:169], v[70:71] op_sel:[0,1] op_sel_hi:[1,1]
	v_pk_mul_f32 v[170:171], v[172:173], v[66:67] op_sel:[0,1] op_sel_hi:[1,1]
	v_pk_fma_f32 v[164:165], v[168:169], v[72:73], v[164:165] op_sel:[1,1,0] op_sel_hi:[0,1,1] neg_lo:[0,1,0]
	v_pk_fma_f32 v[170:171], v[172:173], v[68:69], v[170:171] op_sel:[1,1,0] op_sel_hi:[0,1,1] neg_lo:[0,1,0]
	v_pk_fma_f32 v[54:55], v[78:79], v[168:169], v[54:55] op_sel_hi:[1,0,1]
	v_pk_fma_f32 v[38:39], v[74:75], v[172:173], v[38:39] op_sel_hi:[1,0,1]
	v_pk_fma_f32 v[56:57], v[70:71], v[168:169], v[56:57] op_sel_hi:[1,0,1]
	v_pk_fma_f32 v[40:41], v[66:67], v[172:173], v[40:41] op_sel_hi:[1,0,1]
	v_pk_fma_f32 v[6:7], v[80:81], v[168:169], v[6:7] op_sel_hi:[1,0,1]
	v_pk_fma_f32 v[22:23], v[76:77], v[172:173], v[22:23] op_sel_hi:[1,0,1]
	v_pk_fma_f32 v[8:9], v[72:73], v[168:169], v[8:9] op_sel_hi:[1,0,1]
	v_pk_fma_f32 v[24:25], v[68:69], v[172:173], v[24:25] op_sel_hi:[1,0,1]
	v_pk_fma_f32 v[54:55], v[80:81], v[168:169], v[54:55] op_sel:[0,1,0] op_sel_hi:[1,1,1] neg_lo:[0,1,0] neg_hi:[0,1,0]
	v_pk_fma_f32 v[38:39], v[76:77], v[172:173], v[38:39] op_sel:[0,1,0] op_sel_hi:[1,1,1] neg_lo:[0,1,0] neg_hi:[0,1,0]
	v_pk_fma_f32 v[56:57], v[72:73], v[168:169], v[56:57] op_sel:[0,1,0] op_sel_hi:[1,1,1] neg_lo:[0,1,0] neg_hi:[0,1,0]
	v_pk_fma_f32 v[40:41], v[68:69], v[172:173], v[40:41] op_sel:[0,1,0] op_sel_hi:[1,1,1] neg_lo:[0,1,0] neg_hi:[0,1,0]
	v_pk_fma_f32 v[6:7], v[78:79], v[168:169], v[6:7] op_sel:[0,1,0] op_sel_hi:[1,1,1]
	v_pk_fma_f32 v[22:23], v[74:75], v[172:173], v[22:23] op_sel:[0,1,0] op_sel_hi:[1,1,1]
	v_pk_fma_f32 v[8:9], v[70:71], v[168:169], v[8:9] op_sel:[0,1,0] op_sel_hi:[1,1,1]
	v_pk_fma_f32 v[24:25], v[66:67], v[172:173], v[24:25] op_sel:[0,1,0] op_sel_hi:[1,1,1]
	v_pk_mul_f32 v[168:169], v[164:165], v[70:71] op_sel:[0,1] op_sel_hi:[1,1]
	v_pk_mul_f32 v[172:173], v[170:171], v[66:67] op_sel:[0,1] op_sel_hi:[1,1]
	v_pk_fma_f32 v[168:169], v[164:165], v[72:73], v[168:169] op_sel:[1,1,0] op_sel_hi:[0,1,1] neg_lo:[0,1,0]
	v_pk_fma_f32 v[172:173], v[170:171], v[68:69], v[172:173] op_sel:[1,1,0] op_sel_hi:[0,1,1] neg_lo:[0,1,0]
	v_pk_fma_f32 v[58:59], v[78:79], v[164:165], v[58:59] op_sel_hi:[1,0,1]
	v_pk_fma_f32 v[42:43], v[74:75], v[170:171], v[42:43] op_sel_hi:[1,0,1]
	v_pk_fma_f32 v[60:61], v[70:71], v[164:165], v[60:61] op_sel_hi:[1,0,1]
	v_pk_fma_f32 v[44:45], v[66:67], v[170:171], v[44:45] op_sel_hi:[1,0,1]
	v_pk_fma_f32 v[10:11], v[80:81], v[164:165], v[10:11] op_sel_hi:[1,0,1]
	v_pk_fma_f32 v[26:27], v[76:77], v[170:171], v[26:27] op_sel_hi:[1,0,1]
	v_pk_fma_f32 v[12:13], v[72:73], v[164:165], v[12:13] op_sel_hi:[1,0,1]
	v_pk_fma_f32 v[28:29], v[68:69], v[170:171], v[28:29] op_sel_hi:[1,0,1]
	v_pk_fma_f32 v[58:59], v[80:81], v[164:165], v[58:59] op_sel:[0,1,0] op_sel_hi:[1,1,1] neg_lo:[0,1,0] neg_hi:[0,1,0]
	v_pk_fma_f32 v[42:43], v[76:77], v[170:171], v[42:43] op_sel:[0,1,0] op_sel_hi:[1,1,1] neg_lo:[0,1,0] neg_hi:[0,1,0]
	v_pk_fma_f32 v[60:61], v[72:73], v[164:165], v[60:61] op_sel:[0,1,0] op_sel_hi:[1,1,1] neg_lo:[0,1,0] neg_hi:[0,1,0]
	v_pk_fma_f32 v[44:45], v[68:69], v[170:171], v[44:45] op_sel:[0,1,0] op_sel_hi:[1,1,1] neg_lo:[0,1,0] neg_hi:[0,1,0]
	v_pk_fma_f32 v[10:11], v[78:79], v[164:165], v[10:11] op_sel:[0,1,0] op_sel_hi:[1,1,1]
	v_pk_fma_f32 v[26:27], v[74:75], v[170:171], v[26:27] op_sel:[0,1,0] op_sel_hi:[1,1,1]
	v_pk_fma_f32 v[12:13], v[70:71], v[164:165], v[12:13] op_sel:[0,1,0] op_sel_hi:[1,1,1]
	v_pk_fma_f32 v[28:29], v[66:67], v[170:171], v[28:29] op_sel:[0,1,0] op_sel_hi:[1,1,1]
	v_pk_fma_f32 v[62:63], v[78:79], v[168:169], v[62:63] op_sel_hi:[1,0,1]
	v_pk_fma_f32 v[46:47], v[74:75], v[172:173], v[46:47] op_sel_hi:[1,0,1]
	v_pk_fma_f32 v[64:65], v[70:71], v[168:169], v[64:65] op_sel_hi:[1,0,1]
	v_pk_fma_f32 v[48:49], v[66:67], v[172:173], v[48:49] op_sel_hi:[1,0,1]
	v_pk_fma_f32 v[14:15], v[80:81], v[168:169], v[14:15] op_sel_hi:[1,0,1]
	v_pk_fma_f32 v[30:31], v[76:77], v[172:173], v[30:31] op_sel_hi:[1,0,1]
	v_pk_fma_f32 v[16:17], v[72:73], v[168:169], v[16:17] op_sel_hi:[1,0,1]
	v_pk_fma_f32 v[32:33], v[68:69], v[172:173], v[32:33] op_sel_hi:[1,0,1]
	v_pk_fma_f32 v[62:63], v[80:81], v[168:169], v[62:63] op_sel:[0,1,0] op_sel_hi:[1,1,1] neg_lo:[0,1,0] neg_hi:[0,1,0]
	v_pk_fma_f32 v[46:47], v[76:77], v[172:173], v[46:47] op_sel:[0,1,0] op_sel_hi:[1,1,1] neg_lo:[0,1,0] neg_hi:[0,1,0]
	v_pk_fma_f32 v[64:65], v[72:73], v[168:169], v[64:65] op_sel:[0,1,0] op_sel_hi:[1,1,1] neg_lo:[0,1,0] neg_hi:[0,1,0]
	v_pk_fma_f32 v[48:49], v[68:69], v[172:173], v[48:49] op_sel:[0,1,0] op_sel_hi:[1,1,1] neg_lo:[0,1,0] neg_hi:[0,1,0]
	v_pk_fma_f32 v[14:15], v[78:79], v[168:169], v[14:15] op_sel:[0,1,0] op_sel_hi:[1,1,1]
	v_pk_fma_f32 v[30:31], v[74:75], v[172:173], v[30:31] op_sel:[0,1,0] op_sel_hi:[1,1,1]
	v_pk_fma_f32 v[16:17], v[70:71], v[168:169], v[16:17] op_sel:[0,1,0] op_sel_hi:[1,1,1]
	v_pk_fma_f32 v[32:33], v[66:67], v[172:173], v[32:33] op_sel:[0,1,0] op_sel_hi:[1,1,1]
	v_mov_b32_e32 v156, v65
	v_mov_b32_e32 v157, v17
	v_mov_b32_e32 v166, v65
	v_mov_b32_e32 v167, v17
	s_nop 1
	v_permlane32_swap_b32_e32 v156, v166
	v_permlane32_swap_b32_e32 v157, v167
	v_mov_b32_e32 v156, v49
	v_mov_b32_e32 v157, v33
	v_mov_b32_e32 v150, v49
	v_mov_b32_e32 v151, v33
	s_nop 1
	v_permlane32_swap_b32_e32 v156, v150
	v_permlane32_swap_b32_e32 v157, v151
	v_cvt_pk_bf16_f32 v1, v50, v2
	ds_write_b32 v174, v1
	v_cvt_pk_bf16_f32 v146, v34, v18
	ds_write_b32 v174, v146 offset:128
	v_cvt_pk_bf16_f32 v178, v51, v3
	ds_write_b32 v174, v178 offset:272
	v_cvt_pk_bf16_f32 v1, v35, v19
	ds_write_b32 v174, v1 offset:400
	v_cvt_pk_bf16_f32 v146, v52, v4
	ds_write_b32 v174, v146 offset:544
	v_cvt_pk_bf16_f32 v178, v36, v20
	ds_write_b32 v174, v178 offset:672
	v_cvt_pk_bf16_f32 v1, v53, v5
	ds_write_b32 v174, v1 offset:816
	v_cvt_pk_bf16_f32 v146, v37, v21
	ds_write_b32 v174, v146 offset:944
	v_cvt_pk_bf16_f32 v178, v54, v6
	ds_write_b32 v174, v178 offset:1088
	v_cvt_pk_bf16_f32 v1, v38, v22
	ds_write_b32 v174, v1 offset:1216
	v_cvt_pk_bf16_f32 v146, v55, v7
	ds_write_b32 v174, v146 offset:1360
	v_cvt_pk_bf16_f32 v178, v39, v23
	ds_write_b32 v174, v178 offset:1488
	v_cvt_pk_bf16_f32 v1, v56, v8
	ds_write_b32 v174, v1 offset:1632
	v_cvt_pk_bf16_f32 v146, v40, v24
	ds_write_b32 v174, v146 offset:1760
	v_cvt_pk_bf16_f32 v178, v57, v9
	ds_write_b32 v174, v178 offset:1904
	v_cvt_pk_bf16_f32 v1, v41, v25
	ds_write_b32 v174, v1 offset:2032
	v_cvt_pk_bf16_f32 v146, v58, v10
	ds_write_b32 v174, v146 offset:2176
	v_cvt_pk_bf16_f32 v178, v42, v26
	ds_write_b32 v174, v178 offset:2304
	v_cvt_pk_bf16_f32 v1, v59, v11
	ds_write_b32 v174, v1 offset:2448
	v_cvt_pk_bf16_f32 v146, v43, v27
	ds_write_b32 v174, v146 offset:2576
	v_cvt_pk_bf16_f32 v178, v60, v12
	ds_write_b32 v174, v178 offset:2720
	v_cvt_pk_bf16_f32 v1, v44, v28
	ds_write_b32 v174, v1 offset:2848
	v_cvt_pk_bf16_f32 v146, v61, v13
	ds_write_b32 v174, v146 offset:2992
	v_cvt_pk_bf16_f32 v178, v45, v29
	ds_write_b32 v174, v178 offset:3120
	v_cvt_pk_bf16_f32 v1, v62, v14
	ds_write_b32 v174, v1 offset:3264
	v_cvt_pk_bf16_f32 v146, v46, v30
	ds_write_b32 v174, v146 offset:3392
	v_cvt_pk_bf16_f32 v178, v63, v15
	ds_write_b32 v174, v178 offset:3536
	v_cvt_pk_bf16_f32 v1, v47, v31
	ds_write_b32 v174, v1 offset:3664
	v_cvt_pk_bf16_f32 v146, v64, v16
	ds_write_b32 v174, v146 offset:3808
	v_cvt_pk_bf16_f32 v178, v48, v32
	ds_write_b32 v174, v178 offset:3936
	v_cvt_pk_bf16_f32 v1, v65, v17
	ds_write_b32 v174, v1 offset:4080
	v_cvt_pk_bf16_f32 v146, v49, v33
	ds_write_b32 v174, v146 offset:4208
	s_waitcnt lgkmcnt(0)
	ds_read_b128 v[2:5], v175
	ds_read_b128 v[6:9], v175 offset:64
	ds_read_b128 v[10:13], v175 offset:128
	ds_read_b128 v[14:17], v175 offset:192
	ds_read_b128 v[18:21], v175 offset:4352
	ds_read_b128 v[22:25], v175 offset:4416
	ds_read_b128 v[26:29], v175 offset:4480
	ds_read_b128 v[30:33], v175 offset:4544
	s_waitcnt vmcnt(0)
	s_waitcnt lgkmcnt(7)
	v_mfma_f32_16x16x32_bf16 v[34:37], v[94:97], v[2:5], 0
	s_waitcnt lgkmcnt(6)
	v_mfma_f32_16x16x32_bf16 v[34:37], v[90:93], v[6:9], v[34:37]
	s_waitcnt lgkmcnt(5)
	v_mfma_f32_16x16x32_bf16 v[34:37], v[86:89], v[10:13], v[34:37]
	s_waitcnt lgkmcnt(4)
	v_mfma_f32_16x16x32_bf16 v[34:37], v[82:85], v[14:17], v[34:37]
	s_waitcnt lgkmcnt(3)
	v_mfma_f32_16x16x32_bf16 v[38:41], v[94:97], v[18:21], 0
	s_waitcnt lgkmcnt(2)
	v_mfma_f32_16x16x32_bf16 v[38:41], v[90:93], v[22:25], v[38:41]
	s_waitcnt lgkmcnt(1)
	v_mfma_f32_16x16x32_bf16 v[38:41], v[86:89], v[26:29], v[38:41]
	s_waitcnt lgkmcnt(0)
	v_mfma_f32_16x16x32_bf16 v[38:41], v[82:85], v[30:33], v[38:41]
	s_add_u32 s6, s6, 0x8000
	s_addc_u32 s7, s7, 0
	v_lshlrev_b32_e32 v42, 16, v160
	v_and_b32_e32 v43, 0xffff0000, v160
	v_lshlrev_b32_e32 v44, 16, v161
	v_and_b32_e32 v45, 0xffff0000, v161
	v_lshlrev_b32_e32 v46, 16, v162
	v_and_b32_e32 v47, 0xffff0000, v162
	v_lshlrev_b32_e32 v48, 16, v163
	v_and_b32_e32 v49, 0xffff0000, v163
	s_nop 1
	v_fma_f32 v50, v98, v42, v34
	v_fma_f32 v51, v99, v43, v35
	v_fma_f32 v52, v100, v44, v36
	v_fma_f32 v53, v101, v45, v37
	v_fma_f32 v54, v98, v46, v38
	v_fma_f32 v55, v99, v47, v39
	v_fma_f32 v56, v100, v48, v40
	v_fma_f32 v57, v101, v49, v41
	v_mul_f32_e32 v2, 0x3d372713, v50
	v_mul_f32_e32 v3, 0x3d372713, v51
	v_mul_f32_e32 v4, 0x3d372713, v52
	v_mul_f32_e32 v5, 0x3d372713, v53
	v_mul_f32_e32 v6, 0x3d372713, v54
	v_mul_f32_e32 v7, 0x3d372713, v55
	v_mul_f32_e32 v8, 0x3d372713, v56
	v_mul_f32_e32 v9, 0x3d372713, v57
	v_mul_f32_e32 v2, v50, v2
	v_mul_f32_e32 v3, v51, v3
	v_mul_f32_e32 v4, v52, v4
	v_mul_f32_e32 v5, v53, v5
	v_mul_f32_e32 v6, v54, v6
	v_mul_f32_e32 v7, v55, v7
	v_mul_f32_e32 v8, v56, v8
	v_mul_f32_e32 v9, v57, v9
	v_fma_f32 v2, v50, v2, v50
	v_fma_f32 v3, v51, v3, v51
	v_fma_f32 v4, v52, v4, v52
	v_fma_f32 v5, v53, v5, v53
	v_fma_f32 v6, v54, v6, v54
	v_fma_f32 v7, v55, v7, v55
	v_fma_f32 v8, v56, v8, v56
	v_fma_f32 v9, v57, v9, v57
	v_mul_f32_e32 v2, 0xbfcc422a, v2
	v_mul_f32_e32 v3, 0xbfcc422a, v3
	v_mul_f32_e32 v4, 0xbfcc422a, v4
	v_mul_f32_e32 v5, 0xbfcc422a, v5
	v_mul_f32_e32 v6, 0xbfcc422a, v6
	v_mul_f32_e32 v7, 0xbfcc422a, v7
	v_mul_f32_e32 v8, 0xbfcc422a, v8
	v_mul_f32_e32 v9, 0xbfcc422a, v9
	v_mul_f32_e32 v2, 0x3fb8aa3b, v2
	v_mul_f32_e32 v3, 0x3fb8aa3b, v3
	v_mul_f32_e32 v4, 0x3fb8aa3b, v4
	v_mul_f32_e32 v5, 0x3fb8aa3b, v5
	v_mul_f32_e32 v6, 0x3fb8aa3b, v6
	v_mul_f32_e32 v7, 0x3fb8aa3b, v7
	v_mul_f32_e32 v8, 0x3fb8aa3b, v8
	v_mul_f32_e32 v9, 0x3fb8aa3b, v9
	v_exp_f32_e32 v2, v2
	v_exp_f32_e32 v3, v3
	v_exp_f32_e32 v4, v4
	v_exp_f32_e32 v5, v5
	v_exp_f32_e32 v6, v6
	v_exp_f32_e32 v7, v7
	v_exp_f32_e32 v8, v8
	v_exp_f32_e32 v9, v9
	v_add_f32_e32 v2, 1.0, v2
	v_add_f32_e32 v3, 1.0, v3
	v_add_f32_e32 v4, 1.0, v4
	v_add_f32_e32 v5, 1.0, v5
	v_add_f32_e32 v6, 1.0, v6
	v_add_f32_e32 v7, 1.0, v7
	v_add_f32_e32 v8, 1.0, v8
	v_add_f32_e32 v9, 1.0, v9
	v_rcp_f32_e32 v2, v2
	v_rcp_f32_e32 v3, v3
	v_rcp_f32_e32 v4, v4
	v_rcp_f32_e32 v5, v5
	v_rcp_f32_e32 v6, v6
	v_rcp_f32_e32 v7, v7
	v_rcp_f32_e32 v8, v8
	v_rcp_f32_e32 v9, v9
	v_mul_f32_e32 v50, v50, v2
	v_mul_f32_e32 v51, v51, v3
	v_mul_f32_e32 v52, v52, v4
	v_mul_f32_e32 v53, v53, v5
	v_mul_f32_e32 v54, v54, v6
	v_mul_f32_e32 v55, v55, v7
	v_mul_f32_e32 v56, v56, v8
	v_mul_f32_e32 v57, v57, v9
	v_cvt_pk_bf16_f32 v10, v50, v51
	v_cvt_pk_bf16_f32 v11, v52, v53
	v_cvt_pk_bf16_f32 v12, v54, v55
	v_cvt_pk_bf16_f32 v13, v56, v57
	global_store_dwordx2 v176, v[10:11], s[10:11]
	global_store_dwordx2 v177, v[12:13], s[10:11]
	s_add_u32 s10, s10, 0x8000
	s_addc_u32 s11, s11, 0
	s_nop 0
	v_mfma_f32_32x32x16_bf16 v[50:65], v[118:121], v[114:117], 0
	v_mfma_f32_32x32x16_bf16 v[2:17], v[118:121], v[110:113], 0
	v_mfma_f32_32x32x16_bf16 v[34:49], v[118:121], v[106:109], 0
	v_mfma_f32_32x32x16_bf16 v[18:33], v[118:121], v[102:105], 0
	global_load_dwordx2 v[160:161], v176, s[6:7]
	global_load_dwordx2 v[162:163], v177, s[6:7]
	s_nop 9
	v_fmac_f32_e32 v51, v78, v50
	v_fmac_f32_e32 v35, v74, v34
	v_fmac_f32_e32 v3, v80, v50
	v_fmac_f32_e32 v19, v76, v34
	v_fma_f32 v51, -v80, v2, v51
	v_fma_f32 v35, -v76, v18, v35
	v_fmac_f32_e32 v3, v78, v2
	v_fmac_f32_e32 v19, v74, v18
	v_fmac_f32_e32 v52, v78, v51
	v_fmac_f32_e32 v36, v74, v35
	v_fmac_f32_e32 v4, v80, v51
	v_fmac_f32_e32 v20, v76, v35
	v_fma_f32 v52, -v80, v3, v52
	v_fma_f32 v36, -v76, v19, v36
	v_fmac_f32_e32 v4, v78, v3
	v_fmac_f32_e32 v20, v74, v19
	v_fmac_f32_e32 v53, v78, v52
	v_fmac_f32_e32 v37, v74, v36
	v_fmac_f32_e32 v5, v80, v52
	v_fmac_f32_e32 v21, v76, v36
	v_fma_f32 v53, -v80, v4, v53
	v_fma_f32 v37, -v76, v20, v37
	v_fmac_f32_e32 v5, v78, v4
	v_fmac_f32_e32 v21, v74, v20
	v_fmac_f32_e32 v54, v78, v53
	v_fmac_f32_e32 v38, v74, v37
	v_fmac_f32_e32 v6, v80, v53
	v_fmac_f32_e32 v22, v76, v37
	v_fma_f32 v54, -v80, v5, v54
	v_fma_f32 v38, -v76, v21, v38
	v_fmac_f32_e32 v6, v78, v5
	v_fmac_f32_e32 v22, v74, v21
	v_fmac_f32_e32 v55, v78, v54
	v_fmac_f32_e32 v39, v74, v38
	v_fmac_f32_e32 v7, v80, v54
	v_fmac_f32_e32 v23, v76, v38
	v_fma_f32 v55, -v80, v6, v55
	v_fma_f32 v39, -v76, v22, v39
	v_fmac_f32_e32 v7, v78, v6
	v_fmac_f32_e32 v23, v74, v22
	v_fmac_f32_e32 v56, v78, v55
	v_fmac_f32_e32 v40, v74, v39
	v_fmac_f32_e32 v8, v80, v55
	v_fmac_f32_e32 v24, v76, v39
	v_fma_f32 v56, -v80, v7, v56
	v_fma_f32 v40, -v76, v23, v40
	v_fmac_f32_e32 v8, v78, v7
	v_fmac_f32_e32 v24, v74, v23
	v_fmac_f32_e32 v57, v78, v56
	v_fmac_f32_e32 v41, v74, v40
	v_fmac_f32_e32 v9, v80, v56
	v_fmac_f32_e32 v25, v76, v40
	v_fma_f32 v57, -v80, v8, v57
	v_fma_f32 v41, -v76, v24, v41
	v_fmac_f32_e32 v9, v78, v8
	v_fmac_f32_e32 v25, v74, v24
	v_fmac_f32_e32 v58, v78, v57
	v_fmac_f32_e32 v42, v74, v41
	v_fmac_f32_e32 v10, v80, v57
	v_fmac_f32_e32 v26, v76, v41
	v_fma_f32 v58, -v80, v9, v58
	v_fma_f32 v42, -v76, v25, v42
	v_fmac_f32_e32 v10, v78, v9
	v_fmac_f32_e32 v26, v74, v25
	v_fmac_f32_e32 v59, v78, v58
	v_fmac_f32_e32 v43, v74, v42
	v_fmac_f32_e32 v11, v80, v58
	v_fmac_f32_e32 v27, v76, v42
	v_fma_f32 v59, -v80, v10, v59
	v_fma_f32 v43, -v76, v26, v43
	v_fmac_f32_e32 v11, v78, v10
	v_fmac_f32_e32 v27, v74, v26
	v_fmac_f32_e32 v60, v78, v59
	v_fmac_f32_e32 v44, v74, v43
	v_fmac_f32_e32 v12, v80, v59
	v_fmac_f32_e32 v28, v76, v43
	v_fma_f32 v60, -v80, v11, v60
	v_fma_f32 v44, -v76, v27, v44
	v_fmac_f32_e32 v12, v78, v11
	v_fmac_f32_e32 v28, v74, v27
	v_fmac_f32_e32 v61, v78, v60
	v_fmac_f32_e32 v45, v74, v44
	v_fmac_f32_e32 v13, v80, v60
	v_fmac_f32_e32 v29, v76, v44
	v_fma_f32 v61, -v80, v12, v61
	v_fma_f32 v45, -v76, v28, v45
	v_fmac_f32_e32 v13, v78, v12
	v_fmac_f32_e32 v29, v74, v28
	v_fmac_f32_e32 v62, v78, v61
	v_fmac_f32_e32 v46, v74, v45
	v_fmac_f32_e32 v14, v80, v61
	v_fmac_f32_e32 v30, v76, v45
	v_fma_f32 v62, -v80, v13, v62
	v_fma_f32 v46, -v76, v29, v46
	v_fmac_f32_e32 v14, v78, v13
	v_fmac_f32_e32 v30, v74, v29
	v_fmac_f32_e32 v63, v78, v62
	v_fmac_f32_e32 v47, v74, v46
	v_fmac_f32_e32 v15, v80, v62
	v_fmac_f32_e32 v31, v76, v46
	v_fma_f32 v63, -v80, v14, v63
	v_fma_f32 v47, -v76, v30, v47
	v_fmac_f32_e32 v15, v78, v14
	v_fmac_f32_e32 v31, v74, v30
	v_fmac_f32_e32 v64, v78, v63
	v_fmac_f32_e32 v48, v74, v47
	v_fmac_f32_e32 v16, v80, v63
	v_fmac_f32_e32 v32, v76, v47
	v_fma_f32 v64, -v80, v15, v64
	v_fma_f32 v48, -v76, v31, v48
	v_fmac_f32_e32 v16, v78, v15
	v_fmac_f32_e32 v32, v74, v31
	v_fmac_f32_e32 v65, v78, v64
	v_fmac_f32_e32 v49, v74, v48
	v_fmac_f32_e32 v17, v80, v64
	v_fmac_f32_e32 v33, v76, v48
	v_fma_f32 v65, -v80, v16, v65
	v_fma_f32 v49, -v76, v32, v49
	v_fmac_f32_e32 v17, v78, v16
	v_fmac_f32_e32 v33, v74, v32
	v_mov_b32_e32 v156, v65
	v_mov_b32_e32 v157, v17
	v_mov_b32_e32 v158, v65
	v_mov_b32_e32 v159, v17
	s_nop 1
	v_permlane32_swap_b32_e32 v156, v158
	v_permlane32_swap_b32_e32 v157, v159
	v_pk_fma_f32 v[164:165], v[166:167], v[152:153], v[156:157] op_sel_hi:[1,0,1]
	v_pk_fma_f32 v[164:165], v[166:167], v[152:153], v[164:165] op_sel:[1,1,0] op_sel_hi:[0,1,1] neg_lo:[0,1,0]
	v_cndmask_b32_e32 v164, v166, v164, vcc
	v_cndmask_b32_e32 v165, v167, v165, vcc
	v_mov_b32_e32 v156, v49
	v_mov_b32_e32 v157, v33
	v_mov_b32_e32 v158, v49
	v_mov_b32_e32 v159, v33
	s_nop 1
	v_permlane32_swap_b32_e32 v156, v158
	v_permlane32_swap_b32_e32 v157, v159
	v_pk_fma_f32 v[170:171], v[150:151], v[154:155], v[156:157] op_sel_hi:[1,0,1]
	v_pk_fma_f32 v[170:171], v[150:151], v[154:155], v[170:171] op_sel:[1,1,0] op_sel_hi:[0,1,1] neg_lo:[0,1,0]
	v_cndmask_b32_e32 v170, v150, v170, vcc
	v_cndmask_b32_e32 v171, v151, v171, vcc
	v_pk_mul_f32 v[168:169], v[164:165], v[70:71] op_sel:[0,1] op_sel_hi:[1,1]
	v_pk_mul_f32 v[172:173], v[170:171], v[66:67] op_sel:[0,1] op_sel_hi:[1,1]
	v_pk_fma_f32 v[168:169], v[164:165], v[72:73], v[168:169] op_sel:[1,1,0] op_sel_hi:[0,1,1] neg_lo:[0,1,0]
	v_pk_fma_f32 v[172:173], v[170:171], v[68:69], v[172:173] op_sel:[1,1,0] op_sel_hi:[0,1,1] neg_lo:[0,1,0]
	v_pk_fma_f32 v[50:51], v[78:79], v[164:165], v[50:51] op_sel_hi:[1,0,1]
	v_pk_fma_f32 v[34:35], v[74:75], v[170:171], v[34:35] op_sel_hi:[1,0,1]
	v_pk_fma_f32 v[52:53], v[70:71], v[164:165], v[52:53] op_sel_hi:[1,0,1]
	v_pk_fma_f32 v[36:37], v[66:67], v[170:171], v[36:37] op_sel_hi:[1,0,1]
	v_pk_fma_f32 v[2:3], v[80:81], v[164:165], v[2:3] op_sel_hi:[1,0,1]
	v_pk_fma_f32 v[18:19], v[76:77], v[170:171], v[18:19] op_sel_hi:[1,0,1]
	v_pk_fma_f32 v[4:5], v[72:73], v[164:165], v[4:5] op_sel_hi:[1,0,1]
	v_pk_fma_f32 v[20:21], v[68:69], v[170:171], v[20:21] op_sel_hi:[1,0,1]
	v_pk_fma_f32 v[50:51], v[80:81], v[164:165], v[50:51] op_sel:[0,1,0] op_sel_hi:[1,1,1] neg_lo:[0,1,0] neg_hi:[0,1,0]
	v_pk_fma_f32 v[34:35], v[76:77], v[170:171], v[34:35] op_sel:[0,1,0] op_sel_hi:[1,1,1] neg_lo:[0,1,0] neg_hi:[0,1,0]
	v_pk_fma_f32 v[52:53], v[72:73], v[164:165], v[52:53] op_sel:[0,1,0] op_sel_hi:[1,1,1] neg_lo:[0,1,0] neg_hi:[0,1,0]
	v_pk_fma_f32 v[36:37], v[68:69], v[170:171], v[36:37] op_sel:[0,1,0] op_sel_hi:[1,1,1] neg_lo:[0,1,0] neg_hi:[0,1,0]
	v_pk_fma_f32 v[2:3], v[78:79], v[164:165], v[2:3] op_sel:[0,1,0] op_sel_hi:[1,1,1]
	v_pk_fma_f32 v[18:19], v[74:75], v[170:171], v[18:19] op_sel:[0,1,0] op_sel_hi:[1,1,1]
	v_pk_fma_f32 v[4:5], v[70:71], v[164:165], v[4:5] op_sel:[0,1,0] op_sel_hi:[1,1,1]
	v_pk_fma_f32 v[20:21], v[66:67], v[170:171], v[20:21] op_sel:[0,1,0] op_sel_hi:[1,1,1]
	v_pk_mul_f32 v[164:165], v[168:169], v[70:71] op_sel:[0,1] op_sel_hi:[1,1]
	v_pk_mul_f32 v[170:171], v[172:173], v[66:67] op_sel:[0,1] op_sel_hi:[1,1]
	v_pk_fma_f32 v[164:165], v[168:169], v[72:73], v[164:165] op_sel:[1,1,0] op_sel_hi:[0,1,1] neg_lo:[0,1,0]
	v_pk_fma_f32 v[170:171], v[172:173], v[68:69], v[170:171] op_sel:[1,1,0] op_sel_hi:[0,1,1] neg_lo:[0,1,0]
	v_pk_fma_f32 v[54:55], v[78:79], v[168:169], v[54:55] op_sel_hi:[1,0,1]
	v_pk_fma_f32 v[38:39], v[74:75], v[172:173], v[38:39] op_sel_hi:[1,0,1]
	v_pk_fma_f32 v[56:57], v[70:71], v[168:169], v[56:57] op_sel_hi:[1,0,1]
	v_pk_fma_f32 v[40:41], v[66:67], v[172:173], v[40:41] op_sel_hi:[1,0,1]
	v_pk_fma_f32 v[6:7], v[80:81], v[168:169], v[6:7] op_sel_hi:[1,0,1]
	v_pk_fma_f32 v[22:23], v[76:77], v[172:173], v[22:23] op_sel_hi:[1,0,1]
	v_pk_fma_f32 v[8:9], v[72:73], v[168:169], v[8:9] op_sel_hi:[1,0,1]
	v_pk_fma_f32 v[24:25], v[68:69], v[172:173], v[24:25] op_sel_hi:[1,0,1]
	v_pk_fma_f32 v[54:55], v[80:81], v[168:169], v[54:55] op_sel:[0,1,0] op_sel_hi:[1,1,1] neg_lo:[0,1,0] neg_hi:[0,1,0]
	v_pk_fma_f32 v[38:39], v[76:77], v[172:173], v[38:39] op_sel:[0,1,0] op_sel_hi:[1,1,1] neg_lo:[0,1,0] neg_hi:[0,1,0]
	v_pk_fma_f32 v[56:57], v[72:73], v[168:169], v[56:57] op_sel:[0,1,0] op_sel_hi:[1,1,1] neg_lo:[0,1,0] neg_hi:[0,1,0]
	v_pk_fma_f32 v[40:41], v[68:69], v[172:173], v[40:41] op_sel:[0,1,0] op_sel_hi:[1,1,1] neg_lo:[0,1,0] neg_hi:[0,1,0]
	v_pk_fma_f32 v[6:7], v[78:79], v[168:169], v[6:7] op_sel:[0,1,0] op_sel_hi:[1,1,1]
	v_pk_fma_f32 v[22:23], v[74:75], v[172:173], v[22:23] op_sel:[0,1,0] op_sel_hi:[1,1,1]
	v_pk_fma_f32 v[8:9], v[70:71], v[168:169], v[8:9] op_sel:[0,1,0] op_sel_hi:[1,1,1]
	v_pk_fma_f32 v[24:25], v[66:67], v[172:173], v[24:25] op_sel:[0,1,0] op_sel_hi:[1,1,1]
	v_pk_mul_f32 v[168:169], v[164:165], v[70:71] op_sel:[0,1] op_sel_hi:[1,1]
	v_pk_mul_f32 v[172:173], v[170:171], v[66:67] op_sel:[0,1] op_sel_hi:[1,1]
	v_pk_fma_f32 v[168:169], v[164:165], v[72:73], v[168:169] op_sel:[1,1,0] op_sel_hi:[0,1,1] neg_lo:[0,1,0]
	v_pk_fma_f32 v[172:173], v[170:171], v[68:69], v[172:173] op_sel:[1,1,0] op_sel_hi:[0,1,1] neg_lo:[0,1,0]
	v_pk_fma_f32 v[58:59], v[78:79], v[164:165], v[58:59] op_sel_hi:[1,0,1]
	v_pk_fma_f32 v[42:43], v[74:75], v[170:171], v[42:43] op_sel_hi:[1,0,1]
	v_pk_fma_f32 v[60:61], v[70:71], v[164:165], v[60:61] op_sel_hi:[1,0,1]
	v_pk_fma_f32 v[44:45], v[66:67], v[170:171], v[44:45] op_sel_hi:[1,0,1]
	v_pk_fma_f32 v[10:11], v[80:81], v[164:165], v[10:11] op_sel_hi:[1,0,1]
	v_pk_fma_f32 v[26:27], v[76:77], v[170:171], v[26:27] op_sel_hi:[1,0,1]
	v_pk_fma_f32 v[12:13], v[72:73], v[164:165], v[12:13] op_sel_hi:[1,0,1]
	v_pk_fma_f32 v[28:29], v[68:69], v[170:171], v[28:29] op_sel_hi:[1,0,1]
	v_pk_fma_f32 v[58:59], v[80:81], v[164:165], v[58:59] op_sel:[0,1,0] op_sel_hi:[1,1,1] neg_lo:[0,1,0] neg_hi:[0,1,0]
	v_pk_fma_f32 v[42:43], v[76:77], v[170:171], v[42:43] op_sel:[0,1,0] op_sel_hi:[1,1,1] neg_lo:[0,1,0] neg_hi:[0,1,0]
	v_pk_fma_f32 v[60:61], v[72:73], v[164:165], v[60:61] op_sel:[0,1,0] op_sel_hi:[1,1,1] neg_lo:[0,1,0] neg_hi:[0,1,0]
	v_pk_fma_f32 v[44:45], v[68:69], v[170:171], v[44:45] op_sel:[0,1,0] op_sel_hi:[1,1,1] neg_lo:[0,1,0] neg_hi:[0,1,0]
	v_pk_fma_f32 v[10:11], v[78:79], v[164:165], v[10:11] op_sel:[0,1,0] op_sel_hi:[1,1,1]
	v_pk_fma_f32 v[26:27], v[74:75], v[170:171], v[26:27] op_sel:[0,1,0] op_sel_hi:[1,1,1]
	v_pk_fma_f32 v[12:13], v[70:71], v[164:165], v[12:13] op_sel:[0,1,0] op_sel_hi:[1,1,1]
	v_pk_fma_f32 v[28:29], v[66:67], v[170:171], v[28:29] op_sel:[0,1,0] op_sel_hi:[1,1,1]
	v_pk_fma_f32 v[62:63], v[78:79], v[168:169], v[62:63] op_sel_hi:[1,0,1]
	v_pk_fma_f32 v[46:47], v[74:75], v[172:173], v[46:47] op_sel_hi:[1,0,1]
	v_pk_fma_f32 v[64:65], v[70:71], v[168:169], v[64:65] op_sel_hi:[1,0,1]
	v_pk_fma_f32 v[48:49], v[66:67], v[172:173], v[48:49] op_sel_hi:[1,0,1]
	v_pk_fma_f32 v[14:15], v[80:81], v[168:169], v[14:15] op_sel_hi:[1,0,1]
	v_pk_fma_f32 v[30:31], v[76:77], v[172:173], v[30:31] op_sel_hi:[1,0,1]
	v_pk_fma_f32 v[16:17], v[72:73], v[168:169], v[16:17] op_sel_hi:[1,0,1]
	v_pk_fma_f32 v[32:33], v[68:69], v[172:173], v[32:33] op_sel_hi:[1,0,1]
	v_pk_fma_f32 v[62:63], v[80:81], v[168:169], v[62:63] op_sel:[0,1,0] op_sel_hi:[1,1,1] neg_lo:[0,1,0] neg_hi:[0,1,0]
	v_pk_fma_f32 v[46:47], v[76:77], v[172:173], v[46:47] op_sel:[0,1,0] op_sel_hi:[1,1,1] neg_lo:[0,1,0] neg_hi:[0,1,0]
	v_pk_fma_f32 v[64:65], v[72:73], v[168:169], v[64:65] op_sel:[0,1,0] op_sel_hi:[1,1,1] neg_lo:[0,1,0] neg_hi:[0,1,0]
	v_pk_fma_f32 v[48:49], v[68:69], v[172:173], v[48:49] op_sel:[0,1,0] op_sel_hi:[1,1,1] neg_lo:[0,1,0] neg_hi:[0,1,0]
	v_pk_fma_f32 v[14:15], v[78:79], v[168:169], v[14:15] op_sel:[0,1,0] op_sel_hi:[1,1,1]
	v_pk_fma_f32 v[30:31], v[74:75], v[172:173], v[30:31] op_sel:[0,1,0] op_sel_hi:[1,1,1]
	v_pk_fma_f32 v[16:17], v[70:71], v[168:169], v[16:17] op_sel:[0,1,0] op_sel_hi:[1,1,1]
	v_pk_fma_f32 v[32:33], v[66:67], v[172:173], v[32:33] op_sel:[0,1,0] op_sel_hi:[1,1,1]
	v_mov_b32_e32 v156, v65
	v_mov_b32_e32 v157, v17
	v_mov_b32_e32 v166, v65
	v_mov_b32_e32 v167, v17
	s_nop 1
	v_permlane32_swap_b32_e32 v156, v166
	v_permlane32_swap_b32_e32 v157, v167
	v_mov_b32_e32 v156, v49
	v_mov_b32_e32 v157, v33
	v_mov_b32_e32 v150, v49
	v_mov_b32_e32 v151, v33
	s_nop 1
	v_permlane32_swap_b32_e32 v156, v150
	v_permlane32_swap_b32_e32 v157, v151
	v_cvt_pk_bf16_f32 v1, v50, v2
	ds_write_b32 v174, v1
	v_cvt_pk_bf16_f32 v146, v34, v18
	ds_write_b32 v174, v146 offset:128
	v_cvt_pk_bf16_f32 v178, v51, v3
	ds_write_b32 v174, v178 offset:272
	v_cvt_pk_bf16_f32 v1, v35, v19
	ds_write_b32 v174, v1 offset:400
	v_cvt_pk_bf16_f32 v146, v52, v4
	ds_write_b32 v174, v146 offset:544
	v_cvt_pk_bf16_f32 v178, v36, v20
	ds_write_b32 v174, v178 offset:672
	v_cvt_pk_bf16_f32 v1, v53, v5
	ds_write_b32 v174, v1 offset:816
	v_cvt_pk_bf16_f32 v146, v37, v21
	ds_write_b32 v174, v146 offset:944
	v_cvt_pk_bf16_f32 v178, v54, v6
	ds_write_b32 v174, v178 offset:1088
	v_cvt_pk_bf16_f32 v1, v38, v22
	ds_write_b32 v174, v1 offset:1216
	v_cvt_pk_bf16_f32 v146, v55, v7
	ds_write_b32 v174, v146 offset:1360
	v_cvt_pk_bf16_f32 v178, v39, v23
	ds_write_b32 v174, v178 offset:1488
	v_cvt_pk_bf16_f32 v1, v56, v8
	ds_write_b32 v174, v1 offset:1632
	v_cvt_pk_bf16_f32 v146, v40, v24
	ds_write_b32 v174, v146 offset:1760
	v_cvt_pk_bf16_f32 v178, v57, v9
	ds_write_b32 v174, v178 offset:1904
	v_cvt_pk_bf16_f32 v1, v41, v25
	ds_write_b32 v174, v1 offset:2032
	v_cvt_pk_bf16_f32 v146, v58, v10
	ds_write_b32 v174, v146 offset:2176
	v_cvt_pk_bf16_f32 v178, v42, v26
	ds_write_b32 v174, v178 offset:2304
	v_cvt_pk_bf16_f32 v1, v59, v11
	ds_write_b32 v174, v1 offset:2448
	v_cvt_pk_bf16_f32 v146, v43, v27
	ds_write_b32 v174, v146 offset:2576
	v_cvt_pk_bf16_f32 v178, v60, v12
	ds_write_b32 v174, v178 offset:2720
	v_cvt_pk_bf16_f32 v1, v44, v28
	ds_write_b32 v174, v1 offset:2848
	v_cvt_pk_bf16_f32 v146, v61, v13
	ds_write_b32 v174, v146 offset:2992
	v_cvt_pk_bf16_f32 v178, v45, v29
	ds_write_b32 v174, v178 offset:3120
	v_cvt_pk_bf16_f32 v1, v62, v14
	ds_write_b32 v174, v1 offset:3264
	v_cvt_pk_bf16_f32 v146, v46, v30
	ds_write_b32 v174, v146 offset:3392
	v_cvt_pk_bf16_f32 v178, v63, v15
	ds_write_b32 v174, v178 offset:3536
	v_cvt_pk_bf16_f32 v1, v47, v31
	ds_write_b32 v174, v1 offset:3664
	v_cvt_pk_bf16_f32 v146, v64, v16
	ds_write_b32 v174, v146 offset:3808
	v_cvt_pk_bf16_f32 v178, v48, v32
	ds_write_b32 v174, v178 offset:3936
	v_cvt_pk_bf16_f32 v1, v65, v17
	ds_write_b32 v174, v1 offset:4080
	v_cvt_pk_bf16_f32 v146, v49, v33
	ds_write_b32 v174, v146 offset:4208
	s_waitcnt lgkmcnt(0)
	ds_read_b128 v[2:5], v175
	ds_read_b128 v[6:9], v175 offset:64
	ds_read_b128 v[10:13], v175 offset:128
	ds_read_b128 v[14:17], v175 offset:192
	ds_read_b128 v[18:21], v175 offset:4352
	ds_read_b128 v[22:25], v175 offset:4416
	ds_read_b128 v[26:29], v175 offset:4480
	ds_read_b128 v[30:33], v175 offset:4544
	s_waitcnt vmcnt(0)
	s_waitcnt lgkmcnt(7)
	v_mfma_f32_16x16x32_bf16 v[34:37], v[94:97], v[2:5], 0
	s_waitcnt lgkmcnt(6)
	v_mfma_f32_16x16x32_bf16 v[34:37], v[90:93], v[6:9], v[34:37]
	s_waitcnt lgkmcnt(5)
	v_mfma_f32_16x16x32_bf16 v[34:37], v[86:89], v[10:13], v[34:37]
	s_waitcnt lgkmcnt(4)
	v_mfma_f32_16x16x32_bf16 v[34:37], v[82:85], v[14:17], v[34:37]
	s_waitcnt lgkmcnt(3)
	v_mfma_f32_16x16x32_bf16 v[38:41], v[94:97], v[18:21], 0
	s_waitcnt lgkmcnt(2)
	v_mfma_f32_16x16x32_bf16 v[38:41], v[90:93], v[22:25], v[38:41]
	s_waitcnt lgkmcnt(1)
	v_mfma_f32_16x16x32_bf16 v[38:41], v[86:89], v[26:29], v[38:41]
	s_waitcnt lgkmcnt(0)
	v_mfma_f32_16x16x32_bf16 v[38:41], v[82:85], v[30:33], v[38:41]
	v_lshlrev_b32_e32 v42, 16, v160
	v_and_b32_e32 v43, 0xffff0000, v160
	v_lshlrev_b32_e32 v44, 16, v161
	v_and_b32_e32 v45, 0xffff0000, v161
	v_lshlrev_b32_e32 v46, 16, v162
	v_and_b32_e32 v47, 0xffff0000, v162
	v_lshlrev_b32_e32 v48, 16, v163
	v_and_b32_e32 v49, 0xffff0000, v163
	s_nop 1
	v_fma_f32 v50, v98, v42, v34
	v_fma_f32 v51, v99, v43, v35
	v_fma_f32 v52, v100, v44, v36
	v_fma_f32 v53, v101, v45, v37
	v_fma_f32 v54, v98, v46, v38
	v_fma_f32 v55, v99, v47, v39
	v_fma_f32 v56, v100, v48, v40
	v_fma_f32 v57, v101, v49, v41
	v_mul_f32_e32 v2, 0x3d372713, v50
	v_mul_f32_e32 v3, 0x3d372713, v51
	v_mul_f32_e32 v4, 0x3d372713, v52
	v_mul_f32_e32 v5, 0x3d372713, v53
	v_mul_f32_e32 v6, 0x3d372713, v54
	v_mul_f32_e32 v7, 0x3d372713, v55
	v_mul_f32_e32 v8, 0x3d372713, v56
	v_mul_f32_e32 v9, 0x3d372713, v57
	v_mul_f32_e32 v2, v50, v2
	v_mul_f32_e32 v3, v51, v3
	v_mul_f32_e32 v4, v52, v4
	v_mul_f32_e32 v5, v53, v5
	v_mul_f32_e32 v6, v54, v6
	v_mul_f32_e32 v7, v55, v7
	v_mul_f32_e32 v8, v56, v8
	v_mul_f32_e32 v9, v57, v9
	v_fma_f32 v2, v50, v2, v50
	v_fma_f32 v3, v51, v3, v51
	v_fma_f32 v4, v52, v4, v52
	v_fma_f32 v5, v53, v5, v53
	v_fma_f32 v6, v54, v6, v54
	v_fma_f32 v7, v55, v7, v55
	v_fma_f32 v8, v56, v8, v56
	v_fma_f32 v9, v57, v9, v57
	v_mul_f32_e32 v2, 0xbfcc422a, v2
	v_mul_f32_e32 v3, 0xbfcc422a, v3
	v_mul_f32_e32 v4, 0xbfcc422a, v4
	v_mul_f32_e32 v5, 0xbfcc422a, v5
	v_mul_f32_e32 v6, 0xbfcc422a, v6
	v_mul_f32_e32 v7, 0xbfcc422a, v7
	v_mul_f32_e32 v8, 0xbfcc422a, v8
	v_mul_f32_e32 v9, 0xbfcc422a, v9
	v_mul_f32_e32 v2, 0x3fb8aa3b, v2
	v_mul_f32_e32 v3, 0x3fb8aa3b, v3
	v_mul_f32_e32 v4, 0x3fb8aa3b, v4
	v_mul_f32_e32 v5, 0x3fb8aa3b, v5
	v_mul_f32_e32 v6, 0x3fb8aa3b, v6
	v_mul_f32_e32 v7, 0x3fb8aa3b, v7
	v_mul_f32_e32 v8, 0x3fb8aa3b, v8
	v_mul_f32_e32 v9, 0x3fb8aa3b, v9
	v_exp_f32_e32 v2, v2
	v_exp_f32_e32 v3, v3
	v_exp_f32_e32 v4, v4
	v_exp_f32_e32 v5, v5
	v_exp_f32_e32 v6, v6
	v_exp_f32_e32 v7, v7
	v_exp_f32_e32 v8, v8
	v_exp_f32_e32 v9, v9
	v_add_f32_e32 v2, 1.0, v2
	v_add_f32_e32 v3, 1.0, v3
	v_add_f32_e32 v4, 1.0, v4
	v_add_f32_e32 v5, 1.0, v5
	v_add_f32_e32 v6, 1.0, v6
	v_add_f32_e32 v7, 1.0, v7
	v_add_f32_e32 v8, 1.0, v8
	v_add_f32_e32 v9, 1.0, v9
	v_rcp_f32_e32 v2, v2
	v_rcp_f32_e32 v3, v3
	v_rcp_f32_e32 v4, v4
	v_rcp_f32_e32 v5, v5
	v_rcp_f32_e32 v6, v6
	v_rcp_f32_e32 v7, v7
	v_rcp_f32_e32 v8, v8
	v_rcp_f32_e32 v9, v9
	v_mul_f32_e32 v50, v50, v2
	v_mul_f32_e32 v51, v51, v3
	v_mul_f32_e32 v52, v52, v4
	v_mul_f32_e32 v53, v53, v5
	v_mul_f32_e32 v54, v54, v6
	v_mul_f32_e32 v55, v55, v7
	v_mul_f32_e32 v56, v56, v8
	v_mul_f32_e32 v57, v57, v9
	v_cvt_pk_bf16_f32 v10, v50, v51
	v_cvt_pk_bf16_f32 v11, v52, v53
	v_cvt_pk_bf16_f32 v12, v54, v55
	v_cvt_pk_bf16_f32 v13, v56, v57
	global_store_dwordx2 v176, v[10:11], s[10:11]
	global_store_dwordx2 v177, v[12:13], s[10:11]
	v_readlane_b32 s4, v252, 61
	v_readlane_b32 s5, v252, 62
	v_cmp_gt_u32_e32 vcc, 32, v148
	v_and_b32_e32 v146, 31, v148
	v_mov_b32_e32 v3, v166
	v_mov_b32_e32 v2, v167
	v_mov_b32_e32 v4, v150
	v_mov_b32_e32 v5, v151
	v_lshlrev_b32_e32 v146, 2, v146
	s_and_b64 s[4:5], s[4:5], vcc
	s_cmp_eq_u32 s70, 31
	s_cselect_b64 s[0:1], -1, 0
	s_and_b64 s[4:5], s[0:1], s[4:5]
	s_and_saveexec_b64 s[0:1], s[4:5]
	s_cbranch_execz .LBB0_1057
	s_lshl_b32 s2, s64, 11
	s_or_b32 s4, s30, s2
	s_ashr_i32 s5, s4, 31
	s_lshl_b64 s[4:5], s[4:5], 2
	v_readlane_b32 s8, v252, 4
	v_readlane_b32 s9, v252, 5
	s_add_u32 s4, s8, s4
	s_addc_u32 s5, s9, s5
	v_lshl_add_u64 v[6:7], s[4:5], 0, v[146:147]
	v_add_co_u32_e32 v8, vcc, 0x8400000, v6
	v_readlane_b32 s10, v252, 6
	s_nop 0
	v_addc_co_u32_e32 v9, vcc, 0, v7, vcc
	v_add_co_u32_e32 v6, vcc, 0x8404000, v6
	v_readlane_b32 s11, v252, 7
	s_nop 0
	v_addc_co_u32_e32 v7, vcc, 0, v7, vcc
	global_store_dword v[8:9], v3, off
	global_store_dword v[6:7], v2, off
	global_store_dword v[8:9], v4, off offset:128
	global_store_dword v[6:7], v5, off offset:128
	s_branch .LBB0_1057
